# v58 + diff_finish2 map-1 stash: 16 factor reads batched before the 64 mul+ds_write; residual s_nop runs between v_fmamk and v_rsq removed
# baseline (speedup 1.0000x reference)
.LBB0_988:
	v_readlane_b32 s8, v255, 26
	v_readlane_b32 s10, v255, 28
	v_readlane_b32 s11, v255, 29
	s_add_u32 s6, s10, 0x2ce000
	s_addc_u32 s7, s11, 0
	s_bitcmp0_b32 s48, 2
	s_mov_b32 s0, 0x30878000
	s_cselect_b32 s0, s0, 0x31878000
	s_mov_b32 s1, 0x4400000
	v_readlane_b32 s9, v255, 27
	s_cselect_b32 s1, s1, 0x4c00000
	s_add_u32 s0, s8, s0
	v_readlane_b32 s8, v255, 37
	s_addc_u32 s3, s9, 0
	s_lshl_b32 s2, s8, 18
	s_and_b32 s5, s2, 0x200000
	s_lshl_b32 s2, s5, 2
	s_add_u32 s2, s0, s2
	s_addc_u32 s3, s3, 0
	s_add_u32 s0, s10, s1
	s_addc_u32 s1, s11, 0
	s_lshl_b32 s5, s5, 1
	s_add_u32 s0, s0, s5
	s_addc_u32 s1, s1, 0
	s_lshl_b32 s4, s4, 8
	s_add_i32 s14, s14, s4
	s_nop 0
	v_add_u32_e32 v134, s14, v1
	v_ashrrev_i32_e32 v135, 31, v134
	v_lshl_add_u64 v[136:137], v[134:135], 2, s[6:7]
	global_load_dword v1, v[136:137], off
	v_lshlrev_b32_e32 v132, 3, v2
	v_ashrrev_i32_e32 v133, 31, v132
	v_lshl_add_u64 v[132:133], v[132:133], 0, s[46:47]
	s_waitcnt vmcnt(0)
	v_fmamk_f32 v1, v1, 0x3a800000, v208
	v_cmp_gt_f32_e32 vcc, s90, v1
	v_mul_f32_e32 v2, 0x4f800000, v1
	s_nop 0
	v_cndmask_b32_e32 v1, v1, v2, vcc
	v_sqrt_f32_e32 v2, v1
	s_nop 0
	v_add_u32_e32 v136, -1, v2
	v_fma_f32 v137, -v136, v2, v1
	v_cmp_ge_f32_e64 s[4:5], 0, v137
	v_add_u32_e32 v137, 1, v2
	s_nop 0
	v_cndmask_b32_e64 v136, v2, v136, s[4:5]
	v_fma_f32 v2, -v137, v2, v1
	v_cmp_lt_f32_e64 s[4:5], 0, v2
	s_nop 1
	v_cndmask_b32_e64 v2, v136, v137, s[4:5]
	v_mul_f32_e32 v136, 0x37800000, v2
	v_cndmask_b32_e32 v2, v2, v136, vcc
	v_cmp_class_f32_e32 vcc, v1, v209
	s_nop 1
	v_cndmask_b32_e32 v1, v2, v1, vcc
	v_div_scale_f32 v2, s[4:5], v1, v1, 1.0
	v_rcp_f32_e32 v136, v2
	s_lshl_b32 s4, s8, 8
	s_and_b32 s46, s4, 0x300
	v_fma_f32 v137, -v2, v136, 1.0
	v_fmac_f32_e32 v136, v137, v136
	v_div_scale_f32 v137, vcc, 1.0, v1, 1.0
	v_mul_f32_e32 v138, v137, v136
	v_fma_f32 v139, -v2, v138, v137
	v_fmac_f32_e32 v138, v139, v136
	v_fma_f32 v2, -v2, v138, v137
	v_div_fmas_f32 v2, v2, v136, v138
	v_lshlrev_b64 v[136:137], 10, v[134:135]
	v_lshl_add_u64 v[136:137], v[136:137], 0, v[132:133]
	v_div_fixup_f32 v2, v2, v1, 1.0
	v_lshl_add_u64 v[136:137], v[136:137], 0, s[46:47]
	v_pk_mul_f32 v[130:131], v[130:131], v[2:3] op_sel_hi:[1,0]
	v_pk_mul_f32 v[128:129], v[128:129], v[2:3] op_sel_hi:[1,0]
	v_pk_mul_f32 v[124:125], v[124:125], v[2:3] op_sel_hi:[1,0]
	v_lshl_add_u64 v[138:139], v[136:137], 2, s[2:3]
	v_pk_mul_f32 v[126:127], v[126:127], v[2:3] op_sel_hi:[1,0]
	global_store_dwordx4 v[138:139], v[128:131], off
	global_store_dwordx4 v[138:139], v[124:127], off offset:16
	v_pk_mul_f32 v[122:123], v[122:123], v[2:3] op_sel_hi:[1,0]
	v_cvt_pk_bf16_f32 v128, v128, v129
	v_cvt_pk_bf16_f32 v129, v130, v131
	v_cvt_pk_bf16_f32 v130, v124, v125
	v_pk_mul_f32 v[120:121], v[120:121], v[2:3] op_sel_hi:[1,0]
	v_lshl_add_u64 v[124:125], v[136:137], 1, s[0:1]
	v_pk_mul_f32 v[116:117], v[116:117], v[2:3] op_sel_hi:[1,0]
	v_cvt_pk_bf16_f32 v131, v126, v127
	global_store_dwordx4 v[124:125], v[128:131], off
	v_pk_mul_f32 v[118:119], v[118:119], v[2:3] op_sel_hi:[1,0]
	global_store_dwordx4 v[138:139], v[120:123], off offset:512
	global_store_dwordx4 v[138:139], v[116:119], off offset:528
	s_nop 0
	v_cvt_pk_bf16_f32 v120, v120, v121
	v_cvt_pk_bf16_f32 v121, v122, v123
	v_cvt_pk_bf16_f32 v122, v116, v117
	v_cvt_pk_bf16_f32 v123, v118, v119
	s_nop 0
	v_add_u32_e32 v116, 16, v134
	v_ashrrev_i32_e32 v117, 31, v116
	global_store_dwordx4 v[124:125], v[120:123], off offset:256
	v_lshl_add_u64 v[118:119], v[116:117], 2, s[6:7]
	global_load_dword v1, v[118:119], off
	v_lshlrev_b64 v[116:117], 10, v[116:117]
	v_lshl_add_u64 v[116:117], v[116:117], 0, v[132:133]
	v_lshl_add_u64 v[116:117], v[116:117], 0, s[46:47]
	s_waitcnt vmcnt(0)
	v_fmamk_f32 v1, v1, 0x3a800000, v208
	v_cmp_gt_f32_e32 vcc, s90, v1
	v_mul_f32_e32 v2, 0x4f800000, v1
	s_nop 0
	v_cndmask_b32_e32 v1, v1, v2, vcc
	v_sqrt_f32_e32 v2, v1
	s_nop 0
	v_add_u32_e32 v118, -1, v2
	v_fma_f32 v119, -v118, v2, v1
	v_cmp_ge_f32_e64 s[4:5], 0, v119
	v_add_u32_e32 v119, 1, v2
	s_nop 0
	v_cndmask_b32_e64 v118, v2, v118, s[4:5]
	v_fma_f32 v2, -v119, v2, v1
	v_cmp_lt_f32_e64 s[4:5], 0, v2
	s_nop 1
	v_cndmask_b32_e64 v2, v118, v119, s[4:5]
	v_mul_f32_e32 v118, 0x37800000, v2
	v_cndmask_b32_e32 v2, v2, v118, vcc
	v_cmp_class_f32_e32 vcc, v1, v209
	s_nop 1
	v_cndmask_b32_e32 v1, v2, v1, vcc
	v_div_scale_f32 v2, s[4:5], v1, v1, 1.0
	v_rcp_f32_e32 v118, v2
	s_nop 0
	v_fma_f32 v119, -v2, v118, 1.0
	v_fmac_f32_e32 v118, v119, v118
	v_div_scale_f32 v119, vcc, 1.0, v1, 1.0
	v_mul_f32_e32 v120, v119, v118
	v_fma_f32 v121, -v2, v120, v119
	v_fmac_f32_e32 v120, v121, v118
	v_fma_f32 v2, -v2, v120, v119
	v_div_fmas_f32 v2, v2, v118, v120
	v_div_fixup_f32 v2, v2, v1, 1.0
	v_pk_mul_f32 v[114:115], v[114:115], v[2:3] op_sel_hi:[1,0]
	v_pk_mul_f32 v[112:113], v[112:113], v[2:3] op_sel_hi:[1,0]
	v_pk_mul_f32 v[108:109], v[108:109], v[2:3] op_sel_hi:[1,0]
	v_lshl_add_u64 v[118:119], v[116:117], 2, s[2:3]
	v_pk_mul_f32 v[110:111], v[110:111], v[2:3] op_sel_hi:[1,0]
	global_store_dwordx4 v[118:119], v[112:115], off
	global_store_dwordx4 v[118:119], v[108:111], off offset:16
	v_pk_mul_f32 v[106:107], v[106:107], v[2:3] op_sel_hi:[1,0]
	v_cvt_pk_bf16_f32 v112, v112, v113
	v_cvt_pk_bf16_f32 v113, v114, v115
	v_cvt_pk_bf16_f32 v114, v108, v109
	v_pk_mul_f32 v[104:105], v[104:105], v[2:3] op_sel_hi:[1,0]
	v_lshl_add_u64 v[108:109], v[116:117], 1, s[0:1]
	v_pk_mul_f32 v[100:101], v[100:101], v[2:3] op_sel_hi:[1,0]
	v_cvt_pk_bf16_f32 v115, v110, v111
	global_store_dwordx4 v[108:109], v[112:115], off
	v_pk_mul_f32 v[102:103], v[102:103], v[2:3] op_sel_hi:[1,0]
	global_store_dwordx4 v[118:119], v[104:107], off offset:512
	global_store_dwordx4 v[118:119], v[100:103], off offset:528
	s_nop 0
	v_cvt_pk_bf16_f32 v104, v104, v105
	v_cvt_pk_bf16_f32 v105, v106, v107
	v_cvt_pk_bf16_f32 v106, v100, v101
	v_cvt_pk_bf16_f32 v107, v102, v103
	s_nop 0
	v_add_u32_e32 v100, 32, v134
	v_ashrrev_i32_e32 v101, 31, v100
	global_store_dwordx4 v[108:109], v[104:107], off offset:256
	v_lshl_add_u64 v[102:103], v[100:101], 2, s[6:7]
	global_load_dword v1, v[102:103], off
	v_lshlrev_b64 v[100:101], 10, v[100:101]
	v_lshl_add_u64 v[100:101], v[100:101], 0, v[132:133]
	v_lshl_add_u64 v[100:101], v[100:101], 0, s[46:47]
	s_waitcnt vmcnt(0)
	v_fmamk_f32 v1, v1, 0x3a800000, v208
	v_cmp_gt_f32_e32 vcc, s90, v1
	v_mul_f32_e32 v2, 0x4f800000, v1
	s_nop 0
	v_cndmask_b32_e32 v1, v1, v2, vcc
	v_sqrt_f32_e32 v2, v1
	s_nop 0
	v_add_u32_e32 v102, -1, v2
	v_fma_f32 v103, -v102, v2, v1
	v_cmp_ge_f32_e64 s[4:5], 0, v103
	v_add_u32_e32 v103, 1, v2
	s_nop 0
	v_cndmask_b32_e64 v102, v2, v102, s[4:5]
	v_fma_f32 v2, -v103, v2, v1
	v_cmp_lt_f32_e64 s[4:5], 0, v2
	s_nop 1
	v_cndmask_b32_e64 v2, v102, v103, s[4:5]
	v_mul_f32_e32 v102, 0x37800000, v2
	v_cndmask_b32_e32 v2, v2, v102, vcc
	v_cmp_class_f32_e32 vcc, v1, v209
	s_nop 1
	v_cndmask_b32_e32 v1, v2, v1, vcc
	v_div_scale_f32 v2, s[4:5], v1, v1, 1.0
	v_rcp_f32_e32 v102, v2
	s_nop 0
	v_fma_f32 v103, -v2, v102, 1.0
	v_fmac_f32_e32 v102, v103, v102
	v_div_scale_f32 v103, vcc, 1.0, v1, 1.0
	v_mul_f32_e32 v104, v103, v102
	v_fma_f32 v105, -v2, v104, v103
	v_fmac_f32_e32 v104, v105, v102
	v_fma_f32 v2, -v2, v104, v103
	v_div_fmas_f32 v2, v2, v102, v104
	v_div_fixup_f32 v2, v2, v1, 1.0
	v_pk_mul_f32 v[98:99], v[98:99], v[2:3] op_sel_hi:[1,0]
	v_pk_mul_f32 v[96:97], v[96:97], v[2:3] op_sel_hi:[1,0]
	v_pk_mul_f32 v[92:93], v[92:93], v[2:3] op_sel_hi:[1,0]
	v_lshl_add_u64 v[102:103], v[100:101], 2, s[2:3]
	v_pk_mul_f32 v[94:95], v[94:95], v[2:3] op_sel_hi:[1,0]
	global_store_dwordx4 v[102:103], v[96:99], off
	global_store_dwordx4 v[102:103], v[92:95], off offset:16
	v_pk_mul_f32 v[90:91], v[90:91], v[2:3] op_sel_hi:[1,0]
	v_cvt_pk_bf16_f32 v96, v96, v97
	v_cvt_pk_bf16_f32 v97, v98, v99
	v_cvt_pk_bf16_f32 v98, v92, v93
	v_pk_mul_f32 v[88:89], v[88:89], v[2:3] op_sel_hi:[1,0]
	v_lshl_add_u64 v[92:93], v[100:101], 1, s[0:1]
	v_pk_mul_f32 v[84:85], v[84:85], v[2:3] op_sel_hi:[1,0]
	v_cvt_pk_bf16_f32 v99, v94, v95
	global_store_dwordx4 v[92:93], v[96:99], off
	v_pk_mul_f32 v[86:87], v[86:87], v[2:3] op_sel_hi:[1,0]
	global_store_dwordx4 v[102:103], v[88:91], off offset:512
	global_store_dwordx4 v[102:103], v[84:87], off offset:528
	s_nop 0
	v_cvt_pk_bf16_f32 v88, v88, v89
	v_cvt_pk_bf16_f32 v89, v90, v91
	v_cvt_pk_bf16_f32 v90, v84, v85
	v_cvt_pk_bf16_f32 v91, v86, v87
	s_nop 0
	v_add_u32_e32 v84, 48, v134
	v_ashrrev_i32_e32 v85, 31, v84
	global_store_dwordx4 v[92:93], v[88:91], off offset:256
	v_lshl_add_u64 v[86:87], v[84:85], 2, s[6:7]
	global_load_dword v1, v[86:87], off
	v_lshlrev_b64 v[84:85], 10, v[84:85]
	v_lshl_add_u64 v[84:85], v[84:85], 0, v[132:133]
	v_lshl_add_u64 v[84:85], v[84:85], 0, s[46:47]
	s_waitcnt vmcnt(0)
	v_fmamk_f32 v1, v1, 0x3a800000, v208
	v_cmp_gt_f32_e32 vcc, s90, v1
	v_mul_f32_e32 v2, 0x4f800000, v1
	s_nop 0
	v_cndmask_b32_e32 v1, v1, v2, vcc
	v_sqrt_f32_e32 v2, v1
	s_nop 0
	v_add_u32_e32 v86, -1, v2
	v_fma_f32 v87, -v86, v2, v1
	v_cmp_ge_f32_e64 s[4:5], 0, v87
	v_add_u32_e32 v87, 1, v2
	s_nop 0
	v_cndmask_b32_e64 v86, v2, v86, s[4:5]
	v_fma_f32 v2, -v87, v2, v1
	v_cmp_lt_f32_e64 s[4:5], 0, v2
	s_nop 1
	v_cndmask_b32_e64 v2, v86, v87, s[4:5]
	v_mul_f32_e32 v86, 0x37800000, v2
	v_cndmask_b32_e32 v2, v2, v86, vcc
	v_cmp_class_f32_e32 vcc, v1, v209
	s_nop 1
	v_cndmask_b32_e32 v1, v2, v1, vcc
	v_div_scale_f32 v2, s[4:5], v1, v1, 1.0
	v_rcp_f32_e32 v86, v2
	s_nop 0
	v_fma_f32 v87, -v2, v86, 1.0
	v_fmac_f32_e32 v86, v87, v86
	v_div_scale_f32 v87, vcc, 1.0, v1, 1.0
	v_mul_f32_e32 v88, v87, v86
	v_fma_f32 v89, -v2, v88, v87
	v_fmac_f32_e32 v88, v89, v86
	v_fma_f32 v2, -v2, v88, v87
	v_div_fmas_f32 v2, v2, v86, v88
	v_div_fixup_f32 v2, v2, v1, 1.0
	v_pk_mul_f32 v[82:83], v[82:83], v[2:3] op_sel_hi:[1,0]
	v_pk_mul_f32 v[80:81], v[80:81], v[2:3] op_sel_hi:[1,0]
	v_pk_mul_f32 v[76:77], v[76:77], v[2:3] op_sel_hi:[1,0]
	v_lshl_add_u64 v[86:87], v[84:85], 2, s[2:3]
	v_pk_mul_f32 v[78:79], v[78:79], v[2:3] op_sel_hi:[1,0]
	global_store_dwordx4 v[86:87], v[80:83], off
	global_store_dwordx4 v[86:87], v[76:79], off offset:16
	v_pk_mul_f32 v[74:75], v[74:75], v[2:3] op_sel_hi:[1,0]
	v_cvt_pk_bf16_f32 v80, v80, v81
	v_cvt_pk_bf16_f32 v81, v82, v83
	v_cvt_pk_bf16_f32 v82, v76, v77
	v_pk_mul_f32 v[72:73], v[72:73], v[2:3] op_sel_hi:[1,0]
	v_lshl_add_u64 v[76:77], v[84:85], 1, s[0:1]
	v_pk_mul_f32 v[68:69], v[68:69], v[2:3] op_sel_hi:[1,0]
	v_cvt_pk_bf16_f32 v83, v78, v79
	global_store_dwordx4 v[76:77], v[80:83], off
	v_pk_mul_f32 v[70:71], v[70:71], v[2:3] op_sel_hi:[1,0]
	global_store_dwordx4 v[86:87], v[72:75], off offset:512
	global_store_dwordx4 v[86:87], v[68:71], off offset:528
	s_nop 0
	v_cvt_pk_bf16_f32 v72, v72, v73
	v_cvt_pk_bf16_f32 v73, v74, v75
	v_cvt_pk_bf16_f32 v74, v68, v69
	v_cvt_pk_bf16_f32 v75, v70, v71
	s_nop 0
	v_add_u32_e32 v68, 0x80, v134
	v_ashrrev_i32_e32 v69, 31, v68
	global_store_dwordx4 v[76:77], v[72:75], off offset:256
	v_lshl_add_u64 v[70:71], v[68:69], 2, s[6:7]
	global_load_dword v1, v[70:71], off
	v_lshlrev_b64 v[68:69], 10, v[68:69]
	v_lshl_add_u64 v[68:69], v[68:69], 0, v[132:133]
	v_lshl_add_u64 v[68:69], v[68:69], 0, s[46:47]
	s_waitcnt vmcnt(0)
	v_fmamk_f32 v1, v1, 0x3a800000, v208
	v_cmp_gt_f32_e32 vcc, s90, v1
	v_mul_f32_e32 v2, 0x4f800000, v1
	s_nop 0
	v_cndmask_b32_e32 v1, v1, v2, vcc
	v_sqrt_f32_e32 v2, v1
	s_nop 0
	v_add_u32_e32 v70, -1, v2
	v_fma_f32 v71, -v70, v2, v1
	v_cmp_ge_f32_e64 s[4:5], 0, v71
	v_add_u32_e32 v71, 1, v2
	s_nop 0
	v_cndmask_b32_e64 v70, v2, v70, s[4:5]
	v_fma_f32 v2, -v71, v2, v1
	v_cmp_lt_f32_e64 s[4:5], 0, v2
	s_nop 1
	v_cndmask_b32_e64 v2, v70, v71, s[4:5]
	v_mul_f32_e32 v70, 0x37800000, v2
	v_cndmask_b32_e32 v2, v2, v70, vcc
	v_cmp_class_f32_e32 vcc, v1, v209
	s_nop 1
	v_cndmask_b32_e32 v1, v2, v1, vcc
	v_div_scale_f32 v2, s[4:5], v1, v1, 1.0
	v_rcp_f32_e32 v70, v2
	s_nop 0
	v_fma_f32 v71, -v2, v70, 1.0
	v_fmac_f32_e32 v70, v71, v70
	v_div_scale_f32 v71, vcc, 1.0, v1, 1.0
	v_mul_f32_e32 v72, v71, v70
	v_fma_f32 v73, -v2, v72, v71
	v_fmac_f32_e32 v72, v73, v70
	v_fma_f32 v2, -v2, v72, v71
	v_div_fmas_f32 v2, v2, v70, v72
	v_div_fixup_f32 v2, v2, v1, 1.0
	v_pk_mul_f32 v[66:67], v[66:67], v[2:3] op_sel_hi:[1,0]
	v_pk_mul_f32 v[64:65], v[64:65], v[2:3] op_sel_hi:[1,0]
	v_pk_mul_f32 v[60:61], v[60:61], v[2:3] op_sel_hi:[1,0]
	v_lshl_add_u64 v[70:71], v[68:69], 2, s[2:3]
	v_pk_mul_f32 v[62:63], v[62:63], v[2:3] op_sel_hi:[1,0]
	global_store_dwordx4 v[70:71], v[64:67], off
	global_store_dwordx4 v[70:71], v[60:63], off offset:16
	v_pk_mul_f32 v[58:59], v[58:59], v[2:3] op_sel_hi:[1,0]
	v_cvt_pk_bf16_f32 v64, v64, v65
	v_cvt_pk_bf16_f32 v65, v66, v67
	v_cvt_pk_bf16_f32 v66, v60, v61
	v_pk_mul_f32 v[56:57], v[56:57], v[2:3] op_sel_hi:[1,0]
	v_lshl_add_u64 v[60:61], v[68:69], 1, s[0:1]
	v_pk_mul_f32 v[52:53], v[52:53], v[2:3] op_sel_hi:[1,0]
	v_cvt_pk_bf16_f32 v67, v62, v63
	global_store_dwordx4 v[60:61], v[64:67], off
	v_pk_mul_f32 v[54:55], v[54:55], v[2:3] op_sel_hi:[1,0]
	global_store_dwordx4 v[70:71], v[56:59], off offset:512
	global_store_dwordx4 v[70:71], v[52:55], off offset:528
	s_nop 0
	v_cvt_pk_bf16_f32 v56, v56, v57
	v_cvt_pk_bf16_f32 v57, v58, v59
	v_cvt_pk_bf16_f32 v58, v52, v53
	v_cvt_pk_bf16_f32 v59, v54, v55
	s_nop 0
	v_add_u32_e32 v52, 0x90, v134
	v_ashrrev_i32_e32 v53, 31, v52
	global_store_dwordx4 v[60:61], v[56:59], off offset:256
	v_lshl_add_u64 v[54:55], v[52:53], 2, s[6:7]
	global_load_dword v1, v[54:55], off
	v_lshlrev_b64 v[52:53], 10, v[52:53]
	v_lshl_add_u64 v[52:53], v[52:53], 0, v[132:133]
	v_lshl_add_u64 v[52:53], v[52:53], 0, s[46:47]
	s_waitcnt vmcnt(0)
	v_fmamk_f32 v1, v1, 0x3a800000, v208
	v_rsq_f32_e32 v2, v1
	s_nop 0
	v_pk_mul_f32 v[50:51], v[50:51], v[2:3] op_sel_hi:[1,0]
	v_pk_mul_f32 v[48:49], v[48:49], v[2:3] op_sel_hi:[1,0]
	v_pk_mul_f32 v[44:45], v[44:45], v[2:3] op_sel_hi:[1,0]
	v_lshl_add_u64 v[54:55], v[52:53], 2, s[2:3]
	v_pk_mul_f32 v[46:47], v[46:47], v[2:3] op_sel_hi:[1,0]
	global_store_dwordx4 v[54:55], v[48:51], off
	global_store_dwordx4 v[54:55], v[44:47], off offset:16
	v_pk_mul_f32 v[42:43], v[42:43], v[2:3] op_sel_hi:[1,0]
	v_cvt_pk_bf16_f32 v48, v48, v49
	v_cvt_pk_bf16_f32 v49, v50, v51
	v_cvt_pk_bf16_f32 v50, v44, v45
	v_pk_mul_f32 v[40:41], v[40:41], v[2:3] op_sel_hi:[1,0]
	v_lshl_add_u64 v[44:45], v[52:53], 1, s[0:1]
	v_pk_mul_f32 v[36:37], v[36:37], v[2:3] op_sel_hi:[1,0]
	v_cvt_pk_bf16_f32 v51, v46, v47
	global_store_dwordx4 v[44:45], v[48:51], off
	v_pk_mul_f32 v[38:39], v[38:39], v[2:3] op_sel_hi:[1,0]
	global_store_dwordx4 v[54:55], v[40:43], off offset:512
	global_store_dwordx4 v[54:55], v[36:39], off offset:528
	s_nop 0
	v_cvt_pk_bf16_f32 v40, v40, v41
	v_cvt_pk_bf16_f32 v41, v42, v43
	v_cvt_pk_bf16_f32 v42, v36, v37
	v_cvt_pk_bf16_f32 v43, v38, v39
	s_nop 0
	v_add_u32_e32 v36, 0xa0, v134
	v_ashrrev_i32_e32 v37, 31, v36
	global_store_dwordx4 v[44:45], v[40:43], off offset:256
	v_lshl_add_u64 v[38:39], v[36:37], 2, s[6:7]
	global_load_dword v1, v[38:39], off
	v_lshlrev_b64 v[36:37], 10, v[36:37]
	v_lshl_add_u64 v[36:37], v[36:37], 0, v[132:133]
	v_lshl_add_u64 v[36:37], v[36:37], 0, s[46:47]
	s_waitcnt vmcnt(0)
	v_fmamk_f32 v1, v1, 0x3a800000, v208
	v_rsq_f32_e32 v2, v1
	s_nop 0
	v_pk_mul_f32 v[34:35], v[34:35], v[2:3] op_sel_hi:[1,0]
	v_pk_mul_f32 v[32:33], v[32:33], v[2:3] op_sel_hi:[1,0]
	v_pk_mul_f32 v[28:29], v[28:29], v[2:3] op_sel_hi:[1,0]
	v_lshl_add_u64 v[38:39], v[36:37], 2, s[2:3]
	v_pk_mul_f32 v[30:31], v[30:31], v[2:3] op_sel_hi:[1,0]
	global_store_dwordx4 v[38:39], v[32:35], off
	global_store_dwordx4 v[38:39], v[28:31], off offset:16
	v_pk_mul_f32 v[26:27], v[26:27], v[2:3] op_sel_hi:[1,0]
	v_cvt_pk_bf16_f32 v32, v32, v33
	v_cvt_pk_bf16_f32 v33, v34, v35
	v_cvt_pk_bf16_f32 v34, v28, v29
	v_pk_mul_f32 v[24:25], v[24:25], v[2:3] op_sel_hi:[1,0]
	v_lshl_add_u64 v[28:29], v[36:37], 1, s[0:1]
	v_pk_mul_f32 v[20:21], v[20:21], v[2:3] op_sel_hi:[1,0]
	v_cvt_pk_bf16_f32 v35, v30, v31
	global_store_dwordx4 v[28:29], v[32:35], off
	v_pk_mul_f32 v[22:23], v[22:23], v[2:3] op_sel_hi:[1,0]
	global_store_dwordx4 v[38:39], v[24:27], off offset:512
	global_store_dwordx4 v[38:39], v[20:23], off offset:528
	s_nop 0
	v_cvt_pk_bf16_f32 v24, v24, v25
	v_cvt_pk_bf16_f32 v25, v26, v27
	v_cvt_pk_bf16_f32 v26, v20, v21
	v_cvt_pk_bf16_f32 v27, v22, v23
	s_nop 0
	v_add_u32_e32 v20, 0xb0, v134
	v_ashrrev_i32_e32 v21, 31, v20
	global_store_dwordx4 v[28:29], v[24:27], off offset:256
	v_lshl_add_u64 v[22:23], v[20:21], 2, s[6:7]
	global_load_dword v1, v[22:23], off
	v_lshlrev_b64 v[20:21], 10, v[20:21]
	v_lshl_add_u64 v[20:21], v[20:21], 0, v[132:133]
	v_lshl_add_u64 v[20:21], v[20:21], 0, s[46:47]
	s_waitcnt vmcnt(0)
	v_fmamk_f32 v1, v1, 0x3a800000, v208
	v_rsq_f32_e32 v2, v1
	s_nop 0
	v_pk_mul_f32 v[18:19], v[18:19], v[2:3] op_sel_hi:[1,0]
	v_pk_mul_f32 v[16:17], v[16:17], v[2:3] op_sel_hi:[1,0]
	v_pk_mul_f32 v[12:13], v[12:13], v[2:3] op_sel_hi:[1,0]
	v_lshl_add_u64 v[22:23], v[20:21], 2, s[2:3]
	v_pk_mul_f32 v[14:15], v[14:15], v[2:3] op_sel_hi:[1,0]
	global_store_dwordx4 v[22:23], v[16:19], off
	global_store_dwordx4 v[22:23], v[12:15], off offset:16
	v_pk_mul_f32 v[10:11], v[10:11], v[2:3] op_sel_hi:[1,0]
	v_cvt_pk_bf16_f32 v16, v16, v17
	v_cvt_pk_bf16_f32 v17, v18, v19
	v_cvt_pk_bf16_f32 v18, v12, v13
	v_pk_mul_f32 v[8:9], v[8:9], v[2:3] op_sel_hi:[1,0]
	v_lshl_add_u64 v[12:13], v[20:21], 1, s[0:1]
	v_cvt_pk_bf16_f32 v19, v14, v15
	global_store_dwordx4 v[12:13], v[16:19], off
	v_pk_mul_f32 v[6:7], v[6:7], v[2:3] op_sel_hi:[1,0]
	v_pk_mul_f32 v[4:5], v[4:5], v[2:3] op_sel_hi:[1,0]
	global_store_dwordx4 v[22:23], v[8:11], off offset:512
	global_store_dwordx4 v[22:23], v[4:7], off offset:528
	s_nop 0
	v_cvt_pk_bf16_f32 v8, v8, v9
	v_cvt_pk_bf16_f32 v9, v10, v11
	v_cvt_pk_bf16_f32 v10, v4, v5
	v_cvt_pk_bf16_f32 v11, v6, v7
	global_store_dwordx4 v[12:13], v[8:11], off offset:256
	s_waitcnt vmcnt(0)
	s_barrier

.LBB0_1174:
	s_or_b64 exec, exec, s[4:5]
	s_waitcnt lgkmcnt(0)
	v_lshlrev_b32_e32 v2, 2, v158
	global_load_dword v249, v2, s[0:1]
	global_load_dword v250, v2, s[0:1] offset:128
	global_load_dword v251, v2, s[0:1] offset:256
	global_load_dword v253, v2, s[0:1] offset:384
	v_add_u32_e32 v10, s19, v148
	s_lshl_b64 s[4:5], s[10:11], 13
	s_add_u32 s4, s86, s4
	s_addc_u32 s5, s87, s5
	s_add_u32 s6, s4, s46
	s_addc_u32 s7, s5, 0
	s_waitcnt vmcnt(0)
	v_mul_f32_e32 v7, v164, v249
	v_mul_f32_e32 v9, v164, v250
	v_mul_f32_e32 v6, v164, v251
	v_mul_f32_e32 v8, v164, v253
	v_lshl_or_b32 v2, v159, 14, v158
	ds_read_b32 v11, v10
	ds_read2st64_b32 v[4:5], v1 offset1:16
	ds_read_b32 v23, v10 offset:4
	ds_read2st64_b32 v[16:17], v1 offset0:1 offset1:17
	s_waitcnt lgkmcnt(0)
	v_fma_f32 v12, v84, v11, -v4
	v_fma_f32 v13, v100, v11, -v5
	ds_read2st64_b32 v[4:5], v1 offset0:32 offset1:48
	v_mul_f32_e32 v14, v13, v13
	v_fmac_f32_e32 v14, v12, v12
	v_fma_f32 v24, v85, v23, -v16
	v_fma_f32 v25, v101, v23, -v17
	ds_read2st64_b32 v[16:17], v1 offset0:33 offset1:49
	v_mul_f32_e32 v26, v25, v25
	v_fmac_f32_e32 v26, v24, v24
	s_waitcnt lgkmcnt(0)
	v_fma_f32 v15, v116, v11, -v4
	v_fmac_f32_e32 v14, v15, v15
	v_fma_f32 v11, v132, v11, -v5
	v_fmac_f32_e32 v14, v11, v11
	s_nop 1
	v_add_f32_dpp v4, v14, v14 quad_perm:[1,0,3,2] row_mask:0xf bank_mask:0xf
	s_nop 1
	v_add_f32_dpp v4, v4, v4 quad_perm:[2,3,0,1] row_mask:0xf bank_mask:0xf
	s_nop 1
	v_add_f32_dpp v4, v4, v4 row_half_mirror row_mask:0xf bank_mask:0xf
	s_nop 1
	v_add_f32_dpp v4, v4, v4 row_mirror row_mask:0xf bank_mask:0xf
	ds_swizzle_b32 v5, v4 offset:swizzle(SWAP,16)
	v_fma_f32 v27, v117, v23, -v16
	v_fmac_f32_e32 v26, v27, v27
	v_fma_f32 v23, v133, v23, -v17
	v_fmac_f32_e32 v26, v23, v23
	s_nop 1
	v_add_f32_dpp v16, v26, v26 quad_perm:[1,0,3,2] row_mask:0xf bank_mask:0xf
	s_nop 1
	v_add_f32_dpp v16, v16, v16 quad_perm:[2,3,0,1] row_mask:0xf bank_mask:0xf
	s_nop 1
	v_add_f32_dpp v16, v16, v16 row_half_mirror row_mask:0xf bank_mask:0xf
	s_nop 1
	v_add_f32_dpp v16, v16, v16 row_mirror row_mask:0xf bank_mask:0xf
	ds_swizzle_b32 v17, v16 offset:swizzle(SWAP,16)
	s_waitcnt lgkmcnt(0)
	v_add_f32_e32 v4, v4, v5
	v_fmamk_f32 v4, v4, 0x3c000000, v254
	v_rsq_f32_e32 v14, v4
	s_nop 0
	v_mul_f32_e32 v4, v12, v14
	v_mul_f32_e32 v5, v13, v14
	v_mul_f32_e32 v4, v7, v4
	v_mul_f32_e32 v5, v9, v5
	v_cvt_pk_bf16_f32 v12, v4, v5
	v_lshl_add_u64 v[4:5], v[2:3], 1, s[6:7]
	global_store_short v[4:5], v12, off
	v_add_u32_e32 v4, 32, v2
	v_mov_b32_e32 v5, v3
	v_lshl_add_u64 v[4:5], v[4:5], 1, s[6:7]
	global_store_short_d16_hi v[4:5], v12, off
	v_mul_f32_e32 v4, v15, v14
	v_mul_f32_e32 v5, v11, v14
	v_mul_f32_e32 v4, v6, v4
	v_mul_f32_e32 v5, v8, v5
	v_cvt_pk_bf16_f32 v11, v4, v5
	v_add_u32_e32 v4, 64, v2
	v_mov_b32_e32 v5, v3
	v_lshl_add_u64 v[4:5], v[4:5], 1, s[6:7]
	global_store_short v[4:5], v11, off
	v_add_u32_e32 v4, 0x60, v2
	v_mov_b32_e32 v5, v3
	v_lshl_add_u64 v[4:5], v[4:5], 1, s[6:7]
	global_store_short_d16_hi v[4:5], v11, off
	v_add_f32_e32 v16, v16, v17
	v_fmamk_f32 v16, v16, 0x3c000000, v254
	v_rsq_f32_e32 v26, v16
	s_nop 0
	v_mul_f32_e32 v17, v24, v26
	v_mul_f32_e32 v24, v25, v26
	v_mul_f32_e32 v17, v7, v17
	v_mul_f32_e32 v24, v9, v24
	v_add_u32_e32 v16, 0x1000, v2
	v_cvt_pk_bf16_f32 v24, v17, v24
	v_mov_b32_e32 v17, v3
	v_lshl_add_u64 v[16:17], v[16:17], 1, s[6:7]
	global_store_short v[16:17], v24, off
	v_add_u32_e32 v16, 0x1020, v2
	v_mov_b32_e32 v17, v3
	v_lshl_add_u64 v[16:17], v[16:17], 1, s[6:7]
	global_store_short_d16_hi v[16:17], v24, off
	v_mul_f32_e32 v16, v27, v26
	v_mul_f32_e32 v17, v23, v26
	v_mul_f32_e32 v16, v6, v16
	v_mul_f32_e32 v17, v8, v17
	v_cvt_pk_bf16_f32 v23, v16, v17
	v_add_u32_e32 v16, 0x1040, v2
	v_mov_b32_e32 v17, v3
	v_lshl_add_u64 v[16:17], v[16:17], 1, s[6:7]
	global_store_short v[16:17], v23, off
	v_add_u32_e32 v16, 0x1060, v2
	v_mov_b32_e32 v17, v3
	v_lshl_add_u64 v[16:17], v[16:17], 1, s[6:7]
	global_store_short_d16_hi v[16:17], v23, off
	ds_read_b32 v11, v10 offset:8
	ds_read2st64_b32 v[4:5], v1 offset0:2 offset1:18
	ds_read_b32 v23, v10 offset:12
	ds_read2st64_b32 v[16:17], v1 offset0:3 offset1:19
	s_waitcnt lgkmcnt(0)
	v_fma_f32 v12, v86, v11, -v4
	v_fma_f32 v13, v102, v11, -v5
	ds_read2st64_b32 v[4:5], v1 offset0:34 offset1:50
	v_mul_f32_e32 v14, v13, v13
	v_fmac_f32_e32 v14, v12, v12
	v_fma_f32 v24, v87, v23, -v16
	v_fma_f32 v25, v103, v23, -v17
	ds_read2st64_b32 v[16:17], v1 offset0:35 offset1:51
	v_mul_f32_e32 v26, v25, v25
	v_fmac_f32_e32 v26, v24, v24
	s_waitcnt lgkmcnt(0)
	v_fma_f32 v15, v118, v11, -v4
	v_fmac_f32_e32 v14, v15, v15
	v_fma_f32 v11, v134, v11, -v5
	v_fmac_f32_e32 v14, v11, v11
	s_nop 1
	v_add_f32_dpp v4, v14, v14 quad_perm:[1,0,3,2] row_mask:0xf bank_mask:0xf
	s_nop 1
	v_add_f32_dpp v4, v4, v4 quad_perm:[2,3,0,1] row_mask:0xf bank_mask:0xf
	s_nop 1
	v_add_f32_dpp v4, v4, v4 row_half_mirror row_mask:0xf bank_mask:0xf
	s_nop 1
	v_add_f32_dpp v4, v4, v4 row_mirror row_mask:0xf bank_mask:0xf
	ds_swizzle_b32 v5, v4 offset:swizzle(SWAP,16)
	v_fma_f32 v27, v119, v23, -v16
	v_fmac_f32_e32 v26, v27, v27
	v_fma_f32 v23, v135, v23, -v17
	v_fmac_f32_e32 v26, v23, v23
	s_nop 1
	v_add_f32_dpp v16, v26, v26 quad_perm:[1,0,3,2] row_mask:0xf bank_mask:0xf
	s_nop 1
	v_add_f32_dpp v16, v16, v16 quad_perm:[2,3,0,1] row_mask:0xf bank_mask:0xf
	s_nop 1
	v_add_f32_dpp v16, v16, v16 row_half_mirror row_mask:0xf bank_mask:0xf
	s_nop 1
	v_add_f32_dpp v16, v16, v16 row_mirror row_mask:0xf bank_mask:0xf
	ds_swizzle_b32 v17, v16 offset:swizzle(SWAP,16)
	s_waitcnt lgkmcnt(0)
	v_add_f32_e32 v4, v4, v5
	v_fmamk_f32 v4, v4, 0x3c000000, v254
	v_rsq_f32_e32 v14, v4
	s_nop 0
	v_mul_f32_e32 v5, v12, v14
	v_mul_f32_e32 v12, v13, v14
	v_mul_f32_e32 v5, v7, v5
	v_mul_f32_e32 v12, v9, v12
	v_add_u32_e32 v4, 0x2000, v2
	v_cvt_pk_bf16_f32 v12, v5, v12
	v_mov_b32_e32 v5, v3
	v_lshl_add_u64 v[4:5], v[4:5], 1, s[6:7]
	global_store_short v[4:5], v12, off
	v_add_u32_e32 v4, 0x2020, v2
	v_mov_b32_e32 v5, v3
	v_lshl_add_u64 v[4:5], v[4:5], 1, s[6:7]
	global_store_short_d16_hi v[4:5], v12, off
	v_mul_f32_e32 v4, v15, v14
	v_mul_f32_e32 v5, v11, v14
	v_mul_f32_e32 v4, v6, v4
	v_mul_f32_e32 v5, v8, v5
	v_cvt_pk_bf16_f32 v11, v4, v5
	v_add_u32_e32 v4, 0x2040, v2
	v_mov_b32_e32 v5, v3
	v_lshl_add_u64 v[4:5], v[4:5], 1, s[6:7]
	global_store_short v[4:5], v11, off
	v_add_u32_e32 v4, 0x2060, v2
	v_mov_b32_e32 v5, v3
	v_lshl_add_u64 v[4:5], v[4:5], 1, s[6:7]
	global_store_short_d16_hi v[4:5], v11, off
	v_add_f32_e32 v16, v16, v17
	v_fmamk_f32 v16, v16, 0x3c000000, v254
	v_rsq_f32_e32 v26, v16
	s_nop 0
	v_mul_f32_e32 v17, v24, v26
	v_mul_f32_e32 v24, v25, v26
	v_mul_f32_e32 v17, v7, v17
	v_mul_f32_e32 v24, v9, v24
	v_add_u32_e32 v16, 0x3000, v2
	v_cvt_pk_bf16_f32 v24, v17, v24
	v_mov_b32_e32 v17, v3
	v_lshl_add_u64 v[16:17], v[16:17], 1, s[6:7]
	global_store_short v[16:17], v24, off
	v_add_u32_e32 v16, 0x3020, v2
	v_mov_b32_e32 v17, v3
	v_lshl_add_u64 v[16:17], v[16:17], 1, s[6:7]
	global_store_short_d16_hi v[16:17], v24, off
	v_mul_f32_e32 v16, v27, v26
	v_mul_f32_e32 v17, v23, v26
	v_mul_f32_e32 v16, v6, v16
	v_mul_f32_e32 v17, v8, v17
	v_cvt_pk_bf16_f32 v23, v16, v17
	v_add_u32_e32 v16, 0x3040, v2
	v_mov_b32_e32 v17, v3
	v_lshl_add_u64 v[16:17], v[16:17], 1, s[6:7]
	global_store_short v[16:17], v23, off
	v_add_u32_e32 v16, 0x3060, v2
	v_mov_b32_e32 v17, v3
	v_lshl_add_u64 v[16:17], v[16:17], 1, s[6:7]
	global_store_short_d16_hi v[16:17], v23, off
	ds_read_b32 v11, v10 offset:32
	ds_read2st64_b32 v[4:5], v1 offset0:4 offset1:20
	ds_read_b32 v23, v10 offset:36
	ds_read2st64_b32 v[16:17], v1 offset0:5 offset1:21
	s_waitcnt lgkmcnt(0)
	v_fma_f32 v12, v88, v11, -v4
	v_fma_f32 v13, v104, v11, -v5
	ds_read2st64_b32 v[4:5], v1 offset0:36 offset1:52
	v_mul_f32_e32 v14, v13, v13
	v_fmac_f32_e32 v14, v12, v12
	v_fma_f32 v24, v89, v23, -v16
	v_fma_f32 v25, v105, v23, -v17
	ds_read2st64_b32 v[16:17], v1 offset0:37 offset1:53
	v_mul_f32_e32 v26, v25, v25
	v_fmac_f32_e32 v26, v24, v24
	s_waitcnt lgkmcnt(0)
	v_fma_f32 v15, v120, v11, -v4
	v_fmac_f32_e32 v14, v15, v15
	v_fma_f32 v11, v136, v11, -v5
	v_fmac_f32_e32 v14, v11, v11
	s_nop 1
	v_add_f32_dpp v4, v14, v14 quad_perm:[1,0,3,2] row_mask:0xf bank_mask:0xf
	s_nop 1
	v_add_f32_dpp v4, v4, v4 quad_perm:[2,3,0,1] row_mask:0xf bank_mask:0xf
	s_nop 1
	v_add_f32_dpp v4, v4, v4 row_half_mirror row_mask:0xf bank_mask:0xf
	s_nop 1
	v_add_f32_dpp v4, v4, v4 row_mirror row_mask:0xf bank_mask:0xf
	ds_swizzle_b32 v5, v4 offset:swizzle(SWAP,16)
	v_fma_f32 v27, v121, v23, -v16
	v_fmac_f32_e32 v26, v27, v27
	v_fma_f32 v23, v137, v23, -v17
	v_fmac_f32_e32 v26, v23, v23
	s_nop 1
	v_add_f32_dpp v16, v26, v26 quad_perm:[1,0,3,2] row_mask:0xf bank_mask:0xf
	s_nop 1
	v_add_f32_dpp v16, v16, v16 quad_perm:[2,3,0,1] row_mask:0xf bank_mask:0xf
	s_nop 1
	v_add_f32_dpp v16, v16, v16 row_half_mirror row_mask:0xf bank_mask:0xf
	s_nop 1
	v_add_f32_dpp v16, v16, v16 row_mirror row_mask:0xf bank_mask:0xf
	ds_swizzle_b32 v17, v16 offset:swizzle(SWAP,16)
	s_waitcnt lgkmcnt(0)
	v_add_f32_e32 v4, v4, v5
	v_fmamk_f32 v4, v4, 0x3c000000, v254
	v_rsq_f32_e32 v14, v4
	s_nop 0
	v_mul_f32_e32 v5, v12, v14
	v_mul_f32_e32 v12, v13, v14
	v_mul_f32_e32 v5, v7, v5
	v_mul_f32_e32 v12, v9, v12
	v_add_u32_e32 v4, 0x8000, v2
	v_cvt_pk_bf16_f32 v12, v5, v12
	v_mov_b32_e32 v5, v3
	v_lshl_add_u64 v[4:5], v[4:5], 1, s[6:7]
	global_store_short v[4:5], v12, off
	v_add_u32_e32 v4, 0x8020, v2
	v_mov_b32_e32 v5, v3
	v_lshl_add_u64 v[4:5], v[4:5], 1, s[6:7]
	global_store_short_d16_hi v[4:5], v12, off
	v_mul_f32_e32 v4, v15, v14
	v_mul_f32_e32 v5, v11, v14
	v_mul_f32_e32 v4, v6, v4
	v_mul_f32_e32 v5, v8, v5
	v_cvt_pk_bf16_f32 v11, v4, v5
	v_add_u32_e32 v4, 0x8040, v2
	v_mov_b32_e32 v5, v3
	v_lshl_add_u64 v[4:5], v[4:5], 1, s[6:7]
	global_store_short v[4:5], v11, off
	v_add_u32_e32 v4, 0x8060, v2
	v_mov_b32_e32 v5, v3
	v_lshl_add_u64 v[4:5], v[4:5], 1, s[6:7]
	global_store_short_d16_hi v[4:5], v11, off
	v_add_f32_e32 v16, v16, v17
	v_fmamk_f32 v16, v16, 0x3c000000, v254
	v_rsq_f32_e32 v26, v16
	s_nop 0
	v_mul_f32_e32 v17, v24, v26
	v_mul_f32_e32 v24, v25, v26
	v_mul_f32_e32 v17, v7, v17
	v_mul_f32_e32 v24, v9, v24
	v_add_u32_e32 v16, 0x9000, v2
	v_cvt_pk_bf16_f32 v24, v17, v24
	v_mov_b32_e32 v17, v3
	v_lshl_add_u64 v[16:17], v[16:17], 1, s[6:7]
	global_store_short v[16:17], v24, off
	v_add_u32_e32 v16, 0x9020, v2
	v_mov_b32_e32 v17, v3
	v_lshl_add_u64 v[16:17], v[16:17], 1, s[6:7]
	global_store_short_d16_hi v[16:17], v24, off
	v_mul_f32_e32 v16, v27, v26
	v_mul_f32_e32 v17, v23, v26
	v_mul_f32_e32 v16, v6, v16
	v_mul_f32_e32 v17, v8, v17
	v_cvt_pk_bf16_f32 v23, v16, v17
	v_add_u32_e32 v16, 0x9040, v2
	v_mov_b32_e32 v17, v3
	v_lshl_add_u64 v[16:17], v[16:17], 1, s[6:7]
	global_store_short v[16:17], v23, off
	v_add_u32_e32 v16, 0x9060, v2
	v_mov_b32_e32 v17, v3
	v_lshl_add_u64 v[16:17], v[16:17], 1, s[6:7]
	global_store_short_d16_hi v[16:17], v23, off
	ds_read_b32 v11, v10 offset:40
	ds_read2st64_b32 v[4:5], v1 offset0:6 offset1:22
	ds_read_b32 v23, v10 offset:44
	ds_read2st64_b32 v[16:17], v1 offset0:7 offset1:23
	s_waitcnt lgkmcnt(0)
	v_fma_f32 v12, v90, v11, -v4
	v_fma_f32 v13, v106, v11, -v5
	ds_read2st64_b32 v[4:5], v1 offset0:38 offset1:54
	v_mul_f32_e32 v14, v13, v13
	v_fmac_f32_e32 v14, v12, v12
	v_fma_f32 v24, v91, v23, -v16
	v_fma_f32 v25, v107, v23, -v17
	ds_read2st64_b32 v[16:17], v1 offset0:39 offset1:55
	v_mul_f32_e32 v26, v25, v25
	v_fmac_f32_e32 v26, v24, v24
	s_waitcnt lgkmcnt(0)
	v_fma_f32 v15, v122, v11, -v4
	v_fmac_f32_e32 v14, v15, v15
	v_fma_f32 v11, v138, v11, -v5
	v_fmac_f32_e32 v14, v11, v11
	s_nop 1
	v_add_f32_dpp v4, v14, v14 quad_perm:[1,0,3,2] row_mask:0xf bank_mask:0xf
	s_nop 1
	v_add_f32_dpp v4, v4, v4 quad_perm:[2,3,0,1] row_mask:0xf bank_mask:0xf
	s_nop 1
	v_add_f32_dpp v4, v4, v4 row_half_mirror row_mask:0xf bank_mask:0xf
	s_nop 1
	v_add_f32_dpp v4, v4, v4 row_mirror row_mask:0xf bank_mask:0xf
	ds_swizzle_b32 v5, v4 offset:swizzle(SWAP,16)
	v_fma_f32 v27, v123, v23, -v16
	v_fmac_f32_e32 v26, v27, v27
	v_fma_f32 v23, v139, v23, -v17
	v_fmac_f32_e32 v26, v23, v23
	s_nop 1
	v_add_f32_dpp v16, v26, v26 quad_perm:[1,0,3,2] row_mask:0xf bank_mask:0xf
	s_nop 1
	v_add_f32_dpp v16, v16, v16 quad_perm:[2,3,0,1] row_mask:0xf bank_mask:0xf
	s_nop 1
	v_add_f32_dpp v16, v16, v16 row_half_mirror row_mask:0xf bank_mask:0xf
	s_nop 1
	v_add_f32_dpp v16, v16, v16 row_mirror row_mask:0xf bank_mask:0xf
	ds_swizzle_b32 v17, v16 offset:swizzle(SWAP,16)
	s_waitcnt lgkmcnt(0)
	v_add_f32_e32 v4, v4, v5
	v_fmamk_f32 v4, v4, 0x3c000000, v254
	v_rsq_f32_e32 v14, v4
	s_nop 0
	v_mul_f32_e32 v5, v12, v14
	v_mul_f32_e32 v12, v13, v14
	v_mul_f32_e32 v5, v7, v5
	v_mul_f32_e32 v12, v9, v12
	v_add_u32_e32 v4, 0xa000, v2
	v_cvt_pk_bf16_f32 v12, v5, v12
	v_mov_b32_e32 v5, v3
	v_lshl_add_u64 v[4:5], v[4:5], 1, s[6:7]
	global_store_short v[4:5], v12, off
	v_add_u32_e32 v4, 0xa020, v2
	v_mov_b32_e32 v5, v3
	v_lshl_add_u64 v[4:5], v[4:5], 1, s[6:7]
	global_store_short_d16_hi v[4:5], v12, off
	v_mul_f32_e32 v4, v15, v14
	v_mul_f32_e32 v5, v11, v14
	v_mul_f32_e32 v4, v6, v4
	v_mul_f32_e32 v5, v8, v5
	v_cvt_pk_bf16_f32 v11, v4, v5
	v_add_u32_e32 v4, 0xa040, v2
	v_mov_b32_e32 v5, v3
	v_lshl_add_u64 v[4:5], v[4:5], 1, s[6:7]
	global_store_short v[4:5], v11, off
	v_add_u32_e32 v4, 0xa060, v2
	v_mov_b32_e32 v5, v3
	v_lshl_add_u64 v[4:5], v[4:5], 1, s[6:7]
	global_store_short_d16_hi v[4:5], v11, off
	v_add_f32_e32 v16, v16, v17
	v_fmamk_f32 v16, v16, 0x3c000000, v254
	v_rsq_f32_e32 v26, v16
	s_nop 0
	v_mul_f32_e32 v17, v24, v26
	v_mul_f32_e32 v24, v25, v26
	v_mul_f32_e32 v17, v7, v17
	v_mul_f32_e32 v24, v9, v24
	v_add_u32_e32 v16, 0xb000, v2
	v_cvt_pk_bf16_f32 v24, v17, v24
	v_mov_b32_e32 v17, v3
	v_lshl_add_u64 v[16:17], v[16:17], 1, s[6:7]
	global_store_short v[16:17], v24, off
	v_add_u32_e32 v16, 0xb020, v2
	v_mov_b32_e32 v17, v3
	v_lshl_add_u64 v[16:17], v[16:17], 1, s[6:7]
	global_store_short_d16_hi v[16:17], v24, off
	v_mul_f32_e32 v16, v27, v26
	v_mul_f32_e32 v17, v23, v26
	v_mul_f32_e32 v16, v6, v16
	v_mul_f32_e32 v17, v8, v17
	v_cvt_pk_bf16_f32 v23, v16, v17
	v_add_u32_e32 v16, 0xb040, v2
	v_mov_b32_e32 v17, v3
	v_lshl_add_u64 v[16:17], v[16:17], 1, s[6:7]
	global_store_short v[16:17], v23, off
	v_add_u32_e32 v16, 0xb060, v2
	v_mov_b32_e32 v17, v3
	v_lshl_add_u64 v[16:17], v[16:17], 1, s[6:7]
	global_store_short_d16_hi v[16:17], v23, off
	ds_read_b32 v11, v10 offset:64
	ds_read2st64_b32 v[4:5], v1 offset0:8 offset1:24
	ds_read_b32 v23, v10 offset:68
	ds_read2st64_b32 v[16:17], v1 offset0:9 offset1:25
	s_waitcnt lgkmcnt(0)
	v_fma_f32 v12, v92, v11, -v4
	v_fma_f32 v13, v108, v11, -v5
	ds_read2st64_b32 v[4:5], v1 offset0:40 offset1:56
	v_mul_f32_e32 v14, v13, v13
	v_fmac_f32_e32 v14, v12, v12
	v_fma_f32 v24, v93, v23, -v16
	v_fma_f32 v25, v109, v23, -v17
	ds_read2st64_b32 v[16:17], v1 offset0:41 offset1:57
	v_mul_f32_e32 v26, v25, v25
	v_fmac_f32_e32 v26, v24, v24
	s_waitcnt lgkmcnt(0)
	v_fma_f32 v15, v124, v11, -v4
	v_fmac_f32_e32 v14, v15, v15
	v_fma_f32 v11, v140, v11, -v5
	v_fmac_f32_e32 v14, v11, v11
	s_nop 1
	v_add_f32_dpp v4, v14, v14 quad_perm:[1,0,3,2] row_mask:0xf bank_mask:0xf
	s_nop 1
	v_add_f32_dpp v4, v4, v4 quad_perm:[2,3,0,1] row_mask:0xf bank_mask:0xf
	s_nop 1
	v_add_f32_dpp v4, v4, v4 row_half_mirror row_mask:0xf bank_mask:0xf
	s_nop 1
	v_add_f32_dpp v4, v4, v4 row_mirror row_mask:0xf bank_mask:0xf
	ds_swizzle_b32 v5, v4 offset:swizzle(SWAP,16)
	v_fma_f32 v27, v125, v23, -v16
	v_fmac_f32_e32 v26, v27, v27
	v_fma_f32 v23, v141, v23, -v17
	v_fmac_f32_e32 v26, v23, v23
	s_nop 1
	v_add_f32_dpp v16, v26, v26 quad_perm:[1,0,3,2] row_mask:0xf bank_mask:0xf
	s_nop 1
	v_add_f32_dpp v16, v16, v16 quad_perm:[2,3,0,1] row_mask:0xf bank_mask:0xf
	s_nop 1
	v_add_f32_dpp v16, v16, v16 row_half_mirror row_mask:0xf bank_mask:0xf
	s_nop 1
	v_add_f32_dpp v16, v16, v16 row_mirror row_mask:0xf bank_mask:0xf
	ds_swizzle_b32 v17, v16 offset:swizzle(SWAP,16)
	s_waitcnt lgkmcnt(0)
	v_add_f32_e32 v4, v4, v5
	v_fmamk_f32 v4, v4, 0x3c000000, v254
	v_rsq_f32_e32 v14, v4
	s_nop 0
	v_mul_f32_e32 v5, v12, v14
	v_mul_f32_e32 v12, v13, v14
	v_mul_f32_e32 v5, v7, v5
	v_mul_f32_e32 v12, v9, v12
	v_add_u32_e32 v4, 0x10000, v2
	v_cvt_pk_bf16_f32 v12, v5, v12
	v_mov_b32_e32 v5, v3
	v_lshl_add_u64 v[4:5], v[4:5], 1, s[6:7]
	global_store_short v[4:5], v12, off
	v_add_u32_e32 v4, 0x10020, v2
	v_mov_b32_e32 v5, v3
	v_lshl_add_u64 v[4:5], v[4:5], 1, s[6:7]
	global_store_short_d16_hi v[4:5], v12, off
	v_mul_f32_e32 v4, v15, v14
	v_mul_f32_e32 v5, v11, v14
	v_mul_f32_e32 v4, v6, v4
	v_mul_f32_e32 v5, v8, v5
	v_cvt_pk_bf16_f32 v11, v4, v5
	v_add_u32_e32 v4, 0x10040, v2
	v_mov_b32_e32 v5, v3
	v_lshl_add_u64 v[4:5], v[4:5], 1, s[6:7]
	global_store_short v[4:5], v11, off
	v_add_u32_e32 v4, 0x10060, v2
	v_mov_b32_e32 v5, v3
	v_lshl_add_u64 v[4:5], v[4:5], 1, s[6:7]
	global_store_short_d16_hi v[4:5], v11, off
	v_add_f32_e32 v16, v16, v17
	v_fmamk_f32 v16, v16, 0x3c000000, v254
	v_rsq_f32_e32 v26, v16
	s_nop 0
	v_mul_f32_e32 v17, v24, v26
	v_mul_f32_e32 v24, v25, v26
	v_mul_f32_e32 v17, v7, v17
	v_mul_f32_e32 v24, v9, v24
	v_add_u32_e32 v16, 0x11000, v2
	v_cvt_pk_bf16_f32 v24, v17, v24
	v_mov_b32_e32 v17, v3
	v_lshl_add_u64 v[16:17], v[16:17], 1, s[6:7]
	global_store_short v[16:17], v24, off
	v_add_u32_e32 v16, 0x11020, v2
	v_mov_b32_e32 v17, v3
	v_lshl_add_u64 v[16:17], v[16:17], 1, s[6:7]
	global_store_short_d16_hi v[16:17], v24, off
	v_mul_f32_e32 v16, v27, v26
	v_mul_f32_e32 v17, v23, v26
	v_mul_f32_e32 v16, v6, v16
	v_mul_f32_e32 v17, v8, v17
	v_cvt_pk_bf16_f32 v23, v16, v17
	v_add_u32_e32 v16, 0x11040, v2
	v_mov_b32_e32 v17, v3
	v_lshl_add_u64 v[16:17], v[16:17], 1, s[6:7]
	global_store_short v[16:17], v23, off
	v_add_u32_e32 v16, 0x11060, v2
	v_mov_b32_e32 v17, v3
	v_lshl_add_u64 v[16:17], v[16:17], 1, s[6:7]
	global_store_short_d16_hi v[16:17], v23, off
	ds_read_b32 v11, v10 offset:72
	ds_read2st64_b32 v[4:5], v1 offset0:10 offset1:26
	ds_read_b32 v23, v10 offset:76
	ds_read2st64_b32 v[16:17], v1 offset0:11 offset1:27
	s_waitcnt lgkmcnt(0)
	v_fma_f32 v12, v94, v11, -v4
	v_fma_f32 v13, v110, v11, -v5
	ds_read2st64_b32 v[4:5], v1 offset0:42 offset1:58
	v_mul_f32_e32 v14, v13, v13
	v_fmac_f32_e32 v14, v12, v12
	v_fma_f32 v24, v95, v23, -v16
	v_fma_f32 v25, v111, v23, -v17
	ds_read2st64_b32 v[16:17], v1 offset0:43 offset1:59
	v_mul_f32_e32 v26, v25, v25
	v_fmac_f32_e32 v26, v24, v24
	s_waitcnt lgkmcnt(0)
	v_fma_f32 v15, v126, v11, -v4
	v_fmac_f32_e32 v14, v15, v15
	v_fma_f32 v11, v142, v11, -v5
	v_fmac_f32_e32 v14, v11, v11
	s_nop 1
	v_add_f32_dpp v4, v14, v14 quad_perm:[1,0,3,2] row_mask:0xf bank_mask:0xf
	s_nop 1
	v_add_f32_dpp v4, v4, v4 quad_perm:[2,3,0,1] row_mask:0xf bank_mask:0xf
	s_nop 1
	v_add_f32_dpp v4, v4, v4 row_half_mirror row_mask:0xf bank_mask:0xf
	s_nop 1
	v_add_f32_dpp v4, v4, v4 row_mirror row_mask:0xf bank_mask:0xf
	ds_swizzle_b32 v5, v4 offset:swizzle(SWAP,16)
	v_fma_f32 v27, v127, v23, -v16
	v_fmac_f32_e32 v26, v27, v27
	v_fma_f32 v23, v143, v23, -v17
	v_fmac_f32_e32 v26, v23, v23
	s_nop 1
	v_add_f32_dpp v16, v26, v26 quad_perm:[1,0,3,2] row_mask:0xf bank_mask:0xf
	s_nop 1
	v_add_f32_dpp v16, v16, v16 quad_perm:[2,3,0,1] row_mask:0xf bank_mask:0xf
	s_nop 1
	v_add_f32_dpp v16, v16, v16 row_half_mirror row_mask:0xf bank_mask:0xf
	s_nop 1
	v_add_f32_dpp v16, v16, v16 row_mirror row_mask:0xf bank_mask:0xf
	ds_swizzle_b32 v17, v16 offset:swizzle(SWAP,16)
	s_waitcnt lgkmcnt(0)
	v_add_f32_e32 v4, v4, v5
	v_fmamk_f32 v4, v4, 0x3c000000, v254
	v_rsq_f32_e32 v14, v4
	s_nop 0
	v_mul_f32_e32 v5, v12, v14
	v_mul_f32_e32 v12, v13, v14
	v_mul_f32_e32 v5, v7, v5
	v_mul_f32_e32 v12, v9, v12
	v_add_u32_e32 v4, 0x12000, v2
	v_cvt_pk_bf16_f32 v12, v5, v12
	v_mov_b32_e32 v5, v3
	v_lshl_add_u64 v[4:5], v[4:5], 1, s[6:7]
	global_store_short v[4:5], v12, off
	v_add_u32_e32 v4, 0x12020, v2
	v_mov_b32_e32 v5, v3
	v_lshl_add_u64 v[4:5], v[4:5], 1, s[6:7]
	global_store_short_d16_hi v[4:5], v12, off
	v_mul_f32_e32 v4, v15, v14
	v_mul_f32_e32 v5, v11, v14
	v_mul_f32_e32 v4, v6, v4
	v_mul_f32_e32 v5, v8, v5
	v_cvt_pk_bf16_f32 v11, v4, v5
	v_add_u32_e32 v4, 0x12040, v2
	v_mov_b32_e32 v5, v3
	v_lshl_add_u64 v[4:5], v[4:5], 1, s[6:7]
	global_store_short v[4:5], v11, off
	v_add_u32_e32 v4, 0x12060, v2
	v_mov_b32_e32 v5, v3
	v_lshl_add_u64 v[4:5], v[4:5], 1, s[6:7]
	global_store_short_d16_hi v[4:5], v11, off
	v_add_f32_e32 v16, v16, v17
	v_fmamk_f32 v16, v16, 0x3c000000, v254
	v_rsq_f32_e32 v26, v16
	s_nop 0
	v_mul_f32_e32 v17, v24, v26
	v_mul_f32_e32 v24, v25, v26
	v_mul_f32_e32 v17, v7, v17
	v_mul_f32_e32 v24, v9, v24
	v_add_u32_e32 v16, 0x13000, v2
	v_cvt_pk_bf16_f32 v24, v17, v24
	v_mov_b32_e32 v17, v3
	v_lshl_add_u64 v[16:17], v[16:17], 1, s[6:7]
	global_store_short v[16:17], v24, off
	v_add_u32_e32 v16, 0x13020, v2
	v_mov_b32_e32 v17, v3
	v_lshl_add_u64 v[16:17], v[16:17], 1, s[6:7]
	global_store_short_d16_hi v[16:17], v24, off
	v_mul_f32_e32 v16, v27, v26
	v_mul_f32_e32 v17, v23, v26
	v_mul_f32_e32 v16, v6, v16
	v_mul_f32_e32 v17, v8, v17
	v_cvt_pk_bf16_f32 v23, v16, v17
	v_add_u32_e32 v16, 0x13040, v2
	v_mov_b32_e32 v17, v3
	v_lshl_add_u64 v[16:17], v[16:17], 1, s[6:7]
	global_store_short v[16:17], v23, off
	v_add_u32_e32 v16, 0x13060, v2
	v_mov_b32_e32 v17, v3
	v_lshl_add_u64 v[16:17], v[16:17], 1, s[6:7]
	global_store_short_d16_hi v[16:17], v23, off
	ds_read_b32 v11, v10 offset:96
	ds_read2st64_b32 v[4:5], v1 offset0:12 offset1:28
	ds_read_b32 v23, v10 offset:100
	ds_read2st64_b32 v[16:17], v1 offset0:13 offset1:29
	s_waitcnt lgkmcnt(0)
	v_fma_f32 v12, v96, v11, -v4
	v_fma_f32 v13, v112, v11, -v5
	ds_read2st64_b32 v[4:5], v1 offset0:44 offset1:60
	v_mul_f32_e32 v14, v13, v13
	v_fmac_f32_e32 v14, v12, v12
	v_fma_f32 v24, v97, v23, -v16
	v_fma_f32 v25, v113, v23, -v17
	ds_read2st64_b32 v[16:17], v1 offset0:45 offset1:61
	v_mul_f32_e32 v26, v25, v25
	v_fmac_f32_e32 v26, v24, v24
	s_waitcnt lgkmcnt(0)
	v_fma_f32 v15, v128, v11, -v4
	v_fmac_f32_e32 v14, v15, v15
	v_fma_f32 v11, v144, v11, -v5
	v_fmac_f32_e32 v14, v11, v11
	s_nop 1
	v_add_f32_dpp v4, v14, v14 quad_perm:[1,0,3,2] row_mask:0xf bank_mask:0xf
	s_nop 1
	v_add_f32_dpp v4, v4, v4 quad_perm:[2,3,0,1] row_mask:0xf bank_mask:0xf
	s_nop 1
	v_add_f32_dpp v4, v4, v4 row_half_mirror row_mask:0xf bank_mask:0xf
	s_nop 1
	v_add_f32_dpp v4, v4, v4 row_mirror row_mask:0xf bank_mask:0xf
	ds_swizzle_b32 v5, v4 offset:swizzle(SWAP,16)
	v_fma_f32 v27, v129, v23, -v16
	v_fmac_f32_e32 v26, v27, v27
	v_fma_f32 v23, v145, v23, -v17
	v_fmac_f32_e32 v26, v23, v23
	s_nop 1
	v_add_f32_dpp v16, v26, v26 quad_perm:[1,0,3,2] row_mask:0xf bank_mask:0xf
	s_nop 1
	v_add_f32_dpp v16, v16, v16 quad_perm:[2,3,0,1] row_mask:0xf bank_mask:0xf
	s_nop 1
	v_add_f32_dpp v16, v16, v16 row_half_mirror row_mask:0xf bank_mask:0xf
	s_nop 1
	v_add_f32_dpp v16, v16, v16 row_mirror row_mask:0xf bank_mask:0xf
	ds_swizzle_b32 v17, v16 offset:swizzle(SWAP,16)
	s_waitcnt lgkmcnt(0)
	v_add_f32_e32 v4, v4, v5
	v_fmamk_f32 v4, v4, 0x3c000000, v254
	v_rsq_f32_e32 v14, v4
	s_nop 0
	v_mul_f32_e32 v5, v12, v14
	v_mul_f32_e32 v12, v13, v14
	v_mul_f32_e32 v5, v7, v5
	v_mul_f32_e32 v12, v9, v12
	v_add_u32_e32 v4, 0x18000, v2
	v_cvt_pk_bf16_f32 v12, v5, v12
	v_mov_b32_e32 v5, v3
	v_lshl_add_u64 v[4:5], v[4:5], 1, s[6:7]
	global_store_short v[4:5], v12, off
	v_add_u32_e32 v4, 0x18020, v2
	v_mov_b32_e32 v5, v3
	v_lshl_add_u64 v[4:5], v[4:5], 1, s[6:7]
	global_store_short_d16_hi v[4:5], v12, off
	v_mul_f32_e32 v4, v15, v14
	v_mul_f32_e32 v5, v11, v14
	v_mul_f32_e32 v4, v6, v4
	v_mul_f32_e32 v5, v8, v5
	v_cvt_pk_bf16_f32 v11, v4, v5
	v_add_u32_e32 v4, 0x18040, v2
	v_mov_b32_e32 v5, v3
	v_lshl_add_u64 v[4:5], v[4:5], 1, s[6:7]
	global_store_short v[4:5], v11, off
	v_add_u32_e32 v4, 0x18060, v2
	v_mov_b32_e32 v5, v3
	v_lshl_add_u64 v[4:5], v[4:5], 1, s[6:7]
	global_store_short_d16_hi v[4:5], v11, off
	v_add_f32_e32 v16, v16, v17
	v_fmamk_f32 v16, v16, 0x3c000000, v254
	v_rsq_f32_e32 v26, v16
	s_nop 0
	v_mul_f32_e32 v17, v24, v26
	v_mul_f32_e32 v24, v25, v26
	v_mul_f32_e32 v17, v7, v17
	v_mul_f32_e32 v24, v9, v24
	v_add_u32_e32 v16, 0x19000, v2
	v_cvt_pk_bf16_f32 v24, v17, v24
	v_mov_b32_e32 v17, v3
	v_lshl_add_u64 v[16:17], v[16:17], 1, s[6:7]
	global_store_short v[16:17], v24, off
	v_add_u32_e32 v16, 0x19020, v2
	v_mov_b32_e32 v17, v3
	v_lshl_add_u64 v[16:17], v[16:17], 1, s[6:7]
	global_store_short_d16_hi v[16:17], v24, off
	v_mul_f32_e32 v16, v27, v26
	v_mul_f32_e32 v17, v23, v26
	v_mul_f32_e32 v16, v6, v16
	v_mul_f32_e32 v17, v8, v17
	v_cvt_pk_bf16_f32 v23, v16, v17
	v_add_u32_e32 v16, 0x19040, v2
	v_mov_b32_e32 v17, v3
	v_lshl_add_u64 v[16:17], v[16:17], 1, s[6:7]
	global_store_short v[16:17], v23, off
	v_add_u32_e32 v16, 0x19060, v2
	v_mov_b32_e32 v17, v3
	v_lshl_add_u64 v[16:17], v[16:17], 1, s[6:7]
	global_store_short_d16_hi v[16:17], v23, off
	ds_read_b32 v11, v10 offset:104
	ds_read2st64_b32 v[4:5], v1 offset0:14 offset1:30
	s_waitcnt lgkmcnt(0)
	v_fma_f32 v12, v98, v11, -v4
	v_fma_f32 v13, v114, v11, -v5
	ds_read2st64_b32 v[4:5], v1 offset0:46 offset1:62
	v_mul_f32_e32 v14, v13, v13
	v_fmac_f32_e32 v14, v12, v12
	s_waitcnt lgkmcnt(0)
	v_fma_f32 v15, v130, v11, -v4
	v_fmac_f32_e32 v14, v15, v15
	v_fma_f32 v11, v146, v11, -v5
	v_fmac_f32_e32 v14, v11, v11
	s_nop 1
	v_add_f32_dpp v4, v14, v14 quad_perm:[1,0,3,2] row_mask:0xf bank_mask:0xf
	s_nop 1
	v_add_f32_dpp v4, v4, v4 quad_perm:[2,3,0,1] row_mask:0xf bank_mask:0xf
	s_nop 1
	v_add_f32_dpp v4, v4, v4 row_half_mirror row_mask:0xf bank_mask:0xf
	s_nop 1
	v_add_f32_dpp v4, v4, v4 row_mirror row_mask:0xf bank_mask:0xf
	ds_swizzle_b32 v5, v4 offset:swizzle(SWAP,16)
	s_waitcnt lgkmcnt(0)
	v_add_f32_e32 v4, v4, v5
	v_fmamk_f32 v4, v4, 0x3c000000, v254
	v_rsq_f32_e32 v14, v4
	s_nop 0
	v_mul_f32_e32 v5, v12, v14
	v_mul_f32_e32 v12, v13, v14
	v_mul_f32_e32 v5, v7, v5
	v_mul_f32_e32 v12, v9, v12
	v_add_u32_e32 v4, 0x1a000, v2
	v_cvt_pk_bf16_f32 v12, v5, v12
	v_mov_b32_e32 v5, v3
	v_lshl_add_u64 v[4:5], v[4:5], 1, s[6:7]
	global_store_short v[4:5], v12, off
	v_add_u32_e32 v4, 0x1a020, v2
	v_mov_b32_e32 v5, v3
	v_lshl_add_u64 v[4:5], v[4:5], 1, s[6:7]
	global_store_short_d16_hi v[4:5], v12, off
	v_mul_f32_e32 v4, v15, v14
	v_mul_f32_e32 v5, v11, v14
	v_mul_f32_e32 v4, v6, v4
	v_mul_f32_e32 v5, v8, v5
	v_cvt_pk_bf16_f32 v11, v4, v5
	v_add_u32_e32 v4, 0x1a040, v2
	v_mov_b32_e32 v5, v3
	v_lshl_add_u64 v[4:5], v[4:5], 1, s[6:7]
	global_store_short v[4:5], v11, off
	v_add_u32_e32 v4, 0x1a060, v2
	v_mov_b32_e32 v5, v3
	v_lshl_add_u64 v[4:5], v[4:5], 1, s[6:7]
	global_store_short_d16_hi v[4:5], v11, off
	ds_read_b32 v10, v10 offset:108
	ds_read2st64_b32 v[4:5], v1 offset0:15 offset1:31
	s_waitcnt lgkmcnt(0)
	v_fma_f32 v11, v99, v10, -v4
	v_fma_f32 v12, v115, v10, -v5
	ds_read2st64_b32 v[4:5], v1 offset0:47 offset1:63
	v_mul_f32_e32 v13, v12, v12
	v_fmac_f32_e32 v13, v11, v11
	s_waitcnt lgkmcnt(0)
	v_fma_f32 v1, v131, v10, -v4
	v_fmac_f32_e32 v13, v1, v1
	v_fma_f32 v10, v147, v10, -v5
	v_fmac_f32_e32 v13, v10, v10
	s_nop 1
	v_add_f32_dpp v4, v13, v13 quad_perm:[1,0,3,2] row_mask:0xf bank_mask:0xf
	s_nop 1
	v_add_f32_dpp v4, v4, v4 quad_perm:[2,3,0,1] row_mask:0xf bank_mask:0xf
	s_nop 1
	v_add_f32_dpp v4, v4, v4 row_half_mirror row_mask:0xf bank_mask:0xf
	s_nop 1
	v_add_f32_dpp v4, v4, v4 row_mirror row_mask:0xf bank_mask:0xf
	ds_swizzle_b32 v5, v4 offset:swizzle(SWAP,16)
	s_waitcnt lgkmcnt(0)
	v_add_f32_e32 v4, v4, v5
	v_fmamk_f32 v4, v4, 0x3c000000, v254
	v_rsq_f32_e32 v13, v4
	s_nop 0
	v_mul_f32_e32 v5, v11, v13
	v_mul_f32_e32 v5, v7, v5
	v_mul_f32_e32 v7, v12, v13
	v_mul_f32_e32 v7, v9, v7
	v_add_u32_e32 v4, 0x1b000, v2
	v_cvt_pk_bf16_f32 v7, v5, v7
	v_mov_b32_e32 v5, v3
	v_lshl_add_u64 v[4:5], v[4:5], 1, s[6:7]
	global_store_short v[4:5], v7, off
	v_add_u32_e32 v4, 0x1b020, v2
	v_mov_b32_e32 v5, v3
	v_lshl_add_u64 v[4:5], v[4:5], 1, s[6:7]
	global_store_short_d16_hi v[4:5], v7, off
	v_mul_f32_e32 v1, v1, v13
	v_mul_f32_e32 v4, v10, v13
	v_mul_f32_e32 v1, v6, v1
	v_mul_f32_e32 v4, v8, v4
	v_cvt_pk_bf16_f32 v1, v1, v4
	v_add_u32_e32 v4, 0x1b040, v2
	v_mov_b32_e32 v5, v3
	v_lshl_add_u64 v[4:5], v[4:5], 1, s[6:7]
	v_add_u32_e32 v2, 0x1b060, v2
	global_store_short v[4:5], v1, off
	v_lshl_add_u64 v[4:5], v[2:3], 1, s[6:7]
	global_store_short_d16_hi v[4:5], v1, off

.LBB0_1235:
	s_or_b64 exec, exec, s[4:5]
	s_waitcnt lgkmcnt(0)
	v_add_u32_e32 v4, s43, v148
	ds_read_b32 v16, v4
	ds_read_b32 v17, v4 offset:4
	ds_read_b32 v18, v4 offset:8
	ds_read_b32 v19, v4 offset:12
	ds_read_b32 v20, v4 offset:32
	ds_read_b32 v21, v4 offset:36
	ds_read_b32 v22, v4 offset:40
	ds_read_b32 v23, v4 offset:44
	ds_read_b32 v24, v4 offset:64
	ds_read_b32 v25, v4 offset:68
	ds_read_b32 v26, v4 offset:72
	ds_read_b32 v27, v4 offset:76
	ds_read_b32 v28, v4 offset:96
	ds_read_b32 v29, v4 offset:100
	ds_read_b32 v30, v4 offset:104
	ds_read_b32 v31, v4 offset:108
	s_waitcnt lgkmcnt(0)
	v_mul_f32_e32 v6, v68, v16
	ds_write_b32 v1, v6
	v_mul_f32_e32 v6, v84, v16
	ds_write_b32 v1, v6 offset:4096
	v_mul_f32_e32 v6, v100, v16
	v_mul_f32_e32 v16, v116, v16
	ds_write_b32 v1, v6 offset:8192
	ds_write_b32 v1, v16 offset:12288
	v_mul_f32_e32 v6, v69, v17
	ds_write_b32 v1, v6 offset:256
	v_mul_f32_e32 v6, v85, v17
	ds_write_b32 v1, v6 offset:4352
	v_mul_f32_e32 v6, v101, v17
	v_mul_f32_e32 v17, v117, v17
	ds_write_b32 v1, v6 offset:8448
	ds_write_b32 v1, v17 offset:12544
	v_mul_f32_e32 v6, v70, v18
	ds_write_b32 v1, v6 offset:512
	v_mul_f32_e32 v6, v86, v18
	ds_write_b32 v1, v6 offset:4608
	v_mul_f32_e32 v6, v102, v18
	v_mul_f32_e32 v18, v118, v18
	ds_write_b32 v1, v6 offset:8704
	ds_write_b32 v1, v18 offset:12800
	v_mul_f32_e32 v6, v71, v19
	ds_write_b32 v1, v6 offset:768
	v_mul_f32_e32 v6, v87, v19
	ds_write_b32 v1, v6 offset:4864
	v_mul_f32_e32 v6, v103, v19
	v_mul_f32_e32 v19, v119, v19
	ds_write_b32 v1, v6 offset:8960
	ds_write_b32 v1, v19 offset:13056
	v_mul_f32_e32 v6, v72, v20
	ds_write_b32 v1, v6 offset:1024
	v_mul_f32_e32 v6, v88, v20
	ds_write_b32 v1, v6 offset:5120
	v_mul_f32_e32 v6, v104, v20
	v_mul_f32_e32 v20, v120, v20
	ds_write_b32 v1, v6 offset:9216
	ds_write_b32 v1, v20 offset:13312
	v_mul_f32_e32 v6, v73, v21
	ds_write_b32 v1, v6 offset:1280
	v_mul_f32_e32 v6, v89, v21
	ds_write_b32 v1, v6 offset:5376
	v_mul_f32_e32 v6, v105, v21
	v_mul_f32_e32 v21, v121, v21
	ds_write_b32 v1, v6 offset:9472
	ds_write_b32 v1, v21 offset:13568
	v_mul_f32_e32 v6, v74, v22
	ds_write_b32 v1, v6 offset:1536
	v_mul_f32_e32 v6, v90, v22
	ds_write_b32 v1, v6 offset:5632
	v_mul_f32_e32 v6, v106, v22
	v_mul_f32_e32 v22, v122, v22
	ds_write_b32 v1, v6 offset:9728
	ds_write_b32 v1, v22 offset:13824
	v_mul_f32_e32 v6, v75, v23
	ds_write_b32 v1, v6 offset:1792
	v_mul_f32_e32 v6, v91, v23
	ds_write_b32 v1, v6 offset:5888
	v_mul_f32_e32 v6, v107, v23
	v_mul_f32_e32 v23, v123, v23
	ds_write_b32 v1, v6 offset:9984
	ds_write_b32 v1, v23 offset:14080
	v_mul_f32_e32 v6, v76, v24
	ds_write_b32 v1, v6 offset:2048
	v_mul_f32_e32 v6, v92, v24
	ds_write_b32 v1, v6 offset:6144
	v_mul_f32_e32 v6, v108, v24
	v_mul_f32_e32 v24, v124, v24
	ds_write_b32 v1, v6 offset:10240
	ds_write_b32 v1, v24 offset:14336
	v_mul_f32_e32 v6, v77, v25
	ds_write_b32 v1, v6 offset:2304
	v_mul_f32_e32 v6, v93, v25
	ds_write_b32 v1, v6 offset:6400
	v_mul_f32_e32 v6, v109, v25
	v_mul_f32_e32 v25, v125, v25
	ds_write_b32 v1, v6 offset:10496
	ds_write_b32 v1, v25 offset:14592
	v_mul_f32_e32 v6, v78, v26
	ds_write_b32 v1, v6 offset:2560
	v_mul_f32_e32 v6, v94, v26
	ds_write_b32 v1, v6 offset:6656
	v_mul_f32_e32 v6, v110, v26
	v_mul_f32_e32 v26, v126, v26
	ds_write_b32 v1, v6 offset:10752
	ds_write_b32 v1, v26 offset:14848
	v_mul_f32_e32 v6, v79, v27
	ds_write_b32 v1, v6 offset:2816
	v_mul_f32_e32 v6, v95, v27
	ds_write_b32 v1, v6 offset:6912
	v_mul_f32_e32 v6, v111, v27
	v_mul_f32_e32 v27, v127, v27
	ds_write_b32 v1, v6 offset:11008
	ds_write_b32 v1, v27 offset:15104
	v_mul_f32_e32 v6, v80, v28
	ds_write_b32 v1, v6 offset:3072
	v_mul_f32_e32 v6, v96, v28
	ds_write_b32 v1, v6 offset:7168
	v_mul_f32_e32 v6, v112, v28
	v_mul_f32_e32 v28, v128, v28
	ds_write_b32 v1, v6 offset:11264
	ds_write_b32 v1, v28 offset:15360
	v_mul_f32_e32 v6, v81, v29
	ds_write_b32 v1, v6 offset:3328
	v_mul_f32_e32 v6, v97, v29
	ds_write_b32 v1, v6 offset:7424
	v_mul_f32_e32 v6, v113, v29
	v_mul_f32_e32 v29, v129, v29
	ds_write_b32 v1, v6 offset:11520
	ds_write_b32 v1, v29 offset:15616
	v_mul_f32_e32 v6, v82, v30
	ds_write_b32 v1, v6 offset:3584
	v_mul_f32_e32 v6, v98, v30
	ds_write_b32 v1, v6 offset:7680
	v_mul_f32_e32 v6, v114, v30
	v_mul_f32_e32 v30, v130, v30
	ds_write_b32 v1, v6 offset:11776
	ds_write_b32 v1, v30 offset:15872
	v_mul_f32_e32 v5, v83, v31
	ds_write_b32 v1, v5 offset:3840
	v_mul_f32_e32 v5, v99, v31
	ds_write_b32 v1, v5 offset:7936
	v_mul_f32_e32 v5, v115, v31
	v_mul_f32_e32 v31, v131, v31
	ds_write_b32 v1, v5 offset:12032
	ds_write_b32 v1, v31 offset:16128
	v_mov_b32_e32 v5, v30
	v_mov_b32_e32 v4, v31

.LBB0_1239:
	s_or_b64 exec, exec, s[4:5]
	s_waitcnt lgkmcnt(0)
	v_lshlrev_b32_e32 v2, 2, v158
	global_load_dword v249, v2, s[0:1]
	global_load_dword v250, v2, s[0:1] offset:128
	global_load_dword v251, v2, s[0:1] offset:256
	global_load_dword v253, v2, s[0:1] offset:384
	v_add_u32_e32 v10, s43, v148
	s_lshl_b64 s[4:5], s[24:25], 13
	s_add_u32 s4, s86, s4
	s_addc_u32 s5, s87, s5
	s_lshl_b32 s6, s8, 1
	s_add_u32 s6, s4, s6
	s_addc_u32 s7, s5, 0
	s_waitcnt vmcnt(0)
	v_mul_f32_e32 v7, v164, v249
	v_mul_f32_e32 v9, v164, v250
	v_mul_f32_e32 v6, v164, v251
	v_mul_f32_e32 v8, v164, v253
	v_lshl_or_b32 v2, v159, 14, v158
	ds_read_b32 v11, v10
	ds_read2st64_b32 v[4:5], v1 offset1:16
	ds_read_b32 v23, v10 offset:4
	ds_read2st64_b32 v[16:17], v1 offset0:1 offset1:17
	s_waitcnt lgkmcnt(0)
	v_fma_f32 v12, v68, v11, -v4
	v_fma_f32 v13, v84, v11, -v5
	ds_read2st64_b32 v[4:5], v1 offset0:32 offset1:48
	v_mul_f32_e32 v14, v13, v13
	v_fmac_f32_e32 v14, v12, v12
	v_fma_f32 v24, v69, v23, -v16
	v_fma_f32 v25, v85, v23, -v17
	ds_read2st64_b32 v[16:17], v1 offset0:33 offset1:49
	v_mul_f32_e32 v26, v25, v25
	v_fmac_f32_e32 v26, v24, v24
	s_waitcnt lgkmcnt(0)
	v_fma_f32 v15, v100, v11, -v4
	v_fmac_f32_e32 v14, v15, v15
	v_fma_f32 v11, v116, v11, -v5
	v_fmac_f32_e32 v14, v11, v11
	s_nop 1
	v_add_f32_dpp v4, v14, v14 quad_perm:[1,0,3,2] row_mask:0xf bank_mask:0xf
	s_nop 1
	v_add_f32_dpp v4, v4, v4 quad_perm:[2,3,0,1] row_mask:0xf bank_mask:0xf
	s_nop 1
	v_add_f32_dpp v4, v4, v4 row_half_mirror row_mask:0xf bank_mask:0xf
	s_nop 1
	v_add_f32_dpp v4, v4, v4 row_mirror row_mask:0xf bank_mask:0xf
	ds_swizzle_b32 v5, v4 offset:swizzle(SWAP,16)
	v_fma_f32 v27, v101, v23, -v16
	v_fmac_f32_e32 v26, v27, v27
	v_fma_f32 v23, v117, v23, -v17
	v_fmac_f32_e32 v26, v23, v23
	s_nop 1
	v_add_f32_dpp v16, v26, v26 quad_perm:[1,0,3,2] row_mask:0xf bank_mask:0xf
	s_nop 1
	v_add_f32_dpp v16, v16, v16 quad_perm:[2,3,0,1] row_mask:0xf bank_mask:0xf
	s_nop 1
	v_add_f32_dpp v16, v16, v16 row_half_mirror row_mask:0xf bank_mask:0xf
	s_nop 1
	v_add_f32_dpp v16, v16, v16 row_mirror row_mask:0xf bank_mask:0xf
	ds_swizzle_b32 v17, v16 offset:swizzle(SWAP,16)
	s_waitcnt lgkmcnt(0)
	v_add_f32_e32 v4, v4, v5
	v_fmamk_f32 v4, v4, 0x3c000000, v254
	v_rsq_f32_e32 v14, v4
	s_nop 0
	v_mul_f32_e32 v4, v12, v14
	v_mul_f32_e32 v5, v13, v14
	v_mul_f32_e32 v4, v7, v4
	v_mul_f32_e32 v5, v9, v5
	v_cvt_pk_bf16_f32 v12, v4, v5
	v_lshl_add_u64 v[4:5], v[2:3], 1, s[6:7]
	global_store_short v[4:5], v12, off
	v_add_u32_e32 v4, 32, v2
	v_mov_b32_e32 v5, v3
	v_lshl_add_u64 v[4:5], v[4:5], 1, s[6:7]
	global_store_short_d16_hi v[4:5], v12, off
	v_mul_f32_e32 v4, v15, v14
	v_mul_f32_e32 v5, v11, v14
	v_mul_f32_e32 v4, v6, v4
	v_mul_f32_e32 v5, v8, v5
	v_cvt_pk_bf16_f32 v11, v4, v5
	v_add_u32_e32 v4, 64, v2
	v_mov_b32_e32 v5, v3
	v_lshl_add_u64 v[4:5], v[4:5], 1, s[6:7]
	global_store_short v[4:5], v11, off
	v_add_u32_e32 v4, 0x60, v2
	v_mov_b32_e32 v5, v3
	v_lshl_add_u64 v[4:5], v[4:5], 1, s[6:7]
	global_store_short_d16_hi v[4:5], v11, off
	v_add_f32_e32 v16, v16, v17
	v_fmamk_f32 v16, v16, 0x3c000000, v254
	v_rsq_f32_e32 v26, v16
	s_nop 0
	v_mul_f32_e32 v17, v24, v26
	v_mul_f32_e32 v24, v25, v26
	v_mul_f32_e32 v17, v7, v17
	v_mul_f32_e32 v24, v9, v24
	v_add_u32_e32 v16, 0x1000, v2
	v_cvt_pk_bf16_f32 v24, v17, v24
	v_mov_b32_e32 v17, v3
	v_lshl_add_u64 v[16:17], v[16:17], 1, s[6:7]
	global_store_short v[16:17], v24, off
	v_add_u32_e32 v16, 0x1020, v2
	v_mov_b32_e32 v17, v3
	v_lshl_add_u64 v[16:17], v[16:17], 1, s[6:7]
	global_store_short_d16_hi v[16:17], v24, off
	v_mul_f32_e32 v16, v27, v26
	v_mul_f32_e32 v17, v23, v26
	v_mul_f32_e32 v16, v6, v16
	v_mul_f32_e32 v17, v8, v17
	v_cvt_pk_bf16_f32 v23, v16, v17
	v_add_u32_e32 v16, 0x1040, v2
	v_mov_b32_e32 v17, v3
	v_lshl_add_u64 v[16:17], v[16:17], 1, s[6:7]
	global_store_short v[16:17], v23, off
	v_add_u32_e32 v16, 0x1060, v2
	v_mov_b32_e32 v17, v3
	v_lshl_add_u64 v[16:17], v[16:17], 1, s[6:7]
	global_store_short_d16_hi v[16:17], v23, off
	ds_read_b32 v11, v10 offset:8
	ds_read2st64_b32 v[4:5], v1 offset0:2 offset1:18
	ds_read_b32 v23, v10 offset:12
	ds_read2st64_b32 v[16:17], v1 offset0:3 offset1:19
	s_waitcnt lgkmcnt(0)
	v_fma_f32 v12, v70, v11, -v4
	v_fma_f32 v13, v86, v11, -v5
	ds_read2st64_b32 v[4:5], v1 offset0:34 offset1:50
	v_mul_f32_e32 v14, v13, v13
	v_fmac_f32_e32 v14, v12, v12
	v_fma_f32 v24, v71, v23, -v16
	v_fma_f32 v25, v87, v23, -v17
	ds_read2st64_b32 v[16:17], v1 offset0:35 offset1:51
	v_mul_f32_e32 v26, v25, v25
	v_fmac_f32_e32 v26, v24, v24
	s_waitcnt lgkmcnt(0)
	v_fma_f32 v15, v102, v11, -v4
	v_fmac_f32_e32 v14, v15, v15
	v_fma_f32 v11, v118, v11, -v5
	v_fmac_f32_e32 v14, v11, v11
	s_nop 1
	v_add_f32_dpp v4, v14, v14 quad_perm:[1,0,3,2] row_mask:0xf bank_mask:0xf
	s_nop 1
	v_add_f32_dpp v4, v4, v4 quad_perm:[2,3,0,1] row_mask:0xf bank_mask:0xf
	s_nop 1
	v_add_f32_dpp v4, v4, v4 row_half_mirror row_mask:0xf bank_mask:0xf
	s_nop 1
	v_add_f32_dpp v4, v4, v4 row_mirror row_mask:0xf bank_mask:0xf
	ds_swizzle_b32 v5, v4 offset:swizzle(SWAP,16)
	v_fma_f32 v27, v103, v23, -v16
	v_fmac_f32_e32 v26, v27, v27
	v_fma_f32 v23, v119, v23, -v17
	v_fmac_f32_e32 v26, v23, v23
	s_nop 1
	v_add_f32_dpp v16, v26, v26 quad_perm:[1,0,3,2] row_mask:0xf bank_mask:0xf
	s_nop 1
	v_add_f32_dpp v16, v16, v16 quad_perm:[2,3,0,1] row_mask:0xf bank_mask:0xf
	s_nop 1
	v_add_f32_dpp v16, v16, v16 row_half_mirror row_mask:0xf bank_mask:0xf
	s_nop 1
	v_add_f32_dpp v16, v16, v16 row_mirror row_mask:0xf bank_mask:0xf
	ds_swizzle_b32 v17, v16 offset:swizzle(SWAP,16)
	s_waitcnt lgkmcnt(0)
	v_add_f32_e32 v4, v4, v5
	v_fmamk_f32 v4, v4, 0x3c000000, v254
	v_rsq_f32_e32 v14, v4
	s_nop 0
	v_mul_f32_e32 v5, v12, v14
	v_mul_f32_e32 v12, v13, v14
	v_mul_f32_e32 v5, v7, v5
	v_mul_f32_e32 v12, v9, v12
	v_add_u32_e32 v4, 0x2000, v2
	v_cvt_pk_bf16_f32 v12, v5, v12
	v_mov_b32_e32 v5, v3
	v_lshl_add_u64 v[4:5], v[4:5], 1, s[6:7]
	global_store_short v[4:5], v12, off
	v_add_u32_e32 v4, 0x2020, v2
	v_mov_b32_e32 v5, v3
	v_lshl_add_u64 v[4:5], v[4:5], 1, s[6:7]
	global_store_short_d16_hi v[4:5], v12, off
	v_mul_f32_e32 v4, v15, v14
	v_mul_f32_e32 v5, v11, v14
	v_mul_f32_e32 v4, v6, v4
	v_mul_f32_e32 v5, v8, v5
	v_cvt_pk_bf16_f32 v11, v4, v5
	v_add_u32_e32 v4, 0x2040, v2
	v_mov_b32_e32 v5, v3
	v_lshl_add_u64 v[4:5], v[4:5], 1, s[6:7]
	global_store_short v[4:5], v11, off
	v_add_u32_e32 v4, 0x2060, v2
	v_mov_b32_e32 v5, v3
	v_lshl_add_u64 v[4:5], v[4:5], 1, s[6:7]
	global_store_short_d16_hi v[4:5], v11, off
	v_add_f32_e32 v16, v16, v17
	v_fmamk_f32 v16, v16, 0x3c000000, v254
	v_rsq_f32_e32 v26, v16
	s_nop 0
	v_mul_f32_e32 v17, v24, v26
	v_mul_f32_e32 v24, v25, v26
	v_mul_f32_e32 v17, v7, v17
	v_mul_f32_e32 v24, v9, v24
	v_add_u32_e32 v16, 0x3000, v2
	v_cvt_pk_bf16_f32 v24, v17, v24
	v_mov_b32_e32 v17, v3
	v_lshl_add_u64 v[16:17], v[16:17], 1, s[6:7]
	global_store_short v[16:17], v24, off
	v_add_u32_e32 v16, 0x3020, v2
	v_mov_b32_e32 v17, v3
	v_lshl_add_u64 v[16:17], v[16:17], 1, s[6:7]
	global_store_short_d16_hi v[16:17], v24, off
	v_mul_f32_e32 v16, v27, v26
	v_mul_f32_e32 v17, v23, v26
	v_mul_f32_e32 v16, v6, v16
	v_mul_f32_e32 v17, v8, v17
	v_cvt_pk_bf16_f32 v23, v16, v17
	v_add_u32_e32 v16, 0x3040, v2
	v_mov_b32_e32 v17, v3
	v_lshl_add_u64 v[16:17], v[16:17], 1, s[6:7]
	global_store_short v[16:17], v23, off
	v_add_u32_e32 v16, 0x3060, v2
	v_mov_b32_e32 v17, v3
	v_lshl_add_u64 v[16:17], v[16:17], 1, s[6:7]
	global_store_short_d16_hi v[16:17], v23, off
	ds_read_b32 v11, v10 offset:32
	ds_read2st64_b32 v[4:5], v1 offset0:4 offset1:20
	ds_read_b32 v23, v10 offset:36
	ds_read2st64_b32 v[16:17], v1 offset0:5 offset1:21
	s_waitcnt lgkmcnt(0)
	v_fma_f32 v12, v72, v11, -v4
	v_fma_f32 v13, v88, v11, -v5
	ds_read2st64_b32 v[4:5], v1 offset0:36 offset1:52
	v_mul_f32_e32 v14, v13, v13
	v_fmac_f32_e32 v14, v12, v12
	v_fma_f32 v24, v73, v23, -v16
	v_fma_f32 v25, v89, v23, -v17
	ds_read2st64_b32 v[16:17], v1 offset0:37 offset1:53
	v_mul_f32_e32 v26, v25, v25
	v_fmac_f32_e32 v26, v24, v24
	s_waitcnt lgkmcnt(0)
	v_fma_f32 v15, v104, v11, -v4
	v_fmac_f32_e32 v14, v15, v15
	v_fma_f32 v11, v120, v11, -v5
	v_fmac_f32_e32 v14, v11, v11
	s_nop 1
	v_add_f32_dpp v4, v14, v14 quad_perm:[1,0,3,2] row_mask:0xf bank_mask:0xf
	s_nop 1
	v_add_f32_dpp v4, v4, v4 quad_perm:[2,3,0,1] row_mask:0xf bank_mask:0xf
	s_nop 1
	v_add_f32_dpp v4, v4, v4 row_half_mirror row_mask:0xf bank_mask:0xf
	s_nop 1
	v_add_f32_dpp v4, v4, v4 row_mirror row_mask:0xf bank_mask:0xf
	ds_swizzle_b32 v5, v4 offset:swizzle(SWAP,16)
	v_fma_f32 v27, v105, v23, -v16
	v_fmac_f32_e32 v26, v27, v27
	v_fma_f32 v23, v121, v23, -v17
	v_fmac_f32_e32 v26, v23, v23
	s_nop 1
	v_add_f32_dpp v16, v26, v26 quad_perm:[1,0,3,2] row_mask:0xf bank_mask:0xf
	s_nop 1
	v_add_f32_dpp v16, v16, v16 quad_perm:[2,3,0,1] row_mask:0xf bank_mask:0xf
	s_nop 1
	v_add_f32_dpp v16, v16, v16 row_half_mirror row_mask:0xf bank_mask:0xf
	s_nop 1
	v_add_f32_dpp v16, v16, v16 row_mirror row_mask:0xf bank_mask:0xf
	ds_swizzle_b32 v17, v16 offset:swizzle(SWAP,16)
	s_waitcnt lgkmcnt(0)
	v_add_f32_e32 v4, v4, v5
	v_fmamk_f32 v4, v4, 0x3c000000, v254
	v_rsq_f32_e32 v14, v4
	s_nop 0
	v_mul_f32_e32 v5, v12, v14
	v_mul_f32_e32 v12, v13, v14
	v_mul_f32_e32 v5, v7, v5
	v_mul_f32_e32 v12, v9, v12
	v_add_u32_e32 v4, 0x8000, v2
	v_cvt_pk_bf16_f32 v12, v5, v12
	v_mov_b32_e32 v5, v3
	v_lshl_add_u64 v[4:5], v[4:5], 1, s[6:7]
	global_store_short v[4:5], v12, off
	v_add_u32_e32 v4, 0x8020, v2
	v_mov_b32_e32 v5, v3
	v_lshl_add_u64 v[4:5], v[4:5], 1, s[6:7]
	global_store_short_d16_hi v[4:5], v12, off
	v_mul_f32_e32 v4, v15, v14
	v_mul_f32_e32 v5, v11, v14
	v_mul_f32_e32 v4, v6, v4
	v_mul_f32_e32 v5, v8, v5
	v_cvt_pk_bf16_f32 v11, v4, v5
	v_add_u32_e32 v4, 0x8040, v2
	v_mov_b32_e32 v5, v3
	v_lshl_add_u64 v[4:5], v[4:5], 1, s[6:7]
	global_store_short v[4:5], v11, off
	v_add_u32_e32 v4, 0x8060, v2
	v_mov_b32_e32 v5, v3
	v_lshl_add_u64 v[4:5], v[4:5], 1, s[6:7]
	global_store_short_d16_hi v[4:5], v11, off
	v_add_f32_e32 v16, v16, v17
	v_fmamk_f32 v16, v16, 0x3c000000, v254
	v_rsq_f32_e32 v26, v16
	s_nop 0
	v_mul_f32_e32 v17, v24, v26
	v_mul_f32_e32 v24, v25, v26
	v_mul_f32_e32 v17, v7, v17
	v_mul_f32_e32 v24, v9, v24
	v_add_u32_e32 v16, 0x9000, v2
	v_cvt_pk_bf16_f32 v24, v17, v24
	v_mov_b32_e32 v17, v3
	v_lshl_add_u64 v[16:17], v[16:17], 1, s[6:7]
	global_store_short v[16:17], v24, off
	v_add_u32_e32 v16, 0x9020, v2
	v_mov_b32_e32 v17, v3
	v_lshl_add_u64 v[16:17], v[16:17], 1, s[6:7]
	global_store_short_d16_hi v[16:17], v24, off
	v_mul_f32_e32 v16, v27, v26
	v_mul_f32_e32 v17, v23, v26
	v_mul_f32_e32 v16, v6, v16
	v_mul_f32_e32 v17, v8, v17
	v_cvt_pk_bf16_f32 v23, v16, v17
	v_add_u32_e32 v16, 0x9040, v2
	v_mov_b32_e32 v17, v3
	v_lshl_add_u64 v[16:17], v[16:17], 1, s[6:7]
	global_store_short v[16:17], v23, off
	v_add_u32_e32 v16, 0x9060, v2
	v_mov_b32_e32 v17, v3
	v_lshl_add_u64 v[16:17], v[16:17], 1, s[6:7]
	global_store_short_d16_hi v[16:17], v23, off
	ds_read_b32 v11, v10 offset:40
	ds_read2st64_b32 v[4:5], v1 offset0:6 offset1:22
	ds_read_b32 v23, v10 offset:44
	ds_read2st64_b32 v[16:17], v1 offset0:7 offset1:23
	s_waitcnt lgkmcnt(0)
	v_fma_f32 v12, v74, v11, -v4
	v_fma_f32 v13, v90, v11, -v5
	ds_read2st64_b32 v[4:5], v1 offset0:38 offset1:54
	v_mul_f32_e32 v14, v13, v13
	v_fmac_f32_e32 v14, v12, v12
	v_fma_f32 v24, v75, v23, -v16
	v_fma_f32 v25, v91, v23, -v17
	ds_read2st64_b32 v[16:17], v1 offset0:39 offset1:55
	v_mul_f32_e32 v26, v25, v25
	v_fmac_f32_e32 v26, v24, v24
	s_waitcnt lgkmcnt(0)
	v_fma_f32 v15, v106, v11, -v4
	v_fmac_f32_e32 v14, v15, v15
	v_fma_f32 v11, v122, v11, -v5
	v_fmac_f32_e32 v14, v11, v11
	s_nop 1
	v_add_f32_dpp v4, v14, v14 quad_perm:[1,0,3,2] row_mask:0xf bank_mask:0xf
	s_nop 1
	v_add_f32_dpp v4, v4, v4 quad_perm:[2,3,0,1] row_mask:0xf bank_mask:0xf
	s_nop 1
	v_add_f32_dpp v4, v4, v4 row_half_mirror row_mask:0xf bank_mask:0xf
	s_nop 1
	v_add_f32_dpp v4, v4, v4 row_mirror row_mask:0xf bank_mask:0xf
	ds_swizzle_b32 v5, v4 offset:swizzle(SWAP,16)
	v_fma_f32 v27, v107, v23, -v16
	v_fmac_f32_e32 v26, v27, v27
	v_fma_f32 v23, v123, v23, -v17
	v_fmac_f32_e32 v26, v23, v23
	s_nop 1
	v_add_f32_dpp v16, v26, v26 quad_perm:[1,0,3,2] row_mask:0xf bank_mask:0xf
	s_nop 1
	v_add_f32_dpp v16, v16, v16 quad_perm:[2,3,0,1] row_mask:0xf bank_mask:0xf
	s_nop 1
	v_add_f32_dpp v16, v16, v16 row_half_mirror row_mask:0xf bank_mask:0xf
	s_nop 1
	v_add_f32_dpp v16, v16, v16 row_mirror row_mask:0xf bank_mask:0xf
	ds_swizzle_b32 v17, v16 offset:swizzle(SWAP,16)
	s_waitcnt lgkmcnt(0)
	v_add_f32_e32 v4, v4, v5
	v_fmamk_f32 v4, v4, 0x3c000000, v254
	v_rsq_f32_e32 v14, v4
	s_nop 0
	v_mul_f32_e32 v5, v12, v14
	v_mul_f32_e32 v12, v13, v14
	v_mul_f32_e32 v5, v7, v5
	v_mul_f32_e32 v12, v9, v12
	v_add_u32_e32 v4, 0xa000, v2
	v_cvt_pk_bf16_f32 v12, v5, v12
	v_mov_b32_e32 v5, v3
	v_lshl_add_u64 v[4:5], v[4:5], 1, s[6:7]
	global_store_short v[4:5], v12, off
	v_add_u32_e32 v4, 0xa020, v2
	v_mov_b32_e32 v5, v3
	v_lshl_add_u64 v[4:5], v[4:5], 1, s[6:7]
	global_store_short_d16_hi v[4:5], v12, off
	v_mul_f32_e32 v4, v15, v14
	v_mul_f32_e32 v5, v11, v14
	v_mul_f32_e32 v4, v6, v4
	v_mul_f32_e32 v5, v8, v5
	v_cvt_pk_bf16_f32 v11, v4, v5
	v_add_u32_e32 v4, 0xa040, v2
	v_mov_b32_e32 v5, v3
	v_lshl_add_u64 v[4:5], v[4:5], 1, s[6:7]
	global_store_short v[4:5], v11, off
	v_add_u32_e32 v4, 0xa060, v2
	v_mov_b32_e32 v5, v3
	v_lshl_add_u64 v[4:5], v[4:5], 1, s[6:7]
	global_store_short_d16_hi v[4:5], v11, off
	v_add_f32_e32 v16, v16, v17
	v_fmamk_f32 v16, v16, 0x3c000000, v254
	v_rsq_f32_e32 v26, v16
	s_nop 0
	v_mul_f32_e32 v17, v24, v26
	v_mul_f32_e32 v24, v25, v26
	v_mul_f32_e32 v17, v7, v17
	v_mul_f32_e32 v24, v9, v24
	v_add_u32_e32 v16, 0xb000, v2
	v_cvt_pk_bf16_f32 v24, v17, v24
	v_mov_b32_e32 v17, v3
	v_lshl_add_u64 v[16:17], v[16:17], 1, s[6:7]
	global_store_short v[16:17], v24, off
	v_add_u32_e32 v16, 0xb020, v2
	v_mov_b32_e32 v17, v3
	v_lshl_add_u64 v[16:17], v[16:17], 1, s[6:7]
	global_store_short_d16_hi v[16:17], v24, off
	v_mul_f32_e32 v16, v27, v26
	v_mul_f32_e32 v17, v23, v26
	v_mul_f32_e32 v16, v6, v16
	v_mul_f32_e32 v17, v8, v17
	v_cvt_pk_bf16_f32 v23, v16, v17
	v_add_u32_e32 v16, 0xb040, v2
	v_mov_b32_e32 v17, v3
	v_lshl_add_u64 v[16:17], v[16:17], 1, s[6:7]
	global_store_short v[16:17], v23, off
	v_add_u32_e32 v16, 0xb060, v2
	v_mov_b32_e32 v17, v3
	v_lshl_add_u64 v[16:17], v[16:17], 1, s[6:7]
	global_store_short_d16_hi v[16:17], v23, off
	ds_read_b32 v11, v10 offset:64
	ds_read2st64_b32 v[4:5], v1 offset0:8 offset1:24
	ds_read_b32 v23, v10 offset:68
	ds_read2st64_b32 v[16:17], v1 offset0:9 offset1:25
	s_waitcnt lgkmcnt(0)
	v_fma_f32 v12, v76, v11, -v4
	v_fma_f32 v13, v92, v11, -v5
	ds_read2st64_b32 v[4:5], v1 offset0:40 offset1:56
	v_mul_f32_e32 v14, v13, v13
	v_fmac_f32_e32 v14, v12, v12
	v_fma_f32 v24, v77, v23, -v16
	v_fma_f32 v25, v93, v23, -v17
	ds_read2st64_b32 v[16:17], v1 offset0:41 offset1:57
	v_mul_f32_e32 v26, v25, v25
	v_fmac_f32_e32 v26, v24, v24
	s_waitcnt lgkmcnt(0)
	v_fma_f32 v15, v108, v11, -v4
	v_fmac_f32_e32 v14, v15, v15
	v_fma_f32 v11, v124, v11, -v5
	v_fmac_f32_e32 v14, v11, v11
	s_nop 1
	v_add_f32_dpp v4, v14, v14 quad_perm:[1,0,3,2] row_mask:0xf bank_mask:0xf
	s_nop 1
	v_add_f32_dpp v4, v4, v4 quad_perm:[2,3,0,1] row_mask:0xf bank_mask:0xf
	s_nop 1
	v_add_f32_dpp v4, v4, v4 row_half_mirror row_mask:0xf bank_mask:0xf
	s_nop 1
	v_add_f32_dpp v4, v4, v4 row_mirror row_mask:0xf bank_mask:0xf
	ds_swizzle_b32 v5, v4 offset:swizzle(SWAP,16)
	v_fma_f32 v27, v109, v23, -v16
	v_fmac_f32_e32 v26, v27, v27
	v_fma_f32 v23, v125, v23, -v17
	v_fmac_f32_e32 v26, v23, v23
	s_nop 1
	v_add_f32_dpp v16, v26, v26 quad_perm:[1,0,3,2] row_mask:0xf bank_mask:0xf
	s_nop 1
	v_add_f32_dpp v16, v16, v16 quad_perm:[2,3,0,1] row_mask:0xf bank_mask:0xf
	s_nop 1
	v_add_f32_dpp v16, v16, v16 row_half_mirror row_mask:0xf bank_mask:0xf
	s_nop 1
	v_add_f32_dpp v16, v16, v16 row_mirror row_mask:0xf bank_mask:0xf
	ds_swizzle_b32 v17, v16 offset:swizzle(SWAP,16)
	s_waitcnt lgkmcnt(0)
	v_add_f32_e32 v4, v4, v5
	v_fmamk_f32 v4, v4, 0x3c000000, v254
	v_rsq_f32_e32 v14, v4
	s_nop 0
	v_mul_f32_e32 v5, v12, v14
	v_mul_f32_e32 v12, v13, v14
	v_mul_f32_e32 v5, v7, v5
	v_mul_f32_e32 v12, v9, v12
	v_add_u32_e32 v4, 0x10000, v2
	v_cvt_pk_bf16_f32 v12, v5, v12
	v_mov_b32_e32 v5, v3
	v_lshl_add_u64 v[4:5], v[4:5], 1, s[6:7]
	global_store_short v[4:5], v12, off
	v_add_u32_e32 v4, 0x10020, v2
	v_mov_b32_e32 v5, v3
	v_lshl_add_u64 v[4:5], v[4:5], 1, s[6:7]
	global_store_short_d16_hi v[4:5], v12, off
	v_mul_f32_e32 v4, v15, v14
	v_mul_f32_e32 v5, v11, v14
	v_mul_f32_e32 v4, v6, v4
	v_mul_f32_e32 v5, v8, v5
	v_cvt_pk_bf16_f32 v11, v4, v5
	v_add_u32_e32 v4, 0x10040, v2
	v_mov_b32_e32 v5, v3
	v_lshl_add_u64 v[4:5], v[4:5], 1, s[6:7]
	global_store_short v[4:5], v11, off
	v_add_u32_e32 v4, 0x10060, v2
	v_mov_b32_e32 v5, v3
	v_lshl_add_u64 v[4:5], v[4:5], 1, s[6:7]
	global_store_short_d16_hi v[4:5], v11, off
	v_add_f32_e32 v16, v16, v17
	v_fmamk_f32 v16, v16, 0x3c000000, v254
	v_rsq_f32_e32 v26, v16
	s_nop 0
	v_mul_f32_e32 v17, v24, v26
	v_mul_f32_e32 v24, v25, v26
	v_mul_f32_e32 v17, v7, v17
	v_mul_f32_e32 v24, v9, v24
	v_add_u32_e32 v16, 0x11000, v2
	v_cvt_pk_bf16_f32 v24, v17, v24
	v_mov_b32_e32 v17, v3
	v_lshl_add_u64 v[16:17], v[16:17], 1, s[6:7]
	global_store_short v[16:17], v24, off
	v_add_u32_e32 v16, 0x11020, v2
	v_mov_b32_e32 v17, v3
	v_lshl_add_u64 v[16:17], v[16:17], 1, s[6:7]
	global_store_short_d16_hi v[16:17], v24, off
	v_mul_f32_e32 v16, v27, v26
	v_mul_f32_e32 v17, v23, v26
	v_mul_f32_e32 v16, v6, v16
	v_mul_f32_e32 v17, v8, v17
	v_cvt_pk_bf16_f32 v23, v16, v17
	v_add_u32_e32 v16, 0x11040, v2
	v_mov_b32_e32 v17, v3
	v_lshl_add_u64 v[16:17], v[16:17], 1, s[6:7]
	global_store_short v[16:17], v23, off
	v_add_u32_e32 v16, 0x11060, v2
	v_mov_b32_e32 v17, v3
	v_lshl_add_u64 v[16:17], v[16:17], 1, s[6:7]
	global_store_short_d16_hi v[16:17], v23, off
	ds_read_b32 v11, v10 offset:72
	ds_read2st64_b32 v[4:5], v1 offset0:10 offset1:26
	ds_read_b32 v23, v10 offset:76
	ds_read2st64_b32 v[16:17], v1 offset0:11 offset1:27
	s_waitcnt lgkmcnt(0)
	v_fma_f32 v12, v78, v11, -v4
	v_fma_f32 v13, v94, v11, -v5
	ds_read2st64_b32 v[4:5], v1 offset0:42 offset1:58
	v_mul_f32_e32 v14, v13, v13
	v_fmac_f32_e32 v14, v12, v12
	v_fma_f32 v24, v79, v23, -v16
	v_fma_f32 v25, v95, v23, -v17
	ds_read2st64_b32 v[16:17], v1 offset0:43 offset1:59
	v_mul_f32_e32 v26, v25, v25
	v_fmac_f32_e32 v26, v24, v24
	s_waitcnt lgkmcnt(0)
	v_fma_f32 v15, v110, v11, -v4
	v_fmac_f32_e32 v14, v15, v15
	v_fma_f32 v11, v126, v11, -v5
	v_fmac_f32_e32 v14, v11, v11
	s_nop 1
	v_add_f32_dpp v4, v14, v14 quad_perm:[1,0,3,2] row_mask:0xf bank_mask:0xf
	s_nop 1
	v_add_f32_dpp v4, v4, v4 quad_perm:[2,3,0,1] row_mask:0xf bank_mask:0xf
	s_nop 1
	v_add_f32_dpp v4, v4, v4 row_half_mirror row_mask:0xf bank_mask:0xf
	s_nop 1
	v_add_f32_dpp v4, v4, v4 row_mirror row_mask:0xf bank_mask:0xf
	ds_swizzle_b32 v5, v4 offset:swizzle(SWAP,16)
	v_fma_f32 v27, v111, v23, -v16
	v_fmac_f32_e32 v26, v27, v27
	v_fma_f32 v23, v127, v23, -v17
	v_fmac_f32_e32 v26, v23, v23
	s_nop 1
	v_add_f32_dpp v16, v26, v26 quad_perm:[1,0,3,2] row_mask:0xf bank_mask:0xf
	s_nop 1
	v_add_f32_dpp v16, v16, v16 quad_perm:[2,3,0,1] row_mask:0xf bank_mask:0xf
	s_nop 1
	v_add_f32_dpp v16, v16, v16 row_half_mirror row_mask:0xf bank_mask:0xf
	s_nop 1
	v_add_f32_dpp v16, v16, v16 row_mirror row_mask:0xf bank_mask:0xf
	ds_swizzle_b32 v17, v16 offset:swizzle(SWAP,16)
	s_waitcnt lgkmcnt(0)
	v_add_f32_e32 v4, v4, v5
	v_fmamk_f32 v4, v4, 0x3c000000, v254
	v_rsq_f32_e32 v14, v4
	s_nop 0
	v_mul_f32_e32 v5, v12, v14
	v_mul_f32_e32 v12, v13, v14
	v_mul_f32_e32 v5, v7, v5
	v_mul_f32_e32 v12, v9, v12
	v_add_u32_e32 v4, 0x12000, v2
	v_cvt_pk_bf16_f32 v12, v5, v12
	v_mov_b32_e32 v5, v3
	v_lshl_add_u64 v[4:5], v[4:5], 1, s[6:7]
	global_store_short v[4:5], v12, off
	v_add_u32_e32 v4, 0x12020, v2
	v_mov_b32_e32 v5, v3
	v_lshl_add_u64 v[4:5], v[4:5], 1, s[6:7]
	global_store_short_d16_hi v[4:5], v12, off
	v_mul_f32_e32 v4, v15, v14
	v_mul_f32_e32 v5, v11, v14
	v_mul_f32_e32 v4, v6, v4
	v_mul_f32_e32 v5, v8, v5
	v_cvt_pk_bf16_f32 v11, v4, v5
	v_add_u32_e32 v4, 0x12040, v2
	v_mov_b32_e32 v5, v3
	v_lshl_add_u64 v[4:5], v[4:5], 1, s[6:7]
	global_store_short v[4:5], v11, off
	v_add_u32_e32 v4, 0x12060, v2
	v_mov_b32_e32 v5, v3
	v_lshl_add_u64 v[4:5], v[4:5], 1, s[6:7]
	global_store_short_d16_hi v[4:5], v11, off
	v_add_f32_e32 v16, v16, v17
	v_fmamk_f32 v16, v16, 0x3c000000, v254
	v_rsq_f32_e32 v26, v16
	s_nop 0
	v_mul_f32_e32 v17, v24, v26
	v_mul_f32_e32 v24, v25, v26
	v_mul_f32_e32 v17, v7, v17
	v_mul_f32_e32 v24, v9, v24
	v_add_u32_e32 v16, 0x13000, v2
	v_cvt_pk_bf16_f32 v24, v17, v24
	v_mov_b32_e32 v17, v3
	v_lshl_add_u64 v[16:17], v[16:17], 1, s[6:7]
	global_store_short v[16:17], v24, off
	v_add_u32_e32 v16, 0x13020, v2
	v_mov_b32_e32 v17, v3
	v_lshl_add_u64 v[16:17], v[16:17], 1, s[6:7]
	global_store_short_d16_hi v[16:17], v24, off
	v_mul_f32_e32 v16, v27, v26
	v_mul_f32_e32 v17, v23, v26
	v_mul_f32_e32 v16, v6, v16
	v_mul_f32_e32 v17, v8, v17
	v_cvt_pk_bf16_f32 v23, v16, v17
	v_add_u32_e32 v16, 0x13040, v2
	v_mov_b32_e32 v17, v3
	v_lshl_add_u64 v[16:17], v[16:17], 1, s[6:7]
	global_store_short v[16:17], v23, off
	v_add_u32_e32 v16, 0x13060, v2
	v_mov_b32_e32 v17, v3
	v_lshl_add_u64 v[16:17], v[16:17], 1, s[6:7]
	global_store_short_d16_hi v[16:17], v23, off
	ds_read_b32 v11, v10 offset:96
	ds_read2st64_b32 v[4:5], v1 offset0:12 offset1:28
	ds_read_b32 v23, v10 offset:100
	ds_read2st64_b32 v[16:17], v1 offset0:13 offset1:29
	s_waitcnt lgkmcnt(0)
	v_fma_f32 v12, v80, v11, -v4
	v_fma_f32 v13, v96, v11, -v5
	ds_read2st64_b32 v[4:5], v1 offset0:44 offset1:60
	v_mul_f32_e32 v14, v13, v13
	v_fmac_f32_e32 v14, v12, v12
	v_fma_f32 v24, v81, v23, -v16
	v_fma_f32 v25, v97, v23, -v17
	ds_read2st64_b32 v[16:17], v1 offset0:45 offset1:61
	v_mul_f32_e32 v26, v25, v25
	v_fmac_f32_e32 v26, v24, v24
	s_waitcnt lgkmcnt(0)
	v_fma_f32 v15, v112, v11, -v4
	v_fmac_f32_e32 v14, v15, v15
	v_fma_f32 v11, v128, v11, -v5
	v_fmac_f32_e32 v14, v11, v11
	s_nop 1
	v_add_f32_dpp v4, v14, v14 quad_perm:[1,0,3,2] row_mask:0xf bank_mask:0xf
	s_nop 1
	v_add_f32_dpp v4, v4, v4 quad_perm:[2,3,0,1] row_mask:0xf bank_mask:0xf
	s_nop 1
	v_add_f32_dpp v4, v4, v4 row_half_mirror row_mask:0xf bank_mask:0xf
	s_nop 1
	v_add_f32_dpp v4, v4, v4 row_mirror row_mask:0xf bank_mask:0xf
	ds_swizzle_b32 v5, v4 offset:swizzle(SWAP,16)
	v_fma_f32 v27, v113, v23, -v16
	v_fmac_f32_e32 v26, v27, v27
	v_fma_f32 v23, v129, v23, -v17
	v_fmac_f32_e32 v26, v23, v23
	s_nop 1
	v_add_f32_dpp v16, v26, v26 quad_perm:[1,0,3,2] row_mask:0xf bank_mask:0xf
	s_nop 1
	v_add_f32_dpp v16, v16, v16 quad_perm:[2,3,0,1] row_mask:0xf bank_mask:0xf
	s_nop 1
	v_add_f32_dpp v16, v16, v16 row_half_mirror row_mask:0xf bank_mask:0xf
	s_nop 1
	v_add_f32_dpp v16, v16, v16 row_mirror row_mask:0xf bank_mask:0xf
	ds_swizzle_b32 v17, v16 offset:swizzle(SWAP,16)
	s_waitcnt lgkmcnt(0)
	v_add_f32_e32 v4, v4, v5
	v_fmamk_f32 v4, v4, 0x3c000000, v254
	v_rsq_f32_e32 v14, v4
	s_nop 0
	v_mul_f32_e32 v5, v12, v14
	v_mul_f32_e32 v12, v13, v14
	v_mul_f32_e32 v5, v7, v5
	v_mul_f32_e32 v12, v9, v12
	v_add_u32_e32 v4, 0x18000, v2
	v_cvt_pk_bf16_f32 v12, v5, v12
	v_mov_b32_e32 v5, v3
	v_lshl_add_u64 v[4:5], v[4:5], 1, s[6:7]
	global_store_short v[4:5], v12, off
	v_add_u32_e32 v4, 0x18020, v2
	v_mov_b32_e32 v5, v3
	v_lshl_add_u64 v[4:5], v[4:5], 1, s[6:7]
	global_store_short_d16_hi v[4:5], v12, off
	v_mul_f32_e32 v4, v15, v14
	v_mul_f32_e32 v5, v11, v14
	v_mul_f32_e32 v4, v6, v4
	v_mul_f32_e32 v5, v8, v5
	v_cvt_pk_bf16_f32 v11, v4, v5
	v_add_u32_e32 v4, 0x18040, v2
	v_mov_b32_e32 v5, v3
	v_lshl_add_u64 v[4:5], v[4:5], 1, s[6:7]
	global_store_short v[4:5], v11, off
	v_add_u32_e32 v4, 0x18060, v2
	v_mov_b32_e32 v5, v3
	v_lshl_add_u64 v[4:5], v[4:5], 1, s[6:7]
	global_store_short_d16_hi v[4:5], v11, off
	v_add_f32_e32 v16, v16, v17
	v_fmamk_f32 v16, v16, 0x3c000000, v254
	v_rsq_f32_e32 v26, v16
	s_nop 0
	v_mul_f32_e32 v17, v24, v26
	v_mul_f32_e32 v24, v25, v26
	v_mul_f32_e32 v17, v7, v17
	v_mul_f32_e32 v24, v9, v24
	v_add_u32_e32 v16, 0x19000, v2
	v_cvt_pk_bf16_f32 v24, v17, v24
	v_mov_b32_e32 v17, v3
	v_lshl_add_u64 v[16:17], v[16:17], 1, s[6:7]
	global_store_short v[16:17], v24, off
	v_add_u32_e32 v16, 0x19020, v2
	v_mov_b32_e32 v17, v3
	v_lshl_add_u64 v[16:17], v[16:17], 1, s[6:7]
	global_store_short_d16_hi v[16:17], v24, off
	v_mul_f32_e32 v16, v27, v26
	v_mul_f32_e32 v17, v23, v26
	v_mul_f32_e32 v16, v6, v16
	v_mul_f32_e32 v17, v8, v17
	v_cvt_pk_bf16_f32 v23, v16, v17
	v_add_u32_e32 v16, 0x19040, v2
	v_mov_b32_e32 v17, v3
	v_lshl_add_u64 v[16:17], v[16:17], 1, s[6:7]
	global_store_short v[16:17], v23, off
	v_add_u32_e32 v16, 0x19060, v2
	v_mov_b32_e32 v17, v3
	v_lshl_add_u64 v[16:17], v[16:17], 1, s[6:7]
	global_store_short_d16_hi v[16:17], v23, off
	ds_read_b32 v11, v10 offset:104
	ds_read2st64_b32 v[4:5], v1 offset0:14 offset1:30
	s_waitcnt lgkmcnt(0)
	v_fma_f32 v12, v82, v11, -v4
	v_fma_f32 v13, v98, v11, -v5
	ds_read2st64_b32 v[4:5], v1 offset0:46 offset1:62
	v_mul_f32_e32 v14, v13, v13
	v_fmac_f32_e32 v14, v12, v12
	s_waitcnt lgkmcnt(0)
	v_fma_f32 v15, v114, v11, -v4
	v_fmac_f32_e32 v14, v15, v15
	v_fma_f32 v11, v130, v11, -v5
	v_fmac_f32_e32 v14, v11, v11
	s_nop 1
	v_add_f32_dpp v4, v14, v14 quad_perm:[1,0,3,2] row_mask:0xf bank_mask:0xf
	s_nop 1
	v_add_f32_dpp v4, v4, v4 quad_perm:[2,3,0,1] row_mask:0xf bank_mask:0xf
	s_nop 1
	v_add_f32_dpp v4, v4, v4 row_half_mirror row_mask:0xf bank_mask:0xf
	s_nop 1
	v_add_f32_dpp v4, v4, v4 row_mirror row_mask:0xf bank_mask:0xf
	ds_swizzle_b32 v5, v4 offset:swizzle(SWAP,16)
	s_waitcnt lgkmcnt(0)
	v_add_f32_e32 v4, v4, v5
	v_fmamk_f32 v4, v4, 0x3c000000, v254
	v_rsq_f32_e32 v14, v4
	s_nop 0
	v_mul_f32_e32 v5, v12, v14
	v_mul_f32_e32 v12, v13, v14
	v_mul_f32_e32 v5, v7, v5
	v_mul_f32_e32 v12, v9, v12
	v_add_u32_e32 v4, 0x1a000, v2
	v_cvt_pk_bf16_f32 v12, v5, v12
	v_mov_b32_e32 v5, v3
	v_lshl_add_u64 v[4:5], v[4:5], 1, s[6:7]
	global_store_short v[4:5], v12, off
	v_add_u32_e32 v4, 0x1a020, v2
	v_mov_b32_e32 v5, v3
	v_lshl_add_u64 v[4:5], v[4:5], 1, s[6:7]
	global_store_short_d16_hi v[4:5], v12, off
	v_mul_f32_e32 v4, v15, v14
	v_mul_f32_e32 v5, v11, v14
	v_mul_f32_e32 v4, v6, v4
	v_mul_f32_e32 v5, v8, v5
	v_cvt_pk_bf16_f32 v11, v4, v5
	v_add_u32_e32 v4, 0x1a040, v2
	v_mov_b32_e32 v5, v3
	v_lshl_add_u64 v[4:5], v[4:5], 1, s[6:7]
	global_store_short v[4:5], v11, off
	v_add_u32_e32 v4, 0x1a060, v2
	v_mov_b32_e32 v5, v3
	v_lshl_add_u64 v[4:5], v[4:5], 1, s[6:7]
	global_store_short_d16_hi v[4:5], v11, off
	ds_read_b32 v10, v10 offset:108
	ds_read2st64_b32 v[4:5], v1 offset0:15 offset1:31
	s_waitcnt lgkmcnt(0)
	v_fma_f32 v11, v83, v10, -v4
	v_fma_f32 v12, v99, v10, -v5
	ds_read2st64_b32 v[4:5], v1 offset0:47 offset1:63
	v_mul_f32_e32 v13, v12, v12
	v_fmac_f32_e32 v13, v11, v11
	s_waitcnt lgkmcnt(0)
	v_fma_f32 v1, v115, v10, -v4
	v_fmac_f32_e32 v13, v1, v1
	v_fma_f32 v10, v131, v10, -v5
	v_fmac_f32_e32 v13, v10, v10
	s_nop 1
	v_add_f32_dpp v4, v13, v13 quad_perm:[1,0,3,2] row_mask:0xf bank_mask:0xf
	s_nop 1
	v_add_f32_dpp v4, v4, v4 quad_perm:[2,3,0,1] row_mask:0xf bank_mask:0xf
	s_nop 1
	v_add_f32_dpp v4, v4, v4 row_half_mirror row_mask:0xf bank_mask:0xf
	s_nop 1
	v_add_f32_dpp v4, v4, v4 row_mirror row_mask:0xf bank_mask:0xf
	ds_swizzle_b32 v5, v4 offset:swizzle(SWAP,16)
	s_waitcnt lgkmcnt(0)
	v_add_f32_e32 v4, v4, v5
	v_fmamk_f32 v4, v4, 0x3c000000, v254
	v_rsq_f32_e32 v13, v4
	s_nop 0
	v_mul_f32_e32 v5, v11, v13
	v_mul_f32_e32 v5, v7, v5
	v_mul_f32_e32 v7, v12, v13
	v_mul_f32_e32 v7, v9, v7
	v_add_u32_e32 v4, 0x1b000, v2
	v_cvt_pk_bf16_f32 v7, v5, v7
	v_mov_b32_e32 v5, v3
	v_lshl_add_u64 v[4:5], v[4:5], 1, s[6:7]
	global_store_short v[4:5], v7, off
	v_add_u32_e32 v4, 0x1b020, v2
	v_mov_b32_e32 v5, v3
	v_lshl_add_u64 v[4:5], v[4:5], 1, s[6:7]
	global_store_short_d16_hi v[4:5], v7, off
	v_mul_f32_e32 v1, v1, v13
	v_mul_f32_e32 v4, v10, v13
	v_mul_f32_e32 v1, v6, v1
	v_mul_f32_e32 v4, v8, v4
	v_cvt_pk_bf16_f32 v1, v1, v4
	v_add_u32_e32 v4, 0x1b040, v2
	v_mov_b32_e32 v5, v3
	v_lshl_add_u64 v[4:5], v[4:5], 1, s[6:7]
	v_add_u32_e32 v2, 0x1b060, v2
	global_store_short v[4:5], v1, off
	v_lshl_add_u64 v[4:5], v[2:3], 1, s[6:7]
	global_store_short_d16_hi v[4:5], v1, off

.LBB0_1303:
	s_or_b64 exec, exec, s[4:5]
	s_waitcnt lgkmcnt(0)
	v_add_u32_e32 v4, s19, v148
	ds_read_b32 v16, v4
	ds_read_b32 v17, v4 offset:4
	ds_read_b32 v18, v4 offset:8
	ds_read_b32 v19, v4 offset:12
	ds_read_b32 v20, v4 offset:32
	ds_read_b32 v21, v4 offset:36
	ds_read_b32 v22, v4 offset:40
	ds_read_b32 v23, v4 offset:44
	ds_read_b32 v24, v4 offset:64
	ds_read_b32 v25, v4 offset:68
	ds_read_b32 v26, v4 offset:72
	ds_read_b32 v27, v4 offset:76
	ds_read_b32 v28, v4 offset:96
	ds_read_b32 v29, v4 offset:100
	ds_read_b32 v30, v4 offset:104
	ds_read_b32 v31, v4 offset:108
	s_waitcnt lgkmcnt(0)
	v_mul_f32_e32 v6, v84, v16
	ds_write_b32 v1, v6
	v_mul_f32_e32 v6, v100, v16
	ds_write_b32 v1, v6 offset:4096
	v_mul_f32_e32 v6, v116, v16
	v_mul_f32_e32 v16, v132, v16
	ds_write_b32 v1, v6 offset:8192
	ds_write_b32 v1, v16 offset:12288
	v_mul_f32_e32 v6, v85, v17
	ds_write_b32 v1, v6 offset:256
	v_mul_f32_e32 v6, v101, v17
	ds_write_b32 v1, v6 offset:4352
	v_mul_f32_e32 v6, v117, v17
	v_mul_f32_e32 v17, v133, v17
	ds_write_b32 v1, v6 offset:8448
	ds_write_b32 v1, v17 offset:12544
	v_mul_f32_e32 v6, v86, v18
	ds_write_b32 v1, v6 offset:512
	v_mul_f32_e32 v6, v102, v18
	ds_write_b32 v1, v6 offset:4608
	v_mul_f32_e32 v6, v118, v18
	v_mul_f32_e32 v18, v134, v18
	ds_write_b32 v1, v6 offset:8704
	ds_write_b32 v1, v18 offset:12800
	v_mul_f32_e32 v6, v87, v19
	ds_write_b32 v1, v6 offset:768
	v_mul_f32_e32 v6, v103, v19
	ds_write_b32 v1, v6 offset:4864
	v_mul_f32_e32 v6, v119, v19
	v_mul_f32_e32 v19, v135, v19
	ds_write_b32 v1, v6 offset:8960
	ds_write_b32 v1, v19 offset:13056
	v_mul_f32_e32 v6, v88, v20
	ds_write_b32 v1, v6 offset:1024
	v_mul_f32_e32 v6, v104, v20
	ds_write_b32 v1, v6 offset:5120
	v_mul_f32_e32 v6, v120, v20
	v_mul_f32_e32 v20, v136, v20
	ds_write_b32 v1, v6 offset:9216
	ds_write_b32 v1, v20 offset:13312
	v_mul_f32_e32 v6, v89, v21
	ds_write_b32 v1, v6 offset:1280
	v_mul_f32_e32 v6, v105, v21
	ds_write_b32 v1, v6 offset:5376
	v_mul_f32_e32 v6, v121, v21
	v_mul_f32_e32 v21, v137, v21
	ds_write_b32 v1, v6 offset:9472
	ds_write_b32 v1, v21 offset:13568
	v_mul_f32_e32 v6, v90, v22
	ds_write_b32 v1, v6 offset:1536
	v_mul_f32_e32 v6, v106, v22
	ds_write_b32 v1, v6 offset:5632
	v_mul_f32_e32 v6, v122, v22
	v_mul_f32_e32 v22, v138, v22
	ds_write_b32 v1, v6 offset:9728
	ds_write_b32 v1, v22 offset:13824
	v_mul_f32_e32 v6, v91, v23
	ds_write_b32 v1, v6 offset:1792
	v_mul_f32_e32 v6, v107, v23
	ds_write_b32 v1, v6 offset:5888
	v_mul_f32_e32 v6, v123, v23
	v_mul_f32_e32 v23, v139, v23
	ds_write_b32 v1, v6 offset:9984
	ds_write_b32 v1, v23 offset:14080
	v_mul_f32_e32 v6, v92, v24
	ds_write_b32 v1, v6 offset:2048
	v_mul_f32_e32 v6, v108, v24
	ds_write_b32 v1, v6 offset:6144
	v_mul_f32_e32 v6, v124, v24
	v_mul_f32_e32 v24, v140, v24
	ds_write_b32 v1, v6 offset:10240
	ds_write_b32 v1, v24 offset:14336
	v_mul_f32_e32 v6, v93, v25
	ds_write_b32 v1, v6 offset:2304
	v_mul_f32_e32 v6, v109, v25
	ds_write_b32 v1, v6 offset:6400
	v_mul_f32_e32 v6, v125, v25
	v_mul_f32_e32 v25, v141, v25
	ds_write_b32 v1, v6 offset:10496
	ds_write_b32 v1, v25 offset:14592
	v_mul_f32_e32 v6, v94, v26
	ds_write_b32 v1, v6 offset:2560
	v_mul_f32_e32 v6, v110, v26
	ds_write_b32 v1, v6 offset:6656
	v_mul_f32_e32 v6, v126, v26
	v_mul_f32_e32 v26, v142, v26
	ds_write_b32 v1, v6 offset:10752
	ds_write_b32 v1, v26 offset:14848
	v_mul_f32_e32 v6, v95, v27
	ds_write_b32 v1, v6 offset:2816
	v_mul_f32_e32 v6, v111, v27
	ds_write_b32 v1, v6 offset:6912
	v_mul_f32_e32 v6, v127, v27
	v_mul_f32_e32 v27, v143, v27
	ds_write_b32 v1, v6 offset:11008
	ds_write_b32 v1, v27 offset:15104
	v_mul_f32_e32 v6, v96, v28
	ds_write_b32 v1, v6 offset:3072
	v_mul_f32_e32 v6, v112, v28
	ds_write_b32 v1, v6 offset:7168
	v_mul_f32_e32 v6, v128, v28
	v_mul_f32_e32 v28, v144, v28
	ds_write_b32 v1, v6 offset:11264
	ds_write_b32 v1, v28 offset:15360
	v_mul_f32_e32 v6, v97, v29
	ds_write_b32 v1, v6 offset:3328
	v_mul_f32_e32 v6, v113, v29
	ds_write_b32 v1, v6 offset:7424
	v_mul_f32_e32 v6, v129, v29
	v_mul_f32_e32 v29, v145, v29
	ds_write_b32 v1, v6 offset:11520
	ds_write_b32 v1, v29 offset:15616
	v_mul_f32_e32 v6, v98, v30
	ds_write_b32 v1, v6 offset:3584
	v_mul_f32_e32 v6, v114, v30
	ds_write_b32 v1, v6 offset:7680
	v_mul_f32_e32 v6, v130, v30
	v_mul_f32_e32 v30, v146, v30
	ds_write_b32 v1, v6 offset:11776
	ds_write_b32 v1, v30 offset:15872
	v_mul_f32_e32 v5, v99, v31
	ds_write_b32 v1, v5 offset:3840
	v_mul_f32_e32 v5, v115, v31
	ds_write_b32 v1, v5 offset:7936
	v_mul_f32_e32 v5, v131, v31
	v_mul_f32_e32 v31, v147, v31
	ds_write_b32 v1, v5 offset:12032
	ds_write_b32 v1, v31 offset:16128
	v_mov_b32_e32 v5, v30
	v_mov_b32_e32 v4, v31

.LBB0_1370:
	s_or_b64 exec, exec, s[4:5]
	s_waitcnt lgkmcnt(0)
	v_add_u32_e32 v4, s29, v148
	ds_read_b32 v20, v4
	ds_read_b32 v21, v4 offset:4
	ds_read_b32 v22, v4 offset:8
	ds_read_b32 v23, v4 offset:12
	ds_read_b32 v24, v4 offset:32
	ds_read_b32 v25, v4 offset:36
	ds_read_b32 v26, v4 offset:40
	ds_read_b32 v27, v4 offset:44
	ds_read_b32 v28, v4 offset:64
	ds_read_b32 v29, v4 offset:68
	ds_read_b32 v34, v4 offset:72
	ds_read_b32 v35, v4 offset:76
	ds_read_b32 v36, v4 offset:96
	ds_read_b32 v37, v4 offset:100
	ds_read_b32 v38, v4 offset:104
	ds_read_b32 v39, v4 offset:108
	s_waitcnt lgkmcnt(0)
	v_mul_f32_e32 v6, v68, v20
	ds_write_b32 v1, v6
	v_mul_f32_e32 v6, v84, v20
	ds_write_b32 v1, v6 offset:4096
	v_mul_f32_e32 v6, v100, v20
	v_mul_f32_e32 v20, v116, v20
	ds_write_b32 v1, v6 offset:8192
	ds_write_b32 v1, v20 offset:12288
	v_mul_f32_e32 v6, v69, v21
	ds_write_b32 v1, v6 offset:256
	v_mul_f32_e32 v6, v85, v21
	ds_write_b32 v1, v6 offset:4352
	v_mul_f32_e32 v6, v101, v21
	v_mul_f32_e32 v21, v117, v21
	ds_write_b32 v1, v6 offset:8448
	ds_write_b32 v1, v21 offset:12544
	v_mul_f32_e32 v6, v70, v22
	ds_write_b32 v1, v6 offset:512
	v_mul_f32_e32 v6, v86, v22
	ds_write_b32 v1, v6 offset:4608
	v_mul_f32_e32 v6, v102, v22
	v_mul_f32_e32 v22, v118, v22
	ds_write_b32 v1, v6 offset:8704
	ds_write_b32 v1, v22 offset:12800
	v_mul_f32_e32 v6, v71, v23
	ds_write_b32 v1, v6 offset:768
	v_mul_f32_e32 v6, v87, v23
	ds_write_b32 v1, v6 offset:4864
	v_mul_f32_e32 v6, v103, v23
	v_mul_f32_e32 v23, v119, v23
	ds_write_b32 v1, v6 offset:8960
	ds_write_b32 v1, v23 offset:13056
	v_mul_f32_e32 v6, v72, v24
	ds_write_b32 v1, v6 offset:1024
	v_mul_f32_e32 v6, v88, v24
	ds_write_b32 v1, v6 offset:5120
	v_mul_f32_e32 v6, v104, v24
	v_mul_f32_e32 v24, v120, v24
	ds_write_b32 v1, v6 offset:9216
	ds_write_b32 v1, v24 offset:13312
	v_mul_f32_e32 v6, v73, v25
	ds_write_b32 v1, v6 offset:1280
	v_mul_f32_e32 v6, v89, v25
	ds_write_b32 v1, v6 offset:5376
	v_mul_f32_e32 v6, v105, v25
	v_mul_f32_e32 v25, v121, v25
	ds_write_b32 v1, v6 offset:9472
	ds_write_b32 v1, v25 offset:13568
	v_mul_f32_e32 v6, v74, v26
	ds_write_b32 v1, v6 offset:1536
	v_mul_f32_e32 v6, v90, v26
	ds_write_b32 v1, v6 offset:5632
	v_mul_f32_e32 v6, v106, v26
	v_mul_f32_e32 v26, v122, v26
	ds_write_b32 v1, v6 offset:9728
	ds_write_b32 v1, v26 offset:13824
	v_mul_f32_e32 v6, v75, v27
	ds_write_b32 v1, v6 offset:1792
	v_mul_f32_e32 v6, v91, v27
	ds_write_b32 v1, v6 offset:5888
	v_mul_f32_e32 v6, v107, v27
	v_mul_f32_e32 v27, v123, v27
	ds_write_b32 v1, v6 offset:9984
	ds_write_b32 v1, v27 offset:14080
	v_mul_f32_e32 v6, v76, v28
	ds_write_b32 v1, v6 offset:2048
	v_mul_f32_e32 v6, v92, v28
	ds_write_b32 v1, v6 offset:6144
	v_mul_f32_e32 v6, v108, v28
	v_mul_f32_e32 v28, v124, v28
	ds_write_b32 v1, v6 offset:10240
	ds_write_b32 v1, v28 offset:14336
	v_mul_f32_e32 v6, v77, v29
	ds_write_b32 v1, v6 offset:2304
	v_mul_f32_e32 v6, v93, v29
	ds_write_b32 v1, v6 offset:6400
	v_mul_f32_e32 v6, v109, v29
	v_mul_f32_e32 v29, v125, v29
	ds_write_b32 v1, v6 offset:10496
	ds_write_b32 v1, v29 offset:14592
	v_mul_f32_e32 v6, v78, v34
	ds_write_b32 v1, v6 offset:2560
	v_mul_f32_e32 v6, v94, v34
	ds_write_b32 v1, v6 offset:6656
	v_mul_f32_e32 v6, v110, v34
	v_mul_f32_e32 v34, v126, v34
	ds_write_b32 v1, v6 offset:10752
	ds_write_b32 v1, v34 offset:14848
	v_mul_f32_e32 v6, v79, v35
	ds_write_b32 v1, v6 offset:2816
	v_mul_f32_e32 v6, v95, v35
	ds_write_b32 v1, v6 offset:6912
	v_mul_f32_e32 v6, v111, v35
	v_mul_f32_e32 v35, v127, v35
	ds_write_b32 v1, v6 offset:11008
	ds_write_b32 v1, v35 offset:15104
	v_mul_f32_e32 v6, v80, v36
	ds_write_b32 v1, v6 offset:3072
	v_mul_f32_e32 v6, v96, v36
	ds_write_b32 v1, v6 offset:7168
	v_mul_f32_e32 v6, v112, v36
	v_mul_f32_e32 v36, v128, v36
	ds_write_b32 v1, v6 offset:11264
	ds_write_b32 v1, v36 offset:15360
	v_mul_f32_e32 v6, v81, v37
	ds_write_b32 v1, v6 offset:3328
	v_mul_f32_e32 v6, v97, v37
	ds_write_b32 v1, v6 offset:7424
	v_mul_f32_e32 v6, v113, v37
	v_mul_f32_e32 v37, v129, v37
	ds_write_b32 v1, v6 offset:11520
	ds_write_b32 v1, v37 offset:15616
	v_mul_f32_e32 v6, v82, v38
	ds_write_b32 v1, v6 offset:3584
	v_mul_f32_e32 v6, v98, v38
	ds_write_b32 v1, v6 offset:7680
	v_mul_f32_e32 v6, v114, v38
	v_mul_f32_e32 v38, v130, v38
	ds_write_b32 v1, v6 offset:11776
	ds_write_b32 v1, v38 offset:15872
	v_mul_f32_e32 v5, v83, v39
	ds_write_b32 v1, v5 offset:3840
	v_mul_f32_e32 v5, v99, v39
	ds_write_b32 v1, v5 offset:7936
	v_mul_f32_e32 v5, v115, v39
	v_mul_f32_e32 v39, v131, v39
	ds_write_b32 v1, v5 offset:12032
	ds_write_b32 v1, v39 offset:16128
	v_mov_b32_e32 v5, v38
	v_mov_b32_e32 v4, v39

.LBB0_1374:
	s_or_b64 exec, exec, s[4:5]
	s_waitcnt lgkmcnt(0)
	v_lshlrev_b32_e32 v4, 2, v158
	global_load_dword v248, v4, s[0:1]
	global_load_dword v249, v4, s[0:1] offset:128
	global_load_dword v250, v4, s[0:1] offset:256
	global_load_dword v251, v4, s[0:1] offset:384
	v_add_u32_e32 v9, s29, v148
	s_lshl_b64 s[4:5], s[24:25], 13
	s_add_u32 s6, s86, s4
	s_addc_u32 s7, s87, s5
	s_waitcnt vmcnt(0)
	v_mul_f32_e32 v6, v164, v248
	v_mul_f32_e32 v8, v164, v249
	v_mul_f32_e32 v2, v164, v250
	v_mul_f32_e32 v7, v164, v251
	v_lshl_or_b32 v4, v159, 14, v158
	ds_read_b32 v5, v9
	ds_read2st64_b32 v[10:11], v1 offset1:16
	s_waitcnt lgkmcnt(0)
	v_fma_f32 v12, v68, v5, -v10
	v_fma_f32 v13, v84, v5, -v11
	ds_read2st64_b32 v[10:11], v1 offset0:32 offset1:48
	v_mul_f32_e32 v14, v13, v13
	v_fmac_f32_e32 v14, v12, v12
	s_waitcnt lgkmcnt(0)
	v_fma_f32 v15, v100, v5, -v10
	v_fmac_f32_e32 v14, v15, v15
	v_fma_f32 v16, v116, v5, -v11
	v_fmac_f32_e32 v14, v16, v16
	s_nop 1
	v_add_f32_dpp v5, v14, v14 quad_perm:[1,0,3,2] row_mask:0xf bank_mask:0xf
	s_nop 1
	v_add_f32_dpp v5, v5, v5 quad_perm:[2,3,0,1] row_mask:0xf bank_mask:0xf
	s_nop 1
	v_add_f32_dpp v5, v5, v5 row_half_mirror row_mask:0xf bank_mask:0xf
	s_nop 1
	v_add_f32_dpp v5, v5, v5 row_mirror row_mask:0xf bank_mask:0xf
	ds_swizzle_b32 v10, v5 offset:swizzle(SWAP,16)
	s_waitcnt lgkmcnt(0)
	v_add_f32_e32 v5, v5, v10
	v_fmamk_f32 v5, v5, 0x3c000000, v254
	v_rsq_f32_e32 v14, v5
	s_nop 0
	v_mul_f32_e32 v5, v12, v14
	v_mul_f32_e32 v5, v6, v5
	v_mul_f32_e32 v10, v13, v14
	v_mul_f32_e32 v10, v8, v10
	v_cvt_pk_bf16_f32 v12, v5, v10
	v_mov_b32_e32 v5, v3
	v_lshl_add_u64 v[10:11], v[4:5], 1, s[6:7]
	global_store_short v[10:11], v12, off offset:768
	v_add_u32_e32 v10, 32, v4
	v_mov_b32_e32 v11, v3
	v_lshl_add_u64 v[10:11], v[10:11], 1, s[6:7]
	global_store_short_d16_hi v[10:11], v12, off offset:768
	v_mul_f32_e32 v5, v15, v14
	v_mul_f32_e32 v10, v16, v14
	v_mul_f32_e32 v5, v2, v5
	v_mul_f32_e32 v10, v7, v10
	v_cvt_pk_bf16_f32 v5, v5, v10
	v_add_u32_e32 v10, 64, v4
	v_mov_b32_e32 v11, v3
	v_lshl_add_u64 v[10:11], v[10:11], 1, s[6:7]
	global_store_short v[10:11], v5, off offset:768
	v_add_u32_e32 v10, 0x60, v4
	v_mov_b32_e32 v11, v3
	v_lshl_add_u64 v[10:11], v[10:11], 1, s[6:7]
	global_store_short_d16_hi v[10:11], v5, off offset:768
	ds_read_b32 v5, v9 offset:4
	ds_read2st64_b32 v[10:11], v1 offset0:1 offset1:17
	s_waitcnt lgkmcnt(0)
	v_fma_f32 v12, v69, v5, -v10
	v_fma_f32 v13, v85, v5, -v11
	ds_read2st64_b32 v[10:11], v1 offset0:33 offset1:49
	v_mul_f32_e32 v14, v13, v13
	v_fmac_f32_e32 v14, v12, v12
	s_waitcnt lgkmcnt(0)
	v_fma_f32 v15, v101, v5, -v10
	v_fmac_f32_e32 v14, v15, v15
	v_fma_f32 v5, v117, v5, -v11
	v_fmac_f32_e32 v14, v5, v5
	s_nop 1
	v_add_f32_dpp v10, v14, v14 quad_perm:[1,0,3,2] row_mask:0xf bank_mask:0xf
	s_nop 1
	v_add_f32_dpp v10, v10, v10 quad_perm:[2,3,0,1] row_mask:0xf bank_mask:0xf
	s_nop 1
	v_add_f32_dpp v10, v10, v10 row_half_mirror row_mask:0xf bank_mask:0xf
	s_nop 1
	v_add_f32_dpp v10, v10, v10 row_mirror row_mask:0xf bank_mask:0xf
	ds_swizzle_b32 v11, v10 offset:swizzle(SWAP,16)
	s_waitcnt lgkmcnt(0)
	v_add_f32_e32 v10, v10, v11
	v_fmamk_f32 v10, v10, 0x3c000000, v254
	v_rsq_f32_e32 v14, v10
	s_nop 0
	v_mul_f32_e32 v11, v12, v14
	v_mul_f32_e32 v12, v13, v14
	v_mul_f32_e32 v11, v6, v11
	v_mul_f32_e32 v12, v8, v12
	v_add_u32_e32 v10, 0x1000, v4
	v_cvt_pk_bf16_f32 v12, v11, v12
	v_mov_b32_e32 v11, v3
	v_lshl_add_u64 v[10:11], v[10:11], 1, s[6:7]
	global_store_short v[10:11], v12, off offset:768
	v_add_u32_e32 v10, 0x1020, v4
	v_mov_b32_e32 v11, v3
	v_lshl_add_u64 v[10:11], v[10:11], 1, s[6:7]
	global_store_short_d16_hi v[10:11], v12, off offset:768
	v_mul_f32_e32 v10, v15, v14
	v_mul_f32_e32 v5, v5, v14
	v_mul_f32_e32 v10, v2, v10
	v_mul_f32_e32 v5, v7, v5
	v_cvt_pk_bf16_f32 v5, v10, v5
	v_add_u32_e32 v10, 0x1040, v4
	v_mov_b32_e32 v11, v3
	v_lshl_add_u64 v[10:11], v[10:11], 1, s[6:7]
	global_store_short v[10:11], v5, off offset:768
	v_add_u32_e32 v10, 0x1060, v4
	v_mov_b32_e32 v11, v3
	v_lshl_add_u64 v[10:11], v[10:11], 1, s[6:7]
	global_store_short_d16_hi v[10:11], v5, off offset:768
	ds_read_b32 v5, v9 offset:8
	ds_read2st64_b32 v[10:11], v1 offset0:2 offset1:18
	ds_read_b32 v35, v9 offset:12
	ds_read2st64_b32 v[40:41], v1 offset0:3 offset1:19
	s_waitcnt lgkmcnt(0)
	v_fma_f32 v12, v70, v5, -v10
	v_fma_f32 v13, v86, v5, -v11
	ds_read2st64_b32 v[10:11], v1 offset0:34 offset1:50
	v_mul_f32_e32 v14, v13, v13
	v_fmac_f32_e32 v14, v12, v12
	v_fma_f32 v42, v71, v35, -v40
	v_fma_f32 v43, v87, v35, -v41
	ds_read2st64_b32 v[40:41], v1 offset0:35 offset1:51
	v_mul_f32_e32 v44, v43, v43
	v_fmac_f32_e32 v44, v42, v42
	s_waitcnt lgkmcnt(0)
	v_fma_f32 v15, v102, v5, -v10
	v_fmac_f32_e32 v14, v15, v15
	v_fma_f32 v5, v118, v5, -v11
	v_fmac_f32_e32 v14, v5, v5
	s_nop 1
	v_add_f32_dpp v10, v14, v14 quad_perm:[1,0,3,2] row_mask:0xf bank_mask:0xf
	s_nop 1
	v_add_f32_dpp v10, v10, v10 quad_perm:[2,3,0,1] row_mask:0xf bank_mask:0xf
	s_nop 1
	v_add_f32_dpp v10, v10, v10 row_half_mirror row_mask:0xf bank_mask:0xf
	s_nop 1
	v_add_f32_dpp v10, v10, v10 row_mirror row_mask:0xf bank_mask:0xf
	ds_swizzle_b32 v11, v10 offset:swizzle(SWAP,16)
	v_fma_f32 v45, v103, v35, -v40
	v_fmac_f32_e32 v44, v45, v45
	v_fma_f32 v35, v119, v35, -v41
	v_fmac_f32_e32 v44, v35, v35
	s_nop 1
	v_add_f32_dpp v40, v44, v44 quad_perm:[1,0,3,2] row_mask:0xf bank_mask:0xf
	s_nop 1
	v_add_f32_dpp v40, v40, v40 quad_perm:[2,3,0,1] row_mask:0xf bank_mask:0xf
	s_nop 1
	v_add_f32_dpp v40, v40, v40 row_half_mirror row_mask:0xf bank_mask:0xf
	s_nop 1
	v_add_f32_dpp v40, v40, v40 row_mirror row_mask:0xf bank_mask:0xf
	ds_swizzle_b32 v41, v40 offset:swizzle(SWAP,16)
	s_waitcnt lgkmcnt(0)
	v_add_f32_e32 v10, v10, v11
	v_fmamk_f32 v10, v10, 0x3c000000, v254
	v_rsq_f32_e32 v14, v10
	s_nop 0
	v_mul_f32_e32 v11, v12, v14
	v_mul_f32_e32 v12, v13, v14
	v_mul_f32_e32 v11, v6, v11
	v_mul_f32_e32 v12, v8, v12
	v_add_u32_e32 v10, 0x2000, v4
	v_cvt_pk_bf16_f32 v12, v11, v12
	v_mov_b32_e32 v11, v3
	v_lshl_add_u64 v[10:11], v[10:11], 1, s[6:7]
	global_store_short v[10:11], v12, off offset:768
	v_add_u32_e32 v10, 0x2020, v4
	v_mov_b32_e32 v11, v3
	v_lshl_add_u64 v[10:11], v[10:11], 1, s[6:7]
	global_store_short_d16_hi v[10:11], v12, off offset:768
	v_mul_f32_e32 v10, v15, v14
	v_mul_f32_e32 v5, v5, v14
	v_mul_f32_e32 v10, v2, v10
	v_mul_f32_e32 v5, v7, v5
	v_cvt_pk_bf16_f32 v5, v10, v5
	v_add_u32_e32 v10, 0x2040, v4
	v_mov_b32_e32 v11, v3
	v_lshl_add_u64 v[10:11], v[10:11], 1, s[6:7]
	global_store_short v[10:11], v5, off offset:768
	v_add_u32_e32 v10, 0x2060, v4
	v_mov_b32_e32 v11, v3
	v_lshl_add_u64 v[10:11], v[10:11], 1, s[6:7]
	global_store_short_d16_hi v[10:11], v5, off offset:768
	v_add_f32_e32 v40, v40, v41
	v_fmamk_f32 v40, v40, 0x3c000000, v254
	v_rsq_f32_e32 v44, v40
	s_nop 0
	v_mul_f32_e32 v41, v42, v44
	v_mul_f32_e32 v42, v43, v44
	v_mul_f32_e32 v41, v6, v41
	v_mul_f32_e32 v42, v8, v42
	v_add_u32_e32 v40, 0x3000, v4
	v_cvt_pk_bf16_f32 v42, v41, v42
	v_mov_b32_e32 v41, v3
	v_lshl_add_u64 v[40:41], v[40:41], 1, s[6:7]
	global_store_short v[40:41], v42, off offset:768
	v_add_u32_e32 v40, 0x3020, v4
	v_mov_b32_e32 v41, v3
	v_lshl_add_u64 v[40:41], v[40:41], 1, s[6:7]
	global_store_short_d16_hi v[40:41], v42, off offset:768
	v_mul_f32_e32 v40, v45, v44
	v_mul_f32_e32 v35, v35, v44
	v_mul_f32_e32 v40, v2, v40
	v_mul_f32_e32 v35, v7, v35
	v_cvt_pk_bf16_f32 v35, v40, v35
	v_add_u32_e32 v40, 0x3040, v4
	v_mov_b32_e32 v41, v3
	v_lshl_add_u64 v[40:41], v[40:41], 1, s[6:7]
	global_store_short v[40:41], v35, off offset:768
	v_add_u32_e32 v40, 0x3060, v4
	v_mov_b32_e32 v41, v3
	v_lshl_add_u64 v[40:41], v[40:41], 1, s[6:7]
	global_store_short_d16_hi v[40:41], v35, off offset:768
	ds_read_b32 v5, v9 offset:32
	ds_read2st64_b32 v[10:11], v1 offset0:4 offset1:20
	ds_read_b32 v35, v9 offset:36
	ds_read2st64_b32 v[40:41], v1 offset0:5 offset1:21
	s_waitcnt lgkmcnt(0)
	v_fma_f32 v12, v72, v5, -v10
	v_fma_f32 v13, v88, v5, -v11
	ds_read2st64_b32 v[10:11], v1 offset0:36 offset1:52
	v_mul_f32_e32 v14, v13, v13
	v_fmac_f32_e32 v14, v12, v12
	v_fma_f32 v42, v73, v35, -v40
	v_fma_f32 v43, v89, v35, -v41
	ds_read2st64_b32 v[40:41], v1 offset0:37 offset1:53
	v_mul_f32_e32 v44, v43, v43
	v_fmac_f32_e32 v44, v42, v42
	s_waitcnt lgkmcnt(0)
	v_fma_f32 v15, v104, v5, -v10
	v_fmac_f32_e32 v14, v15, v15
	v_fma_f32 v5, v120, v5, -v11
	v_fmac_f32_e32 v14, v5, v5
	s_nop 1
	v_add_f32_dpp v10, v14, v14 quad_perm:[1,0,3,2] row_mask:0xf bank_mask:0xf
	s_nop 1
	v_add_f32_dpp v10, v10, v10 quad_perm:[2,3,0,1] row_mask:0xf bank_mask:0xf
	s_nop 1
	v_add_f32_dpp v10, v10, v10 row_half_mirror row_mask:0xf bank_mask:0xf
	s_nop 1
	v_add_f32_dpp v10, v10, v10 row_mirror row_mask:0xf bank_mask:0xf
	ds_swizzle_b32 v11, v10 offset:swizzle(SWAP,16)
	v_fma_f32 v45, v105, v35, -v40
	v_fmac_f32_e32 v44, v45, v45
	v_fma_f32 v35, v121, v35, -v41
	v_fmac_f32_e32 v44, v35, v35
	s_nop 1
	v_add_f32_dpp v40, v44, v44 quad_perm:[1,0,3,2] row_mask:0xf bank_mask:0xf
	s_nop 1
	v_add_f32_dpp v40, v40, v40 quad_perm:[2,3,0,1] row_mask:0xf bank_mask:0xf
	s_nop 1
	v_add_f32_dpp v40, v40, v40 row_half_mirror row_mask:0xf bank_mask:0xf
	s_nop 1
	v_add_f32_dpp v40, v40, v40 row_mirror row_mask:0xf bank_mask:0xf
	ds_swizzle_b32 v41, v40 offset:swizzle(SWAP,16)
	s_waitcnt lgkmcnt(0)
	v_add_f32_e32 v10, v10, v11
	v_fmamk_f32 v10, v10, 0x3c000000, v254
	v_rsq_f32_e32 v14, v10
	s_nop 0
	v_mul_f32_e32 v11, v12, v14
	v_mul_f32_e32 v12, v13, v14
	v_mul_f32_e32 v11, v6, v11
	v_mul_f32_e32 v12, v8, v12
	v_add_u32_e32 v10, 0x8000, v4
	v_cvt_pk_bf16_f32 v12, v11, v12
	v_mov_b32_e32 v11, v3
	v_lshl_add_u64 v[10:11], v[10:11], 1, s[6:7]
	global_store_short v[10:11], v12, off offset:768
	v_add_u32_e32 v10, 0x8020, v4
	v_mov_b32_e32 v11, v3
	v_lshl_add_u64 v[10:11], v[10:11], 1, s[6:7]
	global_store_short_d16_hi v[10:11], v12, off offset:768
	v_mul_f32_e32 v10, v15, v14
	v_mul_f32_e32 v5, v5, v14
	v_mul_f32_e32 v10, v2, v10
	v_mul_f32_e32 v5, v7, v5
	v_cvt_pk_bf16_f32 v5, v10, v5
	v_add_u32_e32 v10, 0x8040, v4
	v_mov_b32_e32 v11, v3
	v_lshl_add_u64 v[10:11], v[10:11], 1, s[6:7]
	global_store_short v[10:11], v5, off offset:768
	v_add_u32_e32 v10, 0x8060, v4
	v_mov_b32_e32 v11, v3
	v_lshl_add_u64 v[10:11], v[10:11], 1, s[6:7]
	global_store_short_d16_hi v[10:11], v5, off offset:768
	v_add_f32_e32 v40, v40, v41
	v_fmamk_f32 v40, v40, 0x3c000000, v254
	v_rsq_f32_e32 v44, v40
	s_nop 0
	v_mul_f32_e32 v41, v42, v44
	v_mul_f32_e32 v42, v43, v44
	v_mul_f32_e32 v41, v6, v41
	v_mul_f32_e32 v42, v8, v42
	v_add_u32_e32 v40, 0x9000, v4
	v_cvt_pk_bf16_f32 v42, v41, v42
	v_mov_b32_e32 v41, v3
	v_lshl_add_u64 v[40:41], v[40:41], 1, s[6:7]
	global_store_short v[40:41], v42, off offset:768
	v_add_u32_e32 v40, 0x9020, v4
	v_mov_b32_e32 v41, v3
	v_lshl_add_u64 v[40:41], v[40:41], 1, s[6:7]
	global_store_short_d16_hi v[40:41], v42, off offset:768
	v_mul_f32_e32 v40, v45, v44
	v_mul_f32_e32 v35, v35, v44
	v_mul_f32_e32 v40, v2, v40
	v_mul_f32_e32 v35, v7, v35
	v_cvt_pk_bf16_f32 v35, v40, v35
	v_add_u32_e32 v40, 0x9040, v4
	v_mov_b32_e32 v41, v3
	v_lshl_add_u64 v[40:41], v[40:41], 1, s[6:7]
	global_store_short v[40:41], v35, off offset:768
	v_add_u32_e32 v40, 0x9060, v4
	v_mov_b32_e32 v41, v3
	v_lshl_add_u64 v[40:41], v[40:41], 1, s[6:7]
	global_store_short_d16_hi v[40:41], v35, off offset:768
	ds_read_b32 v5, v9 offset:40
	ds_read2st64_b32 v[10:11], v1 offset0:6 offset1:22
	ds_read_b32 v35, v9 offset:44
	ds_read2st64_b32 v[40:41], v1 offset0:7 offset1:23
	s_waitcnt lgkmcnt(0)
	v_fma_f32 v12, v74, v5, -v10
	v_fma_f32 v13, v90, v5, -v11
	ds_read2st64_b32 v[10:11], v1 offset0:38 offset1:54
	v_mul_f32_e32 v14, v13, v13
	v_fmac_f32_e32 v14, v12, v12
	v_fma_f32 v42, v75, v35, -v40
	v_fma_f32 v43, v91, v35, -v41
	ds_read2st64_b32 v[40:41], v1 offset0:39 offset1:55
	v_mul_f32_e32 v44, v43, v43
	v_fmac_f32_e32 v44, v42, v42
	s_waitcnt lgkmcnt(0)
	v_fma_f32 v15, v106, v5, -v10
	v_fmac_f32_e32 v14, v15, v15
	v_fma_f32 v5, v122, v5, -v11
	v_fmac_f32_e32 v14, v5, v5
	s_nop 1
	v_add_f32_dpp v10, v14, v14 quad_perm:[1,0,3,2] row_mask:0xf bank_mask:0xf
	s_nop 1
	v_add_f32_dpp v10, v10, v10 quad_perm:[2,3,0,1] row_mask:0xf bank_mask:0xf
	s_nop 1
	v_add_f32_dpp v10, v10, v10 row_half_mirror row_mask:0xf bank_mask:0xf
	s_nop 1
	v_add_f32_dpp v10, v10, v10 row_mirror row_mask:0xf bank_mask:0xf
	ds_swizzle_b32 v11, v10 offset:swizzle(SWAP,16)
	v_fma_f32 v45, v107, v35, -v40
	v_fmac_f32_e32 v44, v45, v45
	v_fma_f32 v35, v123, v35, -v41
	v_fmac_f32_e32 v44, v35, v35
	s_nop 1
	v_add_f32_dpp v40, v44, v44 quad_perm:[1,0,3,2] row_mask:0xf bank_mask:0xf
	s_nop 1
	v_add_f32_dpp v40, v40, v40 quad_perm:[2,3,0,1] row_mask:0xf bank_mask:0xf
	s_nop 1
	v_add_f32_dpp v40, v40, v40 row_half_mirror row_mask:0xf bank_mask:0xf
	s_nop 1
	v_add_f32_dpp v40, v40, v40 row_mirror row_mask:0xf bank_mask:0xf
	ds_swizzle_b32 v41, v40 offset:swizzle(SWAP,16)
	s_waitcnt lgkmcnt(0)
	v_add_f32_e32 v10, v10, v11
	v_fmamk_f32 v10, v10, 0x3c000000, v254
	v_rsq_f32_e32 v14, v10
	s_nop 0
	v_mul_f32_e32 v11, v12, v14
	v_mul_f32_e32 v12, v13, v14
	v_mul_f32_e32 v11, v6, v11
	v_mul_f32_e32 v12, v8, v12
	v_add_u32_e32 v10, 0xa000, v4
	v_cvt_pk_bf16_f32 v12, v11, v12
	v_mov_b32_e32 v11, v3
	v_lshl_add_u64 v[10:11], v[10:11], 1, s[6:7]
	global_store_short v[10:11], v12, off offset:768
	v_add_u32_e32 v10, 0xa020, v4
	v_mov_b32_e32 v11, v3
	v_lshl_add_u64 v[10:11], v[10:11], 1, s[6:7]
	global_store_short_d16_hi v[10:11], v12, off offset:768
	v_mul_f32_e32 v10, v15, v14
	v_mul_f32_e32 v5, v5, v14
	v_mul_f32_e32 v10, v2, v10
	v_mul_f32_e32 v5, v7, v5
	v_cvt_pk_bf16_f32 v5, v10, v5
	v_add_u32_e32 v10, 0xa040, v4
	v_mov_b32_e32 v11, v3
	v_lshl_add_u64 v[10:11], v[10:11], 1, s[6:7]
	global_store_short v[10:11], v5, off offset:768
	v_add_u32_e32 v10, 0xa060, v4
	v_mov_b32_e32 v11, v3
	v_lshl_add_u64 v[10:11], v[10:11], 1, s[6:7]
	global_store_short_d16_hi v[10:11], v5, off offset:768
	v_add_f32_e32 v40, v40, v41
	v_fmamk_f32 v40, v40, 0x3c000000, v254
	v_rsq_f32_e32 v44, v40
	s_nop 0
	v_mul_f32_e32 v41, v42, v44
	v_mul_f32_e32 v42, v43, v44
	v_mul_f32_e32 v41, v6, v41
	v_mul_f32_e32 v42, v8, v42
	v_add_u32_e32 v40, 0xb000, v4
	v_cvt_pk_bf16_f32 v42, v41, v42
	v_mov_b32_e32 v41, v3
	v_lshl_add_u64 v[40:41], v[40:41], 1, s[6:7]
	global_store_short v[40:41], v42, off offset:768
	v_add_u32_e32 v40, 0xb020, v4
	v_mov_b32_e32 v41, v3
	v_lshl_add_u64 v[40:41], v[40:41], 1, s[6:7]
	global_store_short_d16_hi v[40:41], v42, off offset:768
	v_mul_f32_e32 v40, v45, v44
	v_mul_f32_e32 v35, v35, v44
	v_mul_f32_e32 v40, v2, v40
	v_mul_f32_e32 v35, v7, v35
	v_cvt_pk_bf16_f32 v35, v40, v35
	v_add_u32_e32 v40, 0xb040, v4
	v_mov_b32_e32 v41, v3
	v_lshl_add_u64 v[40:41], v[40:41], 1, s[6:7]
	global_store_short v[40:41], v35, off offset:768
	v_add_u32_e32 v40, 0xb060, v4
	v_mov_b32_e32 v41, v3
	v_lshl_add_u64 v[40:41], v[40:41], 1, s[6:7]
	global_store_short_d16_hi v[40:41], v35, off offset:768
	ds_read_b32 v5, v9 offset:64
	ds_read2st64_b32 v[10:11], v1 offset0:8 offset1:24
	ds_read_b32 v35, v9 offset:68
	ds_read2st64_b32 v[40:41], v1 offset0:9 offset1:25
	s_waitcnt lgkmcnt(0)
	v_fma_f32 v12, v76, v5, -v10
	v_fma_f32 v13, v92, v5, -v11
	ds_read2st64_b32 v[10:11], v1 offset0:40 offset1:56
	v_mul_f32_e32 v14, v13, v13
	v_fmac_f32_e32 v14, v12, v12
	v_fma_f32 v42, v77, v35, -v40
	v_fma_f32 v43, v93, v35, -v41
	ds_read2st64_b32 v[40:41], v1 offset0:41 offset1:57
	v_mul_f32_e32 v44, v43, v43
	v_fmac_f32_e32 v44, v42, v42
	s_waitcnt lgkmcnt(0)
	v_fma_f32 v15, v108, v5, -v10
	v_fmac_f32_e32 v14, v15, v15
	v_fma_f32 v5, v124, v5, -v11
	v_fmac_f32_e32 v14, v5, v5
	s_nop 1
	v_add_f32_dpp v10, v14, v14 quad_perm:[1,0,3,2] row_mask:0xf bank_mask:0xf
	s_nop 1
	v_add_f32_dpp v10, v10, v10 quad_perm:[2,3,0,1] row_mask:0xf bank_mask:0xf
	s_nop 1
	v_add_f32_dpp v10, v10, v10 row_half_mirror row_mask:0xf bank_mask:0xf
	s_nop 1
	v_add_f32_dpp v10, v10, v10 row_mirror row_mask:0xf bank_mask:0xf
	ds_swizzle_b32 v11, v10 offset:swizzle(SWAP,16)
	v_fma_f32 v45, v109, v35, -v40
	v_fmac_f32_e32 v44, v45, v45
	v_fma_f32 v35, v125, v35, -v41
	v_fmac_f32_e32 v44, v35, v35
	s_nop 1
	v_add_f32_dpp v40, v44, v44 quad_perm:[1,0,3,2] row_mask:0xf bank_mask:0xf
	s_nop 1
	v_add_f32_dpp v40, v40, v40 quad_perm:[2,3,0,1] row_mask:0xf bank_mask:0xf
	s_nop 1
	v_add_f32_dpp v40, v40, v40 row_half_mirror row_mask:0xf bank_mask:0xf
	s_nop 1
	v_add_f32_dpp v40, v40, v40 row_mirror row_mask:0xf bank_mask:0xf
	ds_swizzle_b32 v41, v40 offset:swizzle(SWAP,16)
	s_waitcnt lgkmcnt(0)
	v_add_f32_e32 v10, v10, v11
	v_fmamk_f32 v10, v10, 0x3c000000, v254
	v_rsq_f32_e32 v14, v10
	s_nop 0
	v_mul_f32_e32 v11, v12, v14
	v_mul_f32_e32 v12, v13, v14
	v_mul_f32_e32 v11, v6, v11
	v_mul_f32_e32 v12, v8, v12
	v_add_u32_e32 v10, 0x10000, v4
	v_cvt_pk_bf16_f32 v12, v11, v12
	v_mov_b32_e32 v11, v3
	v_lshl_add_u64 v[10:11], v[10:11], 1, s[6:7]
	global_store_short v[10:11], v12, off offset:768
	v_add_u32_e32 v10, 0x10020, v4
	v_mov_b32_e32 v11, v3
	v_lshl_add_u64 v[10:11], v[10:11], 1, s[6:7]
	global_store_short_d16_hi v[10:11], v12, off offset:768
	v_mul_f32_e32 v10, v15, v14
	v_mul_f32_e32 v5, v5, v14
	v_mul_f32_e32 v10, v2, v10
	v_mul_f32_e32 v5, v7, v5
	v_cvt_pk_bf16_f32 v5, v10, v5
	v_add_u32_e32 v10, 0x10040, v4
	v_mov_b32_e32 v11, v3
	v_lshl_add_u64 v[10:11], v[10:11], 1, s[6:7]
	global_store_short v[10:11], v5, off offset:768
	v_add_u32_e32 v10, 0x10060, v4
	v_mov_b32_e32 v11, v3
	v_lshl_add_u64 v[10:11], v[10:11], 1, s[6:7]
	global_store_short_d16_hi v[10:11], v5, off offset:768
	v_add_f32_e32 v40, v40, v41
	v_fmamk_f32 v40, v40, 0x3c000000, v254
	v_rsq_f32_e32 v44, v40
	s_nop 0
	v_mul_f32_e32 v41, v42, v44
	v_mul_f32_e32 v42, v43, v44
	v_mul_f32_e32 v41, v6, v41
	v_mul_f32_e32 v42, v8, v42
	v_add_u32_e32 v40, 0x11000, v4
	v_cvt_pk_bf16_f32 v42, v41, v42
	v_mov_b32_e32 v41, v3
	v_lshl_add_u64 v[40:41], v[40:41], 1, s[6:7]
	global_store_short v[40:41], v42, off offset:768
	v_add_u32_e32 v40, 0x11020, v4
	v_mov_b32_e32 v41, v3
	v_lshl_add_u64 v[40:41], v[40:41], 1, s[6:7]
	global_store_short_d16_hi v[40:41], v42, off offset:768
	v_mul_f32_e32 v40, v45, v44
	v_mul_f32_e32 v35, v35, v44
	v_mul_f32_e32 v40, v2, v40
	v_mul_f32_e32 v35, v7, v35
	v_cvt_pk_bf16_f32 v35, v40, v35
	v_add_u32_e32 v40, 0x11040, v4
	v_mov_b32_e32 v41, v3
	v_lshl_add_u64 v[40:41], v[40:41], 1, s[6:7]
	global_store_short v[40:41], v35, off offset:768
	v_add_u32_e32 v40, 0x11060, v4
	v_mov_b32_e32 v41, v3
	v_lshl_add_u64 v[40:41], v[40:41], 1, s[6:7]
	global_store_short_d16_hi v[40:41], v35, off offset:768
	ds_read_b32 v5, v9 offset:72
	ds_read2st64_b32 v[10:11], v1 offset0:10 offset1:26
	ds_read_b32 v35, v9 offset:76
	ds_read2st64_b32 v[40:41], v1 offset0:11 offset1:27
	s_waitcnt lgkmcnt(0)
	v_fma_f32 v12, v78, v5, -v10
	v_fma_f32 v13, v94, v5, -v11
	ds_read2st64_b32 v[10:11], v1 offset0:42 offset1:58
	v_mul_f32_e32 v14, v13, v13
	v_fmac_f32_e32 v14, v12, v12
	v_fma_f32 v42, v79, v35, -v40
	v_fma_f32 v43, v95, v35, -v41
	ds_read2st64_b32 v[40:41], v1 offset0:43 offset1:59
	v_mul_f32_e32 v44, v43, v43
	v_fmac_f32_e32 v44, v42, v42
	s_waitcnt lgkmcnt(0)
	v_fma_f32 v15, v110, v5, -v10
	v_fmac_f32_e32 v14, v15, v15
	v_fma_f32 v5, v126, v5, -v11
	v_fmac_f32_e32 v14, v5, v5
	s_nop 1
	v_add_f32_dpp v10, v14, v14 quad_perm:[1,0,3,2] row_mask:0xf bank_mask:0xf
	s_nop 1
	v_add_f32_dpp v10, v10, v10 quad_perm:[2,3,0,1] row_mask:0xf bank_mask:0xf
	s_nop 1
	v_add_f32_dpp v10, v10, v10 row_half_mirror row_mask:0xf bank_mask:0xf
	s_nop 1
	v_add_f32_dpp v10, v10, v10 row_mirror row_mask:0xf bank_mask:0xf
	ds_swizzle_b32 v11, v10 offset:swizzle(SWAP,16)
	v_fma_f32 v45, v111, v35, -v40
	v_fmac_f32_e32 v44, v45, v45
	v_fma_f32 v35, v127, v35, -v41
	v_fmac_f32_e32 v44, v35, v35
	s_nop 1
	v_add_f32_dpp v40, v44, v44 quad_perm:[1,0,3,2] row_mask:0xf bank_mask:0xf
	s_nop 1
	v_add_f32_dpp v40, v40, v40 quad_perm:[2,3,0,1] row_mask:0xf bank_mask:0xf
	s_nop 1
	v_add_f32_dpp v40, v40, v40 row_half_mirror row_mask:0xf bank_mask:0xf
	s_nop 1
	v_add_f32_dpp v40, v40, v40 row_mirror row_mask:0xf bank_mask:0xf
	ds_swizzle_b32 v41, v40 offset:swizzle(SWAP,16)
	s_waitcnt lgkmcnt(0)
	v_add_f32_e32 v10, v10, v11
	v_fmamk_f32 v10, v10, 0x3c000000, v254
	v_rsq_f32_e32 v14, v10
	s_nop 0
	v_mul_f32_e32 v11, v12, v14
	v_mul_f32_e32 v12, v13, v14
	v_mul_f32_e32 v11, v6, v11
	v_mul_f32_e32 v12, v8, v12
	v_add_u32_e32 v10, 0x12000, v4
	v_cvt_pk_bf16_f32 v12, v11, v12
	v_mov_b32_e32 v11, v3
	v_lshl_add_u64 v[10:11], v[10:11], 1, s[6:7]
	global_store_short v[10:11], v12, off offset:768
	v_add_u32_e32 v10, 0x12020, v4
	v_mov_b32_e32 v11, v3
	v_lshl_add_u64 v[10:11], v[10:11], 1, s[6:7]
	global_store_short_d16_hi v[10:11], v12, off offset:768
	v_mul_f32_e32 v10, v15, v14
	v_mul_f32_e32 v5, v5, v14
	v_mul_f32_e32 v10, v2, v10
	v_mul_f32_e32 v5, v7, v5
	v_cvt_pk_bf16_f32 v5, v10, v5
	v_add_u32_e32 v10, 0x12040, v4
	v_mov_b32_e32 v11, v3
	v_lshl_add_u64 v[10:11], v[10:11], 1, s[6:7]
	global_store_short v[10:11], v5, off offset:768
	v_add_u32_e32 v10, 0x12060, v4
	v_mov_b32_e32 v11, v3
	v_lshl_add_u64 v[10:11], v[10:11], 1, s[6:7]
	global_store_short_d16_hi v[10:11], v5, off offset:768
	v_add_f32_e32 v40, v40, v41
	v_fmamk_f32 v40, v40, 0x3c000000, v254
	v_rsq_f32_e32 v44, v40
	s_nop 0
	v_mul_f32_e32 v41, v42, v44
	v_mul_f32_e32 v42, v43, v44
	v_mul_f32_e32 v41, v6, v41
	v_mul_f32_e32 v42, v8, v42
	v_add_u32_e32 v40, 0x13000, v4
	v_cvt_pk_bf16_f32 v42, v41, v42
	v_mov_b32_e32 v41, v3
	v_lshl_add_u64 v[40:41], v[40:41], 1, s[6:7]
	global_store_short v[40:41], v42, off offset:768
	v_add_u32_e32 v40, 0x13020, v4
	v_mov_b32_e32 v41, v3
	v_lshl_add_u64 v[40:41], v[40:41], 1, s[6:7]
	global_store_short_d16_hi v[40:41], v42, off offset:768
	v_mul_f32_e32 v40, v45, v44
	v_mul_f32_e32 v35, v35, v44
	v_mul_f32_e32 v40, v2, v40
	v_mul_f32_e32 v35, v7, v35
	v_cvt_pk_bf16_f32 v35, v40, v35
	v_add_u32_e32 v40, 0x13040, v4
	v_mov_b32_e32 v41, v3
	v_lshl_add_u64 v[40:41], v[40:41], 1, s[6:7]
	global_store_short v[40:41], v35, off offset:768
	v_add_u32_e32 v40, 0x13060, v4
	v_mov_b32_e32 v41, v3
	v_lshl_add_u64 v[40:41], v[40:41], 1, s[6:7]
	global_store_short_d16_hi v[40:41], v35, off offset:768
	ds_read_b32 v5, v9 offset:96
	ds_read2st64_b32 v[10:11], v1 offset0:12 offset1:28
	ds_read_b32 v35, v9 offset:100
	ds_read2st64_b32 v[40:41], v1 offset0:13 offset1:29
	s_waitcnt lgkmcnt(0)
	v_fma_f32 v12, v80, v5, -v10
	v_fma_f32 v13, v96, v5, -v11
	ds_read2st64_b32 v[10:11], v1 offset0:44 offset1:60
	v_mul_f32_e32 v14, v13, v13
	v_fmac_f32_e32 v14, v12, v12
	v_fma_f32 v42, v81, v35, -v40
	v_fma_f32 v43, v97, v35, -v41
	ds_read2st64_b32 v[40:41], v1 offset0:45 offset1:61
	v_mul_f32_e32 v44, v43, v43
	v_fmac_f32_e32 v44, v42, v42
	s_waitcnt lgkmcnt(0)
	v_fma_f32 v15, v112, v5, -v10
	v_fmac_f32_e32 v14, v15, v15
	v_fma_f32 v5, v128, v5, -v11
	v_fmac_f32_e32 v14, v5, v5
	s_nop 1
	v_add_f32_dpp v10, v14, v14 quad_perm:[1,0,3,2] row_mask:0xf bank_mask:0xf
	s_nop 1
	v_add_f32_dpp v10, v10, v10 quad_perm:[2,3,0,1] row_mask:0xf bank_mask:0xf
	s_nop 1
	v_add_f32_dpp v10, v10, v10 row_half_mirror row_mask:0xf bank_mask:0xf
	s_nop 1
	v_add_f32_dpp v10, v10, v10 row_mirror row_mask:0xf bank_mask:0xf
	ds_swizzle_b32 v11, v10 offset:swizzle(SWAP,16)
	v_fma_f32 v45, v113, v35, -v40
	v_fmac_f32_e32 v44, v45, v45
	v_fma_f32 v35, v129, v35, -v41
	v_fmac_f32_e32 v44, v35, v35
	s_nop 1
	v_add_f32_dpp v40, v44, v44 quad_perm:[1,0,3,2] row_mask:0xf bank_mask:0xf
	s_nop 1
	v_add_f32_dpp v40, v40, v40 quad_perm:[2,3,0,1] row_mask:0xf bank_mask:0xf
	s_nop 1
	v_add_f32_dpp v40, v40, v40 row_half_mirror row_mask:0xf bank_mask:0xf
	s_nop 1
	v_add_f32_dpp v40, v40, v40 row_mirror row_mask:0xf bank_mask:0xf
	ds_swizzle_b32 v41, v40 offset:swizzle(SWAP,16)
	s_waitcnt lgkmcnt(0)
	v_add_f32_e32 v10, v10, v11
	v_fmamk_f32 v10, v10, 0x3c000000, v254
	v_rsq_f32_e32 v14, v10
	s_nop 0
	v_mul_f32_e32 v11, v12, v14
	v_mul_f32_e32 v12, v13, v14
	v_mul_f32_e32 v11, v6, v11
	v_mul_f32_e32 v12, v8, v12
	v_add_u32_e32 v10, 0x18000, v4
	v_cvt_pk_bf16_f32 v12, v11, v12
	v_mov_b32_e32 v11, v3
	v_lshl_add_u64 v[10:11], v[10:11], 1, s[6:7]
	global_store_short v[10:11], v12, off offset:768
	v_add_u32_e32 v10, 0x18020, v4
	v_mov_b32_e32 v11, v3
	v_lshl_add_u64 v[10:11], v[10:11], 1, s[6:7]
	global_store_short_d16_hi v[10:11], v12, off offset:768
	v_mul_f32_e32 v10, v15, v14
	v_mul_f32_e32 v5, v5, v14
	v_mul_f32_e32 v10, v2, v10
	v_mul_f32_e32 v5, v7, v5
	v_cvt_pk_bf16_f32 v5, v10, v5
	v_add_u32_e32 v10, 0x18040, v4
	v_mov_b32_e32 v11, v3
	v_lshl_add_u64 v[10:11], v[10:11], 1, s[6:7]
	global_store_short v[10:11], v5, off offset:768
	v_add_u32_e32 v10, 0x18060, v4
	v_mov_b32_e32 v11, v3
	v_lshl_add_u64 v[10:11], v[10:11], 1, s[6:7]
	global_store_short_d16_hi v[10:11], v5, off offset:768
	v_add_f32_e32 v40, v40, v41
	v_fmamk_f32 v40, v40, 0x3c000000, v254
	v_rsq_f32_e32 v44, v40
	s_nop 0
	v_mul_f32_e32 v41, v42, v44
	v_mul_f32_e32 v42, v43, v44
	v_mul_f32_e32 v41, v6, v41
	v_mul_f32_e32 v42, v8, v42
	v_add_u32_e32 v40, 0x19000, v4
	v_cvt_pk_bf16_f32 v42, v41, v42
	v_mov_b32_e32 v41, v3
	v_lshl_add_u64 v[40:41], v[40:41], 1, s[6:7]
	global_store_short v[40:41], v42, off offset:768
	v_add_u32_e32 v40, 0x19020, v4
	v_mov_b32_e32 v41, v3
	v_lshl_add_u64 v[40:41], v[40:41], 1, s[6:7]
	global_store_short_d16_hi v[40:41], v42, off offset:768
	v_mul_f32_e32 v40, v45, v44
	v_mul_f32_e32 v35, v35, v44
	v_mul_f32_e32 v40, v2, v40
	v_mul_f32_e32 v35, v7, v35
	v_cvt_pk_bf16_f32 v35, v40, v35
	v_add_u32_e32 v40, 0x19040, v4
	v_mov_b32_e32 v41, v3
	v_lshl_add_u64 v[40:41], v[40:41], 1, s[6:7]
	global_store_short v[40:41], v35, off offset:768
	v_add_u32_e32 v40, 0x19060, v4
	v_mov_b32_e32 v41, v3
	v_lshl_add_u64 v[40:41], v[40:41], 1, s[6:7]
	global_store_short_d16_hi v[40:41], v35, off offset:768
	ds_read_b32 v5, v9 offset:104
	ds_read2st64_b32 v[10:11], v1 offset0:14 offset1:30
	s_waitcnt lgkmcnt(0)
	v_fma_f32 v12, v82, v5, -v10
	v_fma_f32 v13, v98, v5, -v11
	ds_read2st64_b32 v[10:11], v1 offset0:46 offset1:62
	v_mul_f32_e32 v14, v13, v13
	v_fmac_f32_e32 v14, v12, v12
	s_waitcnt lgkmcnt(0)
	v_fma_f32 v15, v114, v5, -v10
	v_fmac_f32_e32 v14, v15, v15
	v_fma_f32 v5, v130, v5, -v11
	v_fmac_f32_e32 v14, v5, v5
	s_nop 1
	v_add_f32_dpp v10, v14, v14 quad_perm:[1,0,3,2] row_mask:0xf bank_mask:0xf
	s_nop 1
	v_add_f32_dpp v10, v10, v10 quad_perm:[2,3,0,1] row_mask:0xf bank_mask:0xf
	s_nop 1
	v_add_f32_dpp v10, v10, v10 row_half_mirror row_mask:0xf bank_mask:0xf
	s_nop 1
	v_add_f32_dpp v10, v10, v10 row_mirror row_mask:0xf bank_mask:0xf
	ds_swizzle_b32 v11, v10 offset:swizzle(SWAP,16)
	s_waitcnt lgkmcnt(0)
	v_add_f32_e32 v10, v10, v11
	v_fmamk_f32 v10, v10, 0x3c000000, v254
	v_cmp_gt_f32_e32 vcc, s90, v10
	v_mul_f32_e32 v11, 0x4f800000, v10
	s_nop 0
	v_cndmask_b32_e32 v10, v10, v11, vcc
	v_sqrt_f32_e32 v11, v10
	s_nop 0
	v_add_u32_e32 v14, -1, v11
	v_fma_f32 v16, -v14, v11, v10
	v_cmp_ge_f32_e64 s[4:5], 0, v16
	v_add_u32_e32 v16, 1, v11
	s_nop 0
	v_cndmask_b32_e64 v14, v11, v14, s[4:5]
	v_fma_f32 v11, -v16, v11, v10
	v_cmp_lt_f32_e64 s[4:5], 0, v11
	s_nop 1
	v_cndmask_b32_e64 v11, v14, v16, s[4:5]
	v_mul_f32_e32 v14, 0x37800000, v11
	v_cndmask_b32_e32 v11, v11, v14, vcc
	v_cmp_class_f32_e32 vcc, v10, v209
	s_nop 1
	v_cndmask_b32_e32 v10, v11, v10, vcc
	v_div_scale_f32 v11, s[4:5], v10, v10, 1.0
	v_rcp_f32_e32 v14, v11
	s_nop 0
	v_fma_f32 v16, -v11, v14, 1.0
	v_fmac_f32_e32 v14, v16, v14
	v_div_scale_f32 v16, vcc, 1.0, v10, 1.0
	v_mul_f32_e32 v17, v16, v14
	v_fma_f32 v18, -v11, v17, v16
	v_fmac_f32_e32 v17, v18, v14
	v_fma_f32 v11, -v11, v17, v16
	v_div_fmas_f32 v11, v11, v14, v17
	v_div_fixup_f32 v14, v11, v10, 1.0
	v_mul_f32_e32 v11, v12, v14
	v_mul_f32_e32 v12, v13, v14
	v_mul_f32_e32 v11, v6, v11
	v_mul_f32_e32 v12, v8, v12
	v_add_u32_e32 v10, 0x1a000, v4
	v_cvt_pk_bf16_f32 v12, v11, v12
	v_mov_b32_e32 v11, v3
	v_lshl_add_u64 v[10:11], v[10:11], 1, s[6:7]
	global_store_short v[10:11], v12, off offset:768
	v_add_u32_e32 v10, 0x1a020, v4
	v_mov_b32_e32 v11, v3
	v_lshl_add_u64 v[10:11], v[10:11], 1, s[6:7]
	global_store_short_d16_hi v[10:11], v12, off offset:768
	v_mul_f32_e32 v10, v15, v14
	v_mul_f32_e32 v5, v5, v14
	v_mul_f32_e32 v10, v2, v10
	v_mul_f32_e32 v5, v7, v5
	v_cvt_pk_bf16_f32 v5, v10, v5
	v_add_u32_e32 v10, 0x1a040, v4
	v_mov_b32_e32 v11, v3
	v_lshl_add_u64 v[10:11], v[10:11], 1, s[6:7]
	global_store_short v[10:11], v5, off offset:768
	v_add_u32_e32 v10, 0x1a060, v4
	v_mov_b32_e32 v11, v3
	v_lshl_add_u64 v[10:11], v[10:11], 1, s[6:7]
	global_store_short_d16_hi v[10:11], v5, off offset:768
	ds_read_b32 v5, v9 offset:108
	ds_read2st64_b32 v[10:11], v1 offset0:15 offset1:31
	s_waitcnt lgkmcnt(0)
	v_fma_f32 v9, v83, v5, -v10
	v_fma_f32 v12, v99, v5, -v11
	ds_read2st64_b32 v[10:11], v1 offset0:47 offset1:63
	v_mul_f32_e32 v13, v12, v12
	v_fmac_f32_e32 v13, v9, v9
	s_waitcnt lgkmcnt(0)
	v_fma_f32 v1, v115, v5, -v10
	v_fmac_f32_e32 v13, v1, v1
	v_fma_f32 v5, v131, v5, -v11
	v_fmac_f32_e32 v13, v5, v5
	s_nop 1
	v_add_f32_dpp v10, v13, v13 quad_perm:[1,0,3,2] row_mask:0xf bank_mask:0xf
	s_nop 1
	v_add_f32_dpp v10, v10, v10 quad_perm:[2,3,0,1] row_mask:0xf bank_mask:0xf
	s_nop 1
	v_add_f32_dpp v10, v10, v10 row_half_mirror row_mask:0xf bank_mask:0xf
	s_nop 1
	v_add_f32_dpp v10, v10, v10 row_mirror row_mask:0xf bank_mask:0xf
	ds_swizzle_b32 v11, v10 offset:swizzle(SWAP,16)
	s_waitcnt lgkmcnt(0)
	v_add_f32_e32 v10, v10, v11
	v_fmamk_f32 v10, v10, 0x3c000000, v254
	v_cmp_gt_f32_e32 vcc, s90, v10
	v_mul_f32_e32 v11, 0x4f800000, v10
	s_nop 0
	v_cndmask_b32_e32 v10, v10, v11, vcc
	v_sqrt_f32_e32 v11, v10
	s_nop 0
	v_add_u32_e32 v13, -1, v11
	v_fma_f32 v14, -v13, v11, v10
	v_cmp_ge_f32_e64 s[4:5], 0, v14
	v_add_u32_e32 v14, 1, v11
	s_nop 0
	v_cndmask_b32_e64 v13, v11, v13, s[4:5]
	v_fma_f32 v11, -v14, v11, v10
	v_cmp_lt_f32_e64 s[4:5], 0, v11
	s_nop 1
	v_cndmask_b32_e64 v11, v13, v14, s[4:5]
	v_mul_f32_e32 v13, 0x37800000, v11
	v_cndmask_b32_e32 v11, v11, v13, vcc
	v_cmp_class_f32_e32 vcc, v10, v209
	s_nop 1
	v_cndmask_b32_e32 v10, v11, v10, vcc
	v_div_scale_f32 v11, s[4:5], v10, v10, 1.0
	v_rcp_f32_e32 v13, v11
	s_nop 0
	v_fma_f32 v14, -v11, v13, 1.0
	v_fmac_f32_e32 v13, v14, v13
	v_div_scale_f32 v14, vcc, 1.0, v10, 1.0
	v_mul_f32_e32 v15, v14, v13
	v_fma_f32 v16, -v11, v15, v14
	v_fmac_f32_e32 v15, v16, v13
	v_fma_f32 v11, -v11, v15, v14
	v_div_fmas_f32 v11, v11, v13, v15
	v_div_fixup_f32 v13, v11, v10, 1.0
	v_mul_f32_e32 v9, v9, v13
	v_mul_f32_e32 v6, v6, v9
	v_mul_f32_e32 v9, v12, v13
	v_add_u32_e32 v10, 0x1b000, v4
	v_mul_f32_e32 v8, v8, v9
	v_mov_b32_e32 v11, v3
	v_cvt_pk_bf16_f32 v6, v6, v8
	v_lshl_add_u64 v[8:9], v[10:11], 1, s[6:7]
	global_store_short v[8:9], v6, off offset:768
	v_add_u32_e32 v8, 0x1b020, v4
	v_mov_b32_e32 v9, v3
	v_mul_f32_e32 v1, v1, v13
	v_lshl_add_u64 v[8:9], v[8:9], 1, s[6:7]
	v_mul_f32_e32 v1, v2, v1
	v_mul_f32_e32 v2, v5, v13
	global_store_short_d16_hi v[8:9], v6, off offset:768
	v_mul_f32_e32 v2, v7, v2
	v_add_u32_e32 v6, 0x1b040, v4
	v_mov_b32_e32 v7, v3
	v_add_u32_e32 v4, 0x1b060, v4
	v_mov_b32_e32 v5, v3
	v_lshl_add_u64 v[6:7], v[6:7], 1, s[6:7]
	v_lshl_add_u64 v[4:5], v[4:5], 1, s[6:7]
	v_cvt_pk_bf16_f32 v1, v1, v2
	global_store_short v[6:7], v1, off offset:768
	global_store_short_d16_hi v[4:5], v1, off offset:768

.LBB0_1422:
	s_or_b64 exec, exec, s[6:7]
	s_waitcnt lgkmcnt(0)
	v_lshl_add_u32 v68, v2, 4, s34
	ds_read_b32 v84, v68
	ds_read_b32 v85, v68 offset:4
	ds_read_b32 v86, v68 offset:8
	ds_read_b32 v87, v68 offset:12
	ds_read_b32 v88, v68 offset:32
	ds_read_b32 v89, v68 offset:36
	ds_read_b32 v90, v68 offset:40
	ds_read_b32 v91, v68 offset:44
	ds_read_b32 v92, v68 offset:64
	ds_read_b32 v93, v68 offset:68
	ds_read_b32 v94, v68 offset:72
	ds_read_b32 v95, v68 offset:76
	ds_read_b32 v96, v68 offset:96
	ds_read_b32 v97, v68 offset:100
	ds_read_b32 v98, v68 offset:104
	ds_read_b32 v99, v68 offset:108
	s_waitcnt lgkmcnt(0)
	v_mul_f32_e32 v71, v52, v84
	ds_write_b32 v70, v71
	v_mul_f32_e32 v71, v36, v84
	ds_write_b32 v70, v71 offset:4096
	v_mul_f32_e32 v71, v20, v84
	v_mul_f32_e32 v84, v4, v84
	ds_write_b32 v70, v71 offset:8192
	ds_write_b32 v70, v84 offset:12288
	v_mul_f32_e32 v71, v53, v85
	ds_write_b32 v70, v71 offset:256
	v_mul_f32_e32 v71, v37, v85
	ds_write_b32 v70, v71 offset:4352
	v_mul_f32_e32 v71, v21, v85
	v_mul_f32_e32 v85, v5, v85
	ds_write_b32 v70, v71 offset:8448
	ds_write_b32 v70, v85 offset:12544
	v_mul_f32_e32 v71, v54, v86
	ds_write_b32 v70, v71 offset:512
	v_mul_f32_e32 v71, v38, v86
	ds_write_b32 v70, v71 offset:4608
	v_mul_f32_e32 v71, v22, v86
	v_mul_f32_e32 v86, v6, v86
	ds_write_b32 v70, v71 offset:8704
	ds_write_b32 v70, v86 offset:12800
	v_mul_f32_e32 v71, v55, v87
	ds_write_b32 v70, v71 offset:768
	v_mul_f32_e32 v71, v39, v87
	ds_write_b32 v70, v71 offset:4864
	v_mul_f32_e32 v71, v23, v87
	v_mul_f32_e32 v87, v7, v87
	ds_write_b32 v70, v71 offset:8960
	ds_write_b32 v70, v87 offset:13056
	v_mul_f32_e32 v71, v56, v88
	ds_write_b32 v70, v71 offset:1024
	v_mul_f32_e32 v71, v40, v88
	ds_write_b32 v70, v71 offset:5120
	v_mul_f32_e32 v71, v24, v88
	v_mul_f32_e32 v88, v8, v88
	ds_write_b32 v70, v71 offset:9216
	ds_write_b32 v70, v88 offset:13312
	v_mul_f32_e32 v71, v57, v89
	ds_write_b32 v70, v71 offset:1280
	v_mul_f32_e32 v71, v41, v89
	ds_write_b32 v70, v71 offset:5376
	v_mul_f32_e32 v71, v25, v89
	v_mul_f32_e32 v89, v9, v89
	ds_write_b32 v70, v71 offset:9472
	ds_write_b32 v70, v89 offset:13568
	v_mul_f32_e32 v71, v58, v90
	ds_write_b32 v70, v71 offset:1536
	v_mul_f32_e32 v71, v42, v90
	ds_write_b32 v70, v71 offset:5632
	v_mul_f32_e32 v71, v26, v90
	v_mul_f32_e32 v90, v10, v90
	ds_write_b32 v70, v71 offset:9728
	ds_write_b32 v70, v90 offset:13824
	v_mul_f32_e32 v71, v59, v91
	ds_write_b32 v70, v71 offset:1792
	v_mul_f32_e32 v71, v43, v91
	ds_write_b32 v70, v71 offset:5888
	v_mul_f32_e32 v71, v27, v91
	v_mul_f32_e32 v91, v11, v91
	ds_write_b32 v70, v71 offset:9984
	ds_write_b32 v70, v91 offset:14080
	v_mul_f32_e32 v71, v60, v92
	ds_write_b32 v70, v71 offset:2048
	v_mul_f32_e32 v71, v44, v92
	ds_write_b32 v70, v71 offset:6144
	v_mul_f32_e32 v71, v28, v92
	v_mul_f32_e32 v92, v12, v92
	ds_write_b32 v70, v71 offset:10240
	ds_write_b32 v70, v92 offset:14336
	v_mul_f32_e32 v71, v61, v93
	ds_write_b32 v70, v71 offset:2304
	v_mul_f32_e32 v71, v45, v93
	ds_write_b32 v70, v71 offset:6400
	v_mul_f32_e32 v71, v29, v93
	v_mul_f32_e32 v93, v13, v93
	ds_write_b32 v70, v71 offset:10496
	ds_write_b32 v70, v93 offset:14592
	v_mul_f32_e32 v71, v62, v94
	ds_write_b32 v70, v71 offset:2560
	v_mul_f32_e32 v71, v46, v94
	ds_write_b32 v70, v71 offset:6656
	v_mul_f32_e32 v71, v30, v94
	v_mul_f32_e32 v94, v14, v94
	ds_write_b32 v70, v71 offset:10752
	ds_write_b32 v70, v94 offset:14848
	v_mul_f32_e32 v71, v63, v95
	ds_write_b32 v70, v71 offset:2816
	v_mul_f32_e32 v71, v47, v95
	ds_write_b32 v70, v71 offset:6912
	v_mul_f32_e32 v71, v31, v95
	v_mul_f32_e32 v95, v15, v95
	ds_write_b32 v70, v71 offset:11008
	ds_write_b32 v70, v95 offset:15104
	v_mul_f32_e32 v71, v64, v96
	ds_write_b32 v70, v71 offset:3072
	v_mul_f32_e32 v71, v48, v96
	ds_write_b32 v70, v71 offset:7168
	v_mul_f32_e32 v71, v32, v96
	v_mul_f32_e32 v96, v16, v96
	ds_write_b32 v70, v71 offset:11264
	ds_write_b32 v70, v96 offset:15360
	v_mul_f32_e32 v71, v65, v97
	ds_write_b32 v70, v71 offset:3328
	v_mul_f32_e32 v71, v49, v97
	ds_write_b32 v70, v71 offset:7424
	v_mul_f32_e32 v71, v33, v97
	v_mul_f32_e32 v97, v17, v97
	ds_write_b32 v70, v71 offset:11520
	ds_write_b32 v70, v97 offset:15616
	v_mul_f32_e32 v71, v66, v98
	ds_write_b32 v70, v71 offset:3584
	v_mul_f32_e32 v71, v50, v98
	ds_write_b32 v70, v71 offset:7680
	v_mul_f32_e32 v71, v34, v98
	v_mul_f32_e32 v98, v18, v98
	ds_write_b32 v70, v71 offset:11776
	ds_write_b32 v70, v98 offset:15872
	v_mul_f32_e32 v69, v67, v99
	ds_write_b32 v70, v69 offset:3840
	v_mul_f32_e32 v69, v51, v99
	ds_write_b32 v70, v69 offset:7936
	v_mul_f32_e32 v69, v35, v99
	v_mul_f32_e32 v99, v19, v99
	ds_write_b32 v70, v69 offset:12032
	ds_write_b32 v70, v99 offset:16128
	v_mov_b32_e32 v69, v98
	v_mov_b32_e32 v68, v99

.LBB0_1426:
	s_or_b64 exec, exec, s[4:5]
	s_waitcnt lgkmcnt(0)
	v_lshlrev_b32_e32 v68, 2, v1
	global_load_dword v248, v68, s[0:1]
	global_load_dword v249, v68, s[0:1] offset:128
	global_load_dword v250, v68, s[0:1] offset:256
	global_load_dword v251, v68, s[0:1] offset:384
	s_or_b32 s24, s24, s35
	s_lshl_b64 s[4:5], s[24:25], 13
	s_add_u32 s6, s86, s4
	s_addc_u32 s7, s87, s5
	s_lshl_b64 s[4:5], s[46:47], 1
	s_add_u32 s6, s6, s4
	s_addc_u32 s7, s7, s5
	s_waitcnt vmcnt(0)
	v_mul_f32_e32 v72, v164, v248
	v_mul_f32_e32 v74, v164, v249
	v_mul_f32_e32 v71, v164, v250
	v_mul_f32_e32 v73, v164, v251
	v_lshl_or_b32 v68, v2, 14, v1
	v_lshl_add_u32 v1, v2, 4, s34
	ds_read_b32 v2, v1
	ds_read2st64_b32 v[76:77], v70 offset1:16
	s_waitcnt lgkmcnt(0)
	v_fma_f32 v52, v52, v2, -v76
	v_fma_f32 v36, v36, v2, -v77
	ds_read2st64_b32 v[76:77], v70 offset0:32 offset1:48
	v_mul_f32_e32 v69, v36, v36
	v_fmac_f32_e32 v69, v52, v52
	s_waitcnt lgkmcnt(0)
	v_fma_f32 v20, v20, v2, -v76
	v_fmac_f32_e32 v69, v20, v20
	v_fma_f32 v2, v4, v2, -v77
	v_fmac_f32_e32 v69, v2, v2
	s_nop 1
	v_add_f32_dpp v4, v69, v69 quad_perm:[1,0,3,2] row_mask:0xf bank_mask:0xf
	s_nop 1
	v_add_f32_dpp v4, v4, v4 quad_perm:[2,3,0,1] row_mask:0xf bank_mask:0xf
	s_nop 1
	v_add_f32_dpp v4, v4, v4 row_half_mirror row_mask:0xf bank_mask:0xf
	s_nop 1
	v_add_f32_dpp v4, v4, v4 row_mirror row_mask:0xf bank_mask:0xf
	ds_swizzle_b32 v69, v4 offset:swizzle(SWAP,16)
	s_waitcnt lgkmcnt(0)
	v_add_f32_e32 v4, v4, v69
	v_fmamk_f32 v4, v4, 0x3c000000, v254
	v_cmp_gt_f32_e32 vcc, s90, v4
	v_mul_f32_e32 v69, 0x4f800000, v4
	s_nop 0
	v_cndmask_b32_e32 v4, v4, v69, vcc
	v_sqrt_f32_e32 v69, v4
	s_nop 0
	v_add_u32_e32 v75, -1, v69
	v_fma_f32 v76, -v75, v69, v4
	v_cmp_ge_f32_e64 s[4:5], 0, v76
	v_add_u32_e32 v76, 1, v69
	s_nop 0
	v_cndmask_b32_e64 v75, v69, v75, s[4:5]
	v_fma_f32 v69, -v76, v69, v4
	v_cmp_lt_f32_e64 s[4:5], 0, v69
	s_nop 1
	v_cndmask_b32_e64 v69, v75, v76, s[4:5]
	v_mul_f32_e32 v75, 0x37800000, v69
	v_cndmask_b32_e32 v69, v69, v75, vcc
	v_cmp_class_f32_e32 vcc, v4, v209
	s_nop 1
	v_cndmask_b32_e32 v4, v69, v4, vcc
	v_div_scale_f32 v69, s[4:5], v4, v4, 1.0
	v_rcp_f32_e32 v75, v69
	s_nop 0
	v_fma_f32 v76, -v69, v75, 1.0
	v_fmac_f32_e32 v75, v76, v75
	v_div_scale_f32 v76, vcc, 1.0, v4, 1.0
	v_mul_f32_e32 v77, v76, v75
	v_fma_f32 v78, -v69, v77, v76
	v_fmac_f32_e32 v77, v78, v75
	v_fma_f32 v69, -v69, v77, v76
	v_div_fmas_f32 v69, v69, v75, v77
	v_div_fixup_f32 v4, v69, v4, 1.0
	v_mul_f32_e32 v36, v36, v4
	v_mov_b32_e32 v69, v3
	v_mul_f32_e32 v52, v52, v4
	v_mul_f32_e32 v36, v74, v36
	v_lshl_add_u64 v[76:77], v[68:69], 1, s[6:7]
	v_mul_f32_e32 v52, v72, v52
	v_cvt_pk_bf16_f32 v36, v52, v36
	global_store_short v[76:77], v36, off
	v_add_u32_e32 v76, 32, v68
	v_mov_b32_e32 v77, v3
	v_lshl_add_u64 v[76:77], v[76:77], 1, s[6:7]
	global_store_short_d16_hi v[76:77], v36, off
	v_mul_f32_e32 v2, v2, v4
	v_add_u32_e32 v76, 64, v68
	v_mov_b32_e32 v77, v3
	v_mul_f32_e32 v20, v20, v4
	v_mul_f32_e32 v2, v73, v2
	v_lshl_add_u64 v[76:77], v[76:77], 1, s[6:7]
	v_mul_f32_e32 v20, v71, v20
	v_cvt_pk_bf16_f32 v2, v20, v2
	global_store_short v[76:77], v2, off
	v_add_u32_e32 v76, 0x60, v68
	v_mov_b32_e32 v77, v3
	v_lshl_add_u64 v[76:77], v[76:77], 1, s[6:7]
	global_store_short_d16_hi v[76:77], v2, off
	ds_read_b32 v2, v1 offset:4
	ds_read2st64_b32 v[76:77], v70 offset0:1 offset1:17
	s_waitcnt lgkmcnt(0)
	v_fma_f32 v52, v37, v2, -v77
	ds_read2st64_b32 v[36:37], v70 offset0:33 offset1:49
	v_fma_f32 v20, v53, v2, -v76
	v_mul_f32_e32 v4, v52, v52
	v_fmac_f32_e32 v4, v20, v20
	s_waitcnt lgkmcnt(0)
	v_fma_f32 v21, v21, v2, -v36
	v_fmac_f32_e32 v4, v21, v21
	v_fma_f32 v2, v5, v2, -v37
	v_fmac_f32_e32 v4, v2, v2
	ds_swizzle_b32 v5, v4 offset:swizzle(SWAP,1)
	s_waitcnt lgkmcnt(0)
	v_add_f32_e32 v4, v4, v5
	ds_swizzle_b32 v5, v4 offset:swizzle(SWAP,2)
	s_waitcnt lgkmcnt(0)
	v_add_f32_e32 v4, v4, v5
	ds_swizzle_b32 v5, v4 offset:swizzle(SWAP,4)
	s_waitcnt lgkmcnt(0)
	v_add_f32_e32 v4, v4, v5
	ds_swizzle_b32 v5, v4 offset:swizzle(SWAP,8)
	s_waitcnt lgkmcnt(0)
	v_add_f32_e32 v4, v4, v5
	ds_swizzle_b32 v5, v4 offset:swizzle(SWAP,16)
	s_waitcnt lgkmcnt(0)
	v_add_f32_e32 v4, v4, v5
	v_fmamk_f32 v4, v4, 0x3c000000, v254
	v_cmp_gt_f32_e32 vcc, s90, v4
	v_mul_f32_e32 v5, 0x4f800000, v4
	s_nop 0
	v_cndmask_b32_e32 v4, v4, v5, vcc
	v_sqrt_f32_e32 v5, v4
	s_nop 0
	v_add_u32_e32 v36, -1, v5
	v_fma_f32 v37, -v36, v5, v4
	v_cmp_ge_f32_e64 s[4:5], 0, v37
	v_add_u32_e32 v37, 1, v5
	s_nop 0
	v_cndmask_b32_e64 v36, v5, v36, s[4:5]
	v_fma_f32 v5, -v37, v5, v4
	v_cmp_lt_f32_e64 s[4:5], 0, v5
	s_nop 1
	v_cndmask_b32_e64 v5, v36, v37, s[4:5]
	v_mul_f32_e32 v36, 0x37800000, v5
	v_cndmask_b32_e32 v5, v5, v36, vcc
	v_cmp_class_f32_e32 vcc, v4, v209
	s_nop 1
	v_cndmask_b32_e32 v4, v5, v4, vcc
	v_div_scale_f32 v5, s[4:5], v4, v4, 1.0
	v_rcp_f32_e32 v36, v5
	s_nop 0
	v_fma_f32 v37, -v5, v36, 1.0
	v_fmac_f32_e32 v36, v37, v36
	v_div_scale_f32 v37, vcc, 1.0, v4, 1.0
	v_mul_f32_e32 v53, v37, v36
	v_fma_f32 v69, -v5, v53, v37
	v_fmac_f32_e32 v53, v69, v36
	v_fma_f32 v5, -v5, v53, v37
	v_div_fmas_f32 v5, v5, v36, v53
	v_div_fixup_f32 v36, v5, v4, 1.0
	v_mul_f32_e32 v5, v20, v36
	v_mul_f32_e32 v20, v52, v36
	v_mul_f32_e32 v5, v72, v5
	v_mul_f32_e32 v20, v74, v20
	v_add_u32_e32 v4, 0x1000, v68
	v_cvt_pk_bf16_f32 v20, v5, v20
	v_mov_b32_e32 v5, v3
	v_lshl_add_u64 v[4:5], v[4:5], 1, s[6:7]
	global_store_short v[4:5], v20, off
	v_add_u32_e32 v4, 0x1020, v68
	v_mov_b32_e32 v5, v3
	v_lshl_add_u64 v[4:5], v[4:5], 1, s[6:7]
	global_store_short_d16_hi v[4:5], v20, off
	v_mul_f32_e32 v4, v21, v36
	v_mul_f32_e32 v2, v2, v36
	v_mul_f32_e32 v4, v71, v4
	v_mul_f32_e32 v2, v73, v2
	v_cvt_pk_bf16_f32 v2, v4, v2
	v_add_u32_e32 v4, 0x1040, v68
	v_mov_b32_e32 v5, v3
	v_lshl_add_u64 v[4:5], v[4:5], 1, s[6:7]
	global_store_short v[4:5], v2, off
	v_add_u32_e32 v4, 0x1060, v68
	v_mov_b32_e32 v5, v3
	v_lshl_add_u64 v[4:5], v[4:5], 1, s[6:7]
	global_store_short_d16_hi v[4:5], v2, off
	ds_read_b32 v2, v1 offset:8
	ds_read2st64_b32 v[4:5], v70 offset0:2 offset1:18
	s_waitcnt lgkmcnt(0)
	v_fma_f32 v20, v54, v2, -v4
	v_fma_f32 v21, v38, v2, -v5
	ds_read2st64_b32 v[4:5], v70 offset0:34 offset1:50
	v_mul_f32_e32 v36, v21, v21
	v_fmac_f32_e32 v36, v20, v20
	s_waitcnt lgkmcnt(0)
	v_fma_f32 v22, v22, v2, -v4
	v_fmac_f32_e32 v36, v22, v22
	v_fma_f32 v2, v6, v2, -v5
	v_fmac_f32_e32 v36, v2, v2
	s_nop 1
	v_add_f32_dpp v4, v36, v36 quad_perm:[1,0,3,2] row_mask:0xf bank_mask:0xf
	s_nop 1
	v_add_f32_dpp v4, v4, v4 quad_perm:[2,3,0,1] row_mask:0xf bank_mask:0xf
	s_nop 1
	v_add_f32_dpp v4, v4, v4 row_half_mirror row_mask:0xf bank_mask:0xf
	s_nop 1
	v_add_f32_dpp v4, v4, v4 row_mirror row_mask:0xf bank_mask:0xf
	ds_swizzle_b32 v5, v4 offset:swizzle(SWAP,16)
	s_waitcnt lgkmcnt(0)
	v_add_f32_e32 v4, v4, v5
	v_fmamk_f32 v4, v4, 0x3c000000, v254
	v_rsq_f32_e32 v6, v4
	s_nop 0
	v_mul_f32_e32 v5, v20, v6
	v_mul_f32_e32 v20, v21, v6
	v_mul_f32_e32 v5, v72, v5
	v_mul_f32_e32 v20, v74, v20
	v_add_u32_e32 v4, 0x2000, v68
	v_cvt_pk_bf16_f32 v20, v5, v20
	v_mov_b32_e32 v5, v3
	v_lshl_add_u64 v[4:5], v[4:5], 1, s[6:7]
	global_store_short v[4:5], v20, off
	v_add_u32_e32 v4, 0x2020, v68
	v_mov_b32_e32 v5, v3
	v_lshl_add_u64 v[4:5], v[4:5], 1, s[6:7]
	global_store_short_d16_hi v[4:5], v20, off
	v_mul_f32_e32 v4, v22, v6
	v_mul_f32_e32 v2, v2, v6
	v_mul_f32_e32 v4, v71, v4
	v_mul_f32_e32 v2, v73, v2
	v_cvt_pk_bf16_f32 v2, v4, v2
	v_add_u32_e32 v4, 0x2040, v68
	v_mov_b32_e32 v5, v3
	v_lshl_add_u64 v[4:5], v[4:5], 1, s[6:7]
	global_store_short v[4:5], v2, off
	v_add_u32_e32 v4, 0x2060, v68
	v_mov_b32_e32 v5, v3
	v_lshl_add_u64 v[4:5], v[4:5], 1, s[6:7]
	global_store_short_d16_hi v[4:5], v2, off
	ds_read_b32 v2, v1 offset:12
	ds_read2st64_b32 v[4:5], v70 offset0:3 offset1:19
	s_waitcnt lgkmcnt(0)
	v_fma_f32 v6, v55, v2, -v4
	v_fma_f32 v20, v39, v2, -v5
	ds_read2st64_b32 v[4:5], v70 offset0:35 offset1:51
	v_mul_f32_e32 v21, v20, v20
	v_fmac_f32_e32 v21, v6, v6
	s_waitcnt lgkmcnt(0)
	v_fma_f32 v22, v23, v2, -v4
	v_fmac_f32_e32 v21, v22, v22
	v_fma_f32 v2, v7, v2, -v5
	v_fmac_f32_e32 v21, v2, v2
	s_nop 1
	v_add_f32_dpp v4, v21, v21 quad_perm:[1,0,3,2] row_mask:0xf bank_mask:0xf
	s_nop 1
	v_add_f32_dpp v4, v4, v4 quad_perm:[2,3,0,1] row_mask:0xf bank_mask:0xf
	s_nop 1
	v_add_f32_dpp v4, v4, v4 row_half_mirror row_mask:0xf bank_mask:0xf
	s_nop 1
	v_add_f32_dpp v4, v4, v4 row_mirror row_mask:0xf bank_mask:0xf
	ds_swizzle_b32 v5, v4 offset:swizzle(SWAP,16)
	s_waitcnt lgkmcnt(0)
	v_add_f32_e32 v4, v4, v5
	v_fmamk_f32 v4, v4, 0x3c000000, v254
	v_rsq_f32_e32 v7, v4
	s_nop 0
	v_mul_f32_e32 v5, v6, v7
	v_mul_f32_e32 v6, v20, v7
	v_mul_f32_e32 v5, v72, v5
	v_mul_f32_e32 v6, v74, v6
	v_add_u32_e32 v4, 0x3000, v68
	v_cvt_pk_bf16_f32 v6, v5, v6
	v_mov_b32_e32 v5, v3
	v_lshl_add_u64 v[4:5], v[4:5], 1, s[6:7]
	global_store_short v[4:5], v6, off
	v_add_u32_e32 v4, 0x3020, v68
	v_mov_b32_e32 v5, v3
	v_lshl_add_u64 v[4:5], v[4:5], 1, s[6:7]
	global_store_short_d16_hi v[4:5], v6, off
	v_mul_f32_e32 v4, v22, v7
	v_mul_f32_e32 v2, v2, v7
	v_mul_f32_e32 v4, v71, v4
	v_mul_f32_e32 v2, v73, v2
	v_cvt_pk_bf16_f32 v2, v4, v2
	v_add_u32_e32 v4, 0x3040, v68
	v_mov_b32_e32 v5, v3
	v_lshl_add_u64 v[4:5], v[4:5], 1, s[6:7]
	global_store_short v[4:5], v2, off
	v_add_u32_e32 v4, 0x3060, v68
	v_mov_b32_e32 v5, v3
	v_lshl_add_u64 v[4:5], v[4:5], 1, s[6:7]
	global_store_short_d16_hi v[4:5], v2, off
	ds_read_b32 v2, v1 offset:32
	ds_read2st64_b32 v[4:5], v70 offset0:4 offset1:20
	s_waitcnt lgkmcnt(0)
	v_fma_f32 v6, v56, v2, -v4
	v_fma_f32 v7, v40, v2, -v5
	ds_read2st64_b32 v[4:5], v70 offset0:36 offset1:52
	v_mul_f32_e32 v20, v7, v7
	v_fmac_f32_e32 v20, v6, v6
	s_waitcnt lgkmcnt(0)
	v_fma_f32 v21, v24, v2, -v4
	v_fmac_f32_e32 v20, v21, v21
	v_fma_f32 v2, v8, v2, -v5
	v_fmac_f32_e32 v20, v2, v2
	s_nop 1
	v_add_f32_dpp v4, v20, v20 quad_perm:[1,0,3,2] row_mask:0xf bank_mask:0xf
	s_nop 1
	v_add_f32_dpp v4, v4, v4 quad_perm:[2,3,0,1] row_mask:0xf bank_mask:0xf
	s_nop 1
	v_add_f32_dpp v4, v4, v4 row_half_mirror row_mask:0xf bank_mask:0xf
	s_nop 1
	v_add_f32_dpp v4, v4, v4 row_mirror row_mask:0xf bank_mask:0xf
	ds_swizzle_b32 v5, v4 offset:swizzle(SWAP,16)
	s_waitcnt lgkmcnt(0)
	v_add_f32_e32 v4, v4, v5
	v_fmamk_f32 v4, v4, 0x3c000000, v254
	v_rsq_f32_e32 v8, v4
	s_nop 0
	v_mul_f32_e32 v5, v6, v8
	v_mul_f32_e32 v6, v7, v8
	v_mul_f32_e32 v5, v72, v5
	v_mul_f32_e32 v6, v74, v6
	v_add_u32_e32 v4, 0x8000, v68
	v_cvt_pk_bf16_f32 v6, v5, v6
	v_mov_b32_e32 v5, v3
	v_lshl_add_u64 v[4:5], v[4:5], 1, s[6:7]
	global_store_short v[4:5], v6, off
	v_add_u32_e32 v4, 0x8020, v68
	v_mov_b32_e32 v5, v3
	v_lshl_add_u64 v[4:5], v[4:5], 1, s[6:7]
	global_store_short_d16_hi v[4:5], v6, off
	v_mul_f32_e32 v4, v21, v8
	v_mul_f32_e32 v2, v2, v8
	v_mul_f32_e32 v4, v71, v4
	v_mul_f32_e32 v2, v73, v2
	v_cvt_pk_bf16_f32 v2, v4, v2
	v_add_u32_e32 v4, 0x8040, v68
	v_mov_b32_e32 v5, v3
	v_lshl_add_u64 v[4:5], v[4:5], 1, s[6:7]
	global_store_short v[4:5], v2, off
	v_add_u32_e32 v4, 0x8060, v68
	v_mov_b32_e32 v5, v3
	v_lshl_add_u64 v[4:5], v[4:5], 1, s[6:7]
	global_store_short_d16_hi v[4:5], v2, off
	ds_read_b32 v2, v1 offset:36
	ds_read2st64_b32 v[4:5], v70 offset0:5 offset1:21
	s_waitcnt lgkmcnt(0)
	v_fma_f32 v6, v57, v2, -v4
	v_fma_f32 v7, v41, v2, -v5
	ds_read2st64_b32 v[4:5], v70 offset0:37 offset1:53
	v_mul_f32_e32 v8, v7, v7
	v_fmac_f32_e32 v8, v6, v6
	s_waitcnt lgkmcnt(0)
	v_fma_f32 v20, v25, v2, -v4
	v_fmac_f32_e32 v8, v20, v20
	v_fma_f32 v2, v9, v2, -v5
	v_fmac_f32_e32 v8, v2, v2
	s_nop 1
	v_add_f32_dpp v4, v8, v8 quad_perm:[1,0,3,2] row_mask:0xf bank_mask:0xf
	s_nop 1
	v_add_f32_dpp v4, v4, v4 quad_perm:[2,3,0,1] row_mask:0xf bank_mask:0xf
	s_nop 1
	v_add_f32_dpp v4, v4, v4 row_half_mirror row_mask:0xf bank_mask:0xf
	s_nop 1
	v_add_f32_dpp v4, v4, v4 row_mirror row_mask:0xf bank_mask:0xf
	ds_swizzle_b32 v5, v4 offset:swizzle(SWAP,16)
	s_waitcnt lgkmcnt(0)
	v_add_f32_e32 v4, v4, v5
	v_fmamk_f32 v4, v4, 0x3c000000, v254
	v_rsq_f32_e32 v8, v4
	s_nop 0
	v_mul_f32_e32 v5, v6, v8
	v_mul_f32_e32 v6, v7, v8
	v_mul_f32_e32 v5, v72, v5
	v_mul_f32_e32 v6, v74, v6
	v_add_u32_e32 v4, 0x9000, v68
	v_cvt_pk_bf16_f32 v6, v5, v6
	v_mov_b32_e32 v5, v3
	v_lshl_add_u64 v[4:5], v[4:5], 1, s[6:7]
	global_store_short v[4:5], v6, off
	v_add_u32_e32 v4, 0x9020, v68
	v_mov_b32_e32 v5, v3
	v_lshl_add_u64 v[4:5], v[4:5], 1, s[6:7]
	global_store_short_d16_hi v[4:5], v6, off
	v_mul_f32_e32 v4, v20, v8
	v_mul_f32_e32 v2, v2, v8
	v_mul_f32_e32 v4, v71, v4
	v_mul_f32_e32 v2, v73, v2
	v_cvt_pk_bf16_f32 v2, v4, v2
	v_add_u32_e32 v4, 0x9040, v68
	v_mov_b32_e32 v5, v3
	v_lshl_add_u64 v[4:5], v[4:5], 1, s[6:7]
	global_store_short v[4:5], v2, off
	v_add_u32_e32 v4, 0x9060, v68
	v_mov_b32_e32 v5, v3
	v_lshl_add_u64 v[4:5], v[4:5], 1, s[6:7]
	global_store_short_d16_hi v[4:5], v2, off
	ds_read_b32 v2, v1 offset:40
	ds_read2st64_b32 v[4:5], v70 offset0:6 offset1:22
	ds_read_b32 v84, v1 offset:44
	ds_read2st64_b32 v[86:87], v70 offset0:7 offset1:23
	s_waitcnt lgkmcnt(0)
	v_fma_f32 v6, v58, v2, -v4
	v_fma_f32 v7, v42, v2, -v5
	ds_read2st64_b32 v[4:5], v70 offset0:38 offset1:54
	v_mul_f32_e32 v8, v7, v7
	v_fmac_f32_e32 v8, v6, v6
	v_fma_f32 v88, v59, v84, -v86
	v_fma_f32 v89, v43, v84, -v87
	ds_read2st64_b32 v[86:87], v70 offset0:39 offset1:55
	v_mul_f32_e32 v90, v89, v89
	v_fmac_f32_e32 v90, v88, v88
	s_waitcnt lgkmcnt(0)
	v_fma_f32 v9, v26, v2, -v4
	v_fmac_f32_e32 v8, v9, v9
	v_fma_f32 v2, v10, v2, -v5
	v_fmac_f32_e32 v8, v2, v2
	s_nop 1
	v_add_f32_dpp v4, v8, v8 quad_perm:[1,0,3,2] row_mask:0xf bank_mask:0xf
	s_nop 1
	v_add_f32_dpp v4, v4, v4 quad_perm:[2,3,0,1] row_mask:0xf bank_mask:0xf
	s_nop 1
	v_add_f32_dpp v4, v4, v4 row_half_mirror row_mask:0xf bank_mask:0xf
	s_nop 1
	v_add_f32_dpp v4, v4, v4 row_mirror row_mask:0xf bank_mask:0xf
	ds_swizzle_b32 v5, v4 offset:swizzle(SWAP,16)
	v_fma_f32 v91, v27, v84, -v86
	v_fmac_f32_e32 v90, v91, v91
	v_fma_f32 v84, v11, v84, -v87
	v_fmac_f32_e32 v90, v84, v84
	s_nop 1
	v_add_f32_dpp v86, v90, v90 quad_perm:[1,0,3,2] row_mask:0xf bank_mask:0xf
	s_nop 1
	v_add_f32_dpp v86, v86, v86 quad_perm:[2,3,0,1] row_mask:0xf bank_mask:0xf
	s_nop 1
	v_add_f32_dpp v86, v86, v86 row_half_mirror row_mask:0xf bank_mask:0xf
	s_nop 1
	v_add_f32_dpp v86, v86, v86 row_mirror row_mask:0xf bank_mask:0xf
	ds_swizzle_b32 v87, v86 offset:swizzle(SWAP,16)
	s_waitcnt lgkmcnt(0)
	v_add_f32_e32 v4, v4, v5
	v_fmamk_f32 v4, v4, 0x3c000000, v254
	v_rsq_f32_e32 v8, v4
	s_nop 0
	v_mul_f32_e32 v5, v6, v8
	v_mul_f32_e32 v6, v7, v8
	v_mul_f32_e32 v5, v72, v5
	v_mul_f32_e32 v6, v74, v6
	v_add_u32_e32 v4, 0xa000, v68
	v_cvt_pk_bf16_f32 v6, v5, v6
	v_mov_b32_e32 v5, v3
	v_lshl_add_u64 v[4:5], v[4:5], 1, s[6:7]
	global_store_short v[4:5], v6, off
	v_add_u32_e32 v4, 0xa020, v68
	v_mov_b32_e32 v5, v3
	v_lshl_add_u64 v[4:5], v[4:5], 1, s[6:7]
	global_store_short_d16_hi v[4:5], v6, off
	v_mul_f32_e32 v4, v9, v8
	v_mul_f32_e32 v2, v2, v8
	v_mul_f32_e32 v4, v71, v4
	v_mul_f32_e32 v2, v73, v2
	v_cvt_pk_bf16_f32 v2, v4, v2
	v_add_u32_e32 v4, 0xa040, v68
	v_mov_b32_e32 v5, v3
	v_lshl_add_u64 v[4:5], v[4:5], 1, s[6:7]
	global_store_short v[4:5], v2, off
	v_add_u32_e32 v4, 0xa060, v68
	v_mov_b32_e32 v5, v3
	v_lshl_add_u64 v[4:5], v[4:5], 1, s[6:7]
	global_store_short_d16_hi v[4:5], v2, off
	v_add_f32_e32 v86, v86, v87
	v_fmamk_f32 v86, v86, 0x3c000000, v254
	v_rsq_f32_e32 v90, v86
	s_nop 0
	v_mul_f32_e32 v87, v88, v90
	v_mul_f32_e32 v88, v89, v90
	v_mul_f32_e32 v87, v72, v87
	v_mul_f32_e32 v88, v74, v88
	v_add_u32_e32 v86, 0xb000, v68
	v_cvt_pk_bf16_f32 v88, v87, v88
	v_mov_b32_e32 v87, v3
	v_lshl_add_u64 v[86:87], v[86:87], 1, s[6:7]
	global_store_short v[86:87], v88, off
	v_add_u32_e32 v86, 0xb020, v68
	v_mov_b32_e32 v87, v3
	v_lshl_add_u64 v[86:87], v[86:87], 1, s[6:7]
	global_store_short_d16_hi v[86:87], v88, off
	v_mul_f32_e32 v86, v91, v90
	v_mul_f32_e32 v84, v84, v90
	v_mul_f32_e32 v86, v71, v86
	v_mul_f32_e32 v84, v73, v84
	v_cvt_pk_bf16_f32 v84, v86, v84
	v_add_u32_e32 v86, 0xb040, v68
	v_mov_b32_e32 v87, v3
	v_lshl_add_u64 v[86:87], v[86:87], 1, s[6:7]
	global_store_short v[86:87], v84, off
	v_add_u32_e32 v86, 0xb060, v68
	v_mov_b32_e32 v87, v3
	v_lshl_add_u64 v[86:87], v[86:87], 1, s[6:7]
	global_store_short_d16_hi v[86:87], v84, off
	ds_read_b32 v2, v1 offset:64
	ds_read2st64_b32 v[4:5], v70 offset0:8 offset1:24
	ds_read_b32 v84, v1 offset:68
	ds_read2st64_b32 v[86:87], v70 offset0:9 offset1:25
	s_waitcnt lgkmcnt(0)
	v_fma_f32 v6, v60, v2, -v4
	v_fma_f32 v7, v44, v2, -v5
	ds_read2st64_b32 v[4:5], v70 offset0:40 offset1:56
	v_mul_f32_e32 v8, v7, v7
	v_fmac_f32_e32 v8, v6, v6
	v_fma_f32 v88, v61, v84, -v86
	v_fma_f32 v89, v45, v84, -v87
	ds_read2st64_b32 v[86:87], v70 offset0:41 offset1:57
	v_mul_f32_e32 v90, v89, v89
	v_fmac_f32_e32 v90, v88, v88
	s_waitcnt lgkmcnt(0)
	v_fma_f32 v9, v28, v2, -v4
	v_fmac_f32_e32 v8, v9, v9
	v_fma_f32 v2, v12, v2, -v5
	v_fmac_f32_e32 v8, v2, v2
	s_nop 1
	v_add_f32_dpp v4, v8, v8 quad_perm:[1,0,3,2] row_mask:0xf bank_mask:0xf
	s_nop 1
	v_add_f32_dpp v4, v4, v4 quad_perm:[2,3,0,1] row_mask:0xf bank_mask:0xf
	s_nop 1
	v_add_f32_dpp v4, v4, v4 row_half_mirror row_mask:0xf bank_mask:0xf
	s_nop 1
	v_add_f32_dpp v4, v4, v4 row_mirror row_mask:0xf bank_mask:0xf
	ds_swizzle_b32 v5, v4 offset:swizzle(SWAP,16)
	v_fma_f32 v91, v29, v84, -v86
	v_fmac_f32_e32 v90, v91, v91
	v_fma_f32 v84, v13, v84, -v87
	v_fmac_f32_e32 v90, v84, v84
	s_nop 1
	v_add_f32_dpp v86, v90, v90 quad_perm:[1,0,3,2] row_mask:0xf bank_mask:0xf
	s_nop 1
	v_add_f32_dpp v86, v86, v86 quad_perm:[2,3,0,1] row_mask:0xf bank_mask:0xf
	s_nop 1
	v_add_f32_dpp v86, v86, v86 row_half_mirror row_mask:0xf bank_mask:0xf
	s_nop 1
	v_add_f32_dpp v86, v86, v86 row_mirror row_mask:0xf bank_mask:0xf
	ds_swizzle_b32 v87, v86 offset:swizzle(SWAP,16)
	s_waitcnt lgkmcnt(0)
	v_add_f32_e32 v4, v4, v5
	v_fmamk_f32 v4, v4, 0x3c000000, v254
	v_rsq_f32_e32 v8, v4
	s_nop 0
	v_mul_f32_e32 v5, v6, v8
	v_mul_f32_e32 v6, v7, v8
	v_mul_f32_e32 v5, v72, v5
	v_mul_f32_e32 v6, v74, v6
	v_add_u32_e32 v4, 0x10000, v68
	v_cvt_pk_bf16_f32 v6, v5, v6
	v_mov_b32_e32 v5, v3
	v_lshl_add_u64 v[4:5], v[4:5], 1, s[6:7]
	global_store_short v[4:5], v6, off
	v_add_u32_e32 v4, 0x10020, v68
	v_mov_b32_e32 v5, v3
	v_lshl_add_u64 v[4:5], v[4:5], 1, s[6:7]
	global_store_short_d16_hi v[4:5], v6, off
	v_mul_f32_e32 v4, v9, v8
	v_mul_f32_e32 v2, v2, v8
	v_mul_f32_e32 v4, v71, v4
	v_mul_f32_e32 v2, v73, v2
	v_cvt_pk_bf16_f32 v2, v4, v2
	v_add_u32_e32 v4, 0x10040, v68
	v_mov_b32_e32 v5, v3
	v_lshl_add_u64 v[4:5], v[4:5], 1, s[6:7]
	global_store_short v[4:5], v2, off
	v_add_u32_e32 v4, 0x10060, v68
	v_mov_b32_e32 v5, v3
	v_lshl_add_u64 v[4:5], v[4:5], 1, s[6:7]
	global_store_short_d16_hi v[4:5], v2, off
	v_add_f32_e32 v86, v86, v87
	v_fmamk_f32 v86, v86, 0x3c000000, v254
	v_rsq_f32_e32 v90, v86
	s_nop 0
	v_mul_f32_e32 v87, v88, v90
	v_mul_f32_e32 v88, v89, v90
	v_mul_f32_e32 v87, v72, v87
	v_mul_f32_e32 v88, v74, v88
	v_add_u32_e32 v86, 0x11000, v68
	v_cvt_pk_bf16_f32 v88, v87, v88
	v_mov_b32_e32 v87, v3
	v_lshl_add_u64 v[86:87], v[86:87], 1, s[6:7]
	global_store_short v[86:87], v88, off
	v_add_u32_e32 v86, 0x11020, v68
	v_mov_b32_e32 v87, v3
	v_lshl_add_u64 v[86:87], v[86:87], 1, s[6:7]
	global_store_short_d16_hi v[86:87], v88, off
	v_mul_f32_e32 v86, v91, v90
	v_mul_f32_e32 v84, v84, v90
	v_mul_f32_e32 v86, v71, v86
	v_mul_f32_e32 v84, v73, v84
	v_cvt_pk_bf16_f32 v84, v86, v84
	v_add_u32_e32 v86, 0x11040, v68
	v_mov_b32_e32 v87, v3
	v_lshl_add_u64 v[86:87], v[86:87], 1, s[6:7]
	global_store_short v[86:87], v84, off
	v_add_u32_e32 v86, 0x11060, v68
	v_mov_b32_e32 v87, v3
	v_lshl_add_u64 v[86:87], v[86:87], 1, s[6:7]
	global_store_short_d16_hi v[86:87], v84, off
	ds_read_b32 v2, v1 offset:72
	ds_read2st64_b32 v[4:5], v70 offset0:10 offset1:26
	ds_read_b32 v84, v1 offset:76
	ds_read2st64_b32 v[86:87], v70 offset0:11 offset1:27
	s_waitcnt lgkmcnt(0)
	v_fma_f32 v6, v62, v2, -v4
	v_fma_f32 v7, v46, v2, -v5
	ds_read2st64_b32 v[4:5], v70 offset0:42 offset1:58
	v_mul_f32_e32 v8, v7, v7
	v_fmac_f32_e32 v8, v6, v6
	v_fma_f32 v88, v63, v84, -v86
	v_fma_f32 v89, v47, v84, -v87
	ds_read2st64_b32 v[86:87], v70 offset0:43 offset1:59
	v_mul_f32_e32 v90, v89, v89
	v_fmac_f32_e32 v90, v88, v88
	s_waitcnt lgkmcnt(0)
	v_fma_f32 v9, v30, v2, -v4
	v_fmac_f32_e32 v8, v9, v9
	v_fma_f32 v2, v14, v2, -v5
	v_fmac_f32_e32 v8, v2, v2
	s_nop 1
	v_add_f32_dpp v4, v8, v8 quad_perm:[1,0,3,2] row_mask:0xf bank_mask:0xf
	s_nop 1
	v_add_f32_dpp v4, v4, v4 quad_perm:[2,3,0,1] row_mask:0xf bank_mask:0xf
	s_nop 1
	v_add_f32_dpp v4, v4, v4 row_half_mirror row_mask:0xf bank_mask:0xf
	s_nop 1
	v_add_f32_dpp v4, v4, v4 row_mirror row_mask:0xf bank_mask:0xf
	ds_swizzle_b32 v5, v4 offset:swizzle(SWAP,16)
	v_fma_f32 v91, v31, v84, -v86
	v_fmac_f32_e32 v90, v91, v91
	v_fma_f32 v84, v15, v84, -v87
	v_fmac_f32_e32 v90, v84, v84
	s_nop 1
	v_add_f32_dpp v86, v90, v90 quad_perm:[1,0,3,2] row_mask:0xf bank_mask:0xf
	s_nop 1
	v_add_f32_dpp v86, v86, v86 quad_perm:[2,3,0,1] row_mask:0xf bank_mask:0xf
	s_nop 1
	v_add_f32_dpp v86, v86, v86 row_half_mirror row_mask:0xf bank_mask:0xf
	s_nop 1
	v_add_f32_dpp v86, v86, v86 row_mirror row_mask:0xf bank_mask:0xf
	ds_swizzle_b32 v87, v86 offset:swizzle(SWAP,16)
	s_waitcnt lgkmcnt(0)
	v_add_f32_e32 v4, v4, v5
	v_fmamk_f32 v4, v4, 0x3c000000, v254
	v_rsq_f32_e32 v8, v4
	s_nop 0
	v_mul_f32_e32 v5, v6, v8
	v_mul_f32_e32 v6, v7, v8
	v_mul_f32_e32 v5, v72, v5
	v_mul_f32_e32 v6, v74, v6
	v_add_u32_e32 v4, 0x12000, v68
	v_cvt_pk_bf16_f32 v6, v5, v6
	v_mov_b32_e32 v5, v3
	v_lshl_add_u64 v[4:5], v[4:5], 1, s[6:7]
	global_store_short v[4:5], v6, off
	v_add_u32_e32 v4, 0x12020, v68
	v_mov_b32_e32 v5, v3
	v_lshl_add_u64 v[4:5], v[4:5], 1, s[6:7]
	global_store_short_d16_hi v[4:5], v6, off
	v_mul_f32_e32 v4, v9, v8
	v_mul_f32_e32 v2, v2, v8
	v_mul_f32_e32 v4, v71, v4
	v_mul_f32_e32 v2, v73, v2
	v_cvt_pk_bf16_f32 v2, v4, v2
	v_add_u32_e32 v4, 0x12040, v68
	v_mov_b32_e32 v5, v3
	v_lshl_add_u64 v[4:5], v[4:5], 1, s[6:7]
	global_store_short v[4:5], v2, off
	v_add_u32_e32 v4, 0x12060, v68
	v_mov_b32_e32 v5, v3
	v_lshl_add_u64 v[4:5], v[4:5], 1, s[6:7]
	global_store_short_d16_hi v[4:5], v2, off
	v_add_f32_e32 v86, v86, v87
	v_fmamk_f32 v86, v86, 0x3c000000, v254
	v_rsq_f32_e32 v90, v86
	s_nop 0
	v_mul_f32_e32 v87, v88, v90
	v_mul_f32_e32 v88, v89, v90
	v_mul_f32_e32 v87, v72, v87
	v_mul_f32_e32 v88, v74, v88
	v_add_u32_e32 v86, 0x13000, v68
	v_cvt_pk_bf16_f32 v88, v87, v88
	v_mov_b32_e32 v87, v3
	v_lshl_add_u64 v[86:87], v[86:87], 1, s[6:7]
	global_store_short v[86:87], v88, off
	v_add_u32_e32 v86, 0x13020, v68
	v_mov_b32_e32 v87, v3
	v_lshl_add_u64 v[86:87], v[86:87], 1, s[6:7]
	global_store_short_d16_hi v[86:87], v88, off
	v_mul_f32_e32 v86, v91, v90
	v_mul_f32_e32 v84, v84, v90
	v_mul_f32_e32 v86, v71, v86
	v_mul_f32_e32 v84, v73, v84
	v_cvt_pk_bf16_f32 v84, v86, v84
	v_add_u32_e32 v86, 0x13040, v68
	v_mov_b32_e32 v87, v3
	v_lshl_add_u64 v[86:87], v[86:87], 1, s[6:7]
	global_store_short v[86:87], v84, off
	v_add_u32_e32 v86, 0x13060, v68
	v_mov_b32_e32 v87, v3
	v_lshl_add_u64 v[86:87], v[86:87], 1, s[6:7]
	global_store_short_d16_hi v[86:87], v84, off
	ds_read_b32 v2, v1 offset:96
	ds_read2st64_b32 v[4:5], v70 offset0:12 offset1:28
	ds_read_b32 v84, v1 offset:100
	ds_read2st64_b32 v[86:87], v70 offset0:13 offset1:29
	s_waitcnt lgkmcnt(0)
	v_fma_f32 v6, v64, v2, -v4
	v_fma_f32 v7, v48, v2, -v5
	ds_read2st64_b32 v[4:5], v70 offset0:44 offset1:60
	v_mul_f32_e32 v8, v7, v7
	v_fmac_f32_e32 v8, v6, v6
	v_fma_f32 v88, v65, v84, -v86
	v_fma_f32 v89, v49, v84, -v87
	ds_read2st64_b32 v[86:87], v70 offset0:45 offset1:61
	v_mul_f32_e32 v90, v89, v89
	v_fmac_f32_e32 v90, v88, v88
	s_waitcnt lgkmcnt(0)
	v_fma_f32 v9, v32, v2, -v4
	v_fmac_f32_e32 v8, v9, v9
	v_fma_f32 v2, v16, v2, -v5
	v_fmac_f32_e32 v8, v2, v2
	s_nop 1
	v_add_f32_dpp v4, v8, v8 quad_perm:[1,0,3,2] row_mask:0xf bank_mask:0xf
	s_nop 1
	v_add_f32_dpp v4, v4, v4 quad_perm:[2,3,0,1] row_mask:0xf bank_mask:0xf
	s_nop 1
	v_add_f32_dpp v4, v4, v4 row_half_mirror row_mask:0xf bank_mask:0xf
	s_nop 1
	v_add_f32_dpp v4, v4, v4 row_mirror row_mask:0xf bank_mask:0xf
	ds_swizzle_b32 v5, v4 offset:swizzle(SWAP,16)
	v_fma_f32 v91, v33, v84, -v86
	v_fmac_f32_e32 v90, v91, v91
	v_fma_f32 v84, v17, v84, -v87
	v_fmac_f32_e32 v90, v84, v84
	s_nop 1
	v_add_f32_dpp v86, v90, v90 quad_perm:[1,0,3,2] row_mask:0xf bank_mask:0xf
	s_nop 1
	v_add_f32_dpp v86, v86, v86 quad_perm:[2,3,0,1] row_mask:0xf bank_mask:0xf
	s_nop 1
	v_add_f32_dpp v86, v86, v86 row_half_mirror row_mask:0xf bank_mask:0xf
	s_nop 1
	v_add_f32_dpp v86, v86, v86 row_mirror row_mask:0xf bank_mask:0xf
	ds_swizzle_b32 v87, v86 offset:swizzle(SWAP,16)
	s_waitcnt lgkmcnt(0)
	v_add_f32_e32 v4, v4, v5
	v_fmamk_f32 v4, v4, 0x3c000000, v254
	v_rsq_f32_e32 v8, v4
	s_nop 0
	v_mul_f32_e32 v5, v6, v8
	v_mul_f32_e32 v6, v7, v8
	v_mul_f32_e32 v5, v72, v5
	v_mul_f32_e32 v6, v74, v6
	v_add_u32_e32 v4, 0x18000, v68
	v_cvt_pk_bf16_f32 v6, v5, v6
	v_mov_b32_e32 v5, v3
	v_lshl_add_u64 v[4:5], v[4:5], 1, s[6:7]
	global_store_short v[4:5], v6, off
	v_add_u32_e32 v4, 0x18020, v68
	v_mov_b32_e32 v5, v3
	v_lshl_add_u64 v[4:5], v[4:5], 1, s[6:7]
	global_store_short_d16_hi v[4:5], v6, off
	v_mul_f32_e32 v4, v9, v8
	v_mul_f32_e32 v2, v2, v8
	v_mul_f32_e32 v4, v71, v4
	v_mul_f32_e32 v2, v73, v2
	v_cvt_pk_bf16_f32 v2, v4, v2
	v_add_u32_e32 v4, 0x18040, v68
	v_mov_b32_e32 v5, v3
	v_lshl_add_u64 v[4:5], v[4:5], 1, s[6:7]
	global_store_short v[4:5], v2, off
	v_add_u32_e32 v4, 0x18060, v68
	v_mov_b32_e32 v5, v3
	v_lshl_add_u64 v[4:5], v[4:5], 1, s[6:7]
	global_store_short_d16_hi v[4:5], v2, off
	v_add_f32_e32 v86, v86, v87
	v_fmamk_f32 v86, v86, 0x3c000000, v254
	v_rsq_f32_e32 v90, v86
	s_nop 0
	v_mul_f32_e32 v87, v88, v90
	v_mul_f32_e32 v88, v89, v90
	v_mul_f32_e32 v87, v72, v87
	v_mul_f32_e32 v88, v74, v88
	v_add_u32_e32 v86, 0x19000, v68
	v_cvt_pk_bf16_f32 v88, v87, v88
	v_mov_b32_e32 v87, v3
	v_lshl_add_u64 v[86:87], v[86:87], 1, s[6:7]
	global_store_short v[86:87], v88, off
	v_add_u32_e32 v86, 0x19020, v68
	v_mov_b32_e32 v87, v3
	v_lshl_add_u64 v[86:87], v[86:87], 1, s[6:7]
	global_store_short_d16_hi v[86:87], v88, off
	v_mul_f32_e32 v86, v91, v90
	v_mul_f32_e32 v84, v84, v90
	v_mul_f32_e32 v86, v71, v86
	v_mul_f32_e32 v84, v73, v84
	v_cvt_pk_bf16_f32 v84, v86, v84
	v_add_u32_e32 v86, 0x19040, v68
	v_mov_b32_e32 v87, v3
	v_lshl_add_u64 v[86:87], v[86:87], 1, s[6:7]
	global_store_short v[86:87], v84, off
	v_add_u32_e32 v86, 0x19060, v68
	v_mov_b32_e32 v87, v3
	v_lshl_add_u64 v[86:87], v[86:87], 1, s[6:7]
	global_store_short_d16_hi v[86:87], v84, off
	ds_read_b32 v2, v1 offset:104
	ds_read2st64_b32 v[4:5], v70 offset0:14 offset1:30
	s_waitcnt lgkmcnt(0)
	v_fma_f32 v6, v66, v2, -v4
	v_fma_f32 v7, v50, v2, -v5
	ds_read2st64_b32 v[4:5], v70 offset0:46 offset1:62
	v_mul_f32_e32 v8, v7, v7
	v_fmac_f32_e32 v8, v6, v6
	s_waitcnt lgkmcnt(0)
	v_fma_f32 v9, v34, v2, -v4
	v_fmac_f32_e32 v8, v9, v9
	v_fma_f32 v2, v18, v2, -v5
	v_fmac_f32_e32 v8, v2, v2
	s_nop 1
	v_add_f32_dpp v4, v8, v8 quad_perm:[1,0,3,2] row_mask:0xf bank_mask:0xf
	s_nop 1
	v_add_f32_dpp v4, v4, v4 quad_perm:[2,3,0,1] row_mask:0xf bank_mask:0xf
	s_nop 1
	v_add_f32_dpp v4, v4, v4 row_half_mirror row_mask:0xf bank_mask:0xf
	s_nop 1
	v_add_f32_dpp v4, v4, v4 row_mirror row_mask:0xf bank_mask:0xf
	ds_swizzle_b32 v5, v4 offset:swizzle(SWAP,16)
	s_waitcnt lgkmcnt(0)
	v_add_f32_e32 v4, v4, v5
	v_fmamk_f32 v4, v4, 0x3c000000, v254
	v_cmp_gt_f32_e32 vcc, s90, v4
	v_mul_f32_e32 v5, 0x4f800000, v4
	s_nop 0
	v_cndmask_b32_e32 v4, v4, v5, vcc
	v_sqrt_f32_e32 v5, v4
	s_nop 0
	v_add_u32_e32 v8, -1, v5
	v_fma_f32 v10, -v8, v5, v4
	v_cmp_ge_f32_e64 s[4:5], 0, v10
	v_add_u32_e32 v10, 1, v5
	s_nop 0
	v_cndmask_b32_e64 v8, v5, v8, s[4:5]
	v_fma_f32 v5, -v10, v5, v4
	v_cmp_lt_f32_e64 s[4:5], 0, v5
	s_nop 1
	v_cndmask_b32_e64 v5, v8, v10, s[4:5]
	v_mul_f32_e32 v8, 0x37800000, v5
	v_cndmask_b32_e32 v5, v5, v8, vcc
	v_cmp_class_f32_e32 vcc, v4, v209
	s_nop 1
	v_cndmask_b32_e32 v4, v5, v4, vcc
	v_div_scale_f32 v5, s[4:5], v4, v4, 1.0
	v_rcp_f32_e32 v8, v5
	s_nop 0
	v_fma_f32 v10, -v5, v8, 1.0
	v_fmac_f32_e32 v8, v10, v8
	v_div_scale_f32 v10, vcc, 1.0, v4, 1.0
	v_mul_f32_e32 v11, v10, v8
	v_fma_f32 v12, -v5, v11, v10
	v_fmac_f32_e32 v11, v12, v8
	v_fma_f32 v5, -v5, v11, v10
	v_div_fmas_f32 v5, v5, v8, v11
	v_div_fixup_f32 v8, v5, v4, 1.0
	v_mul_f32_e32 v5, v6, v8
	v_mul_f32_e32 v6, v7, v8
	v_mul_f32_e32 v5, v72, v5
	v_mul_f32_e32 v6, v74, v6
	v_add_u32_e32 v4, 0x1a000, v68
	v_cvt_pk_bf16_f32 v6, v5, v6
	v_mov_b32_e32 v5, v3
	v_lshl_add_u64 v[4:5], v[4:5], 1, s[6:7]
	global_store_short v[4:5], v6, off
	v_add_u32_e32 v4, 0x1a020, v68
	v_mov_b32_e32 v5, v3
	v_lshl_add_u64 v[4:5], v[4:5], 1, s[6:7]
	global_store_short_d16_hi v[4:5], v6, off
	v_mul_f32_e32 v4, v9, v8
	v_mul_f32_e32 v2, v2, v8
	v_mul_f32_e32 v4, v71, v4
	v_mul_f32_e32 v2, v73, v2
	v_cvt_pk_bf16_f32 v2, v4, v2
	v_add_u32_e32 v4, 0x1a040, v68
	v_mov_b32_e32 v5, v3
	v_lshl_add_u64 v[4:5], v[4:5], 1, s[6:7]
	global_store_short v[4:5], v2, off
	v_add_u32_e32 v4, 0x1a060, v68
	v_mov_b32_e32 v5, v3
	v_lshl_add_u64 v[4:5], v[4:5], 1, s[6:7]
	global_store_short_d16_hi v[4:5], v2, off
	ds_read_b32 v1, v1 offset:108
	ds_read2st64_b32 v[4:5], v70 offset0:15 offset1:31
	s_waitcnt lgkmcnt(0)
	v_fma_f32 v2, v67, v1, -v4
	v_fma_f32 v6, v51, v1, -v5
	ds_read2st64_b32 v[4:5], v70 offset0:47 offset1:63
	v_mul_f32_e32 v7, v6, v6
	v_fmac_f32_e32 v7, v2, v2
	s_waitcnt lgkmcnt(0)
	v_fma_f32 v8, v35, v1, -v4
	v_fmac_f32_e32 v7, v8, v8
	v_fma_f32 v1, v19, v1, -v5
	v_fmac_f32_e32 v7, v1, v1
	s_nop 1
	v_add_f32_dpp v4, v7, v7 quad_perm:[1,0,3,2] row_mask:0xf bank_mask:0xf
	s_nop 1
	v_add_f32_dpp v4, v4, v4 quad_perm:[2,3,0,1] row_mask:0xf bank_mask:0xf
	s_nop 1
	v_add_f32_dpp v4, v4, v4 row_half_mirror row_mask:0xf bank_mask:0xf
	s_nop 1
	v_add_f32_dpp v4, v4, v4 row_mirror row_mask:0xf bank_mask:0xf
	ds_swizzle_b32 v5, v4 offset:swizzle(SWAP,16)
	s_waitcnt lgkmcnt(0)
	v_add_f32_e32 v4, v4, v5
	v_fmamk_f32 v4, v4, 0x3c000000, v254
	v_cmp_gt_f32_e32 vcc, s90, v4
	v_mul_f32_e32 v5, 0x4f800000, v4
	s_nop 0
	v_cndmask_b32_e32 v4, v4, v5, vcc
	v_sqrt_f32_e32 v5, v4
	s_nop 0
	v_add_u32_e32 v7, -1, v5
	v_fma_f32 v9, -v7, v5, v4
	v_cmp_ge_f32_e64 s[4:5], 0, v9
	v_add_u32_e32 v9, 1, v5
	s_nop 0
	v_cndmask_b32_e64 v7, v5, v7, s[4:5]
	v_fma_f32 v5, -v9, v5, v4
	v_cmp_lt_f32_e64 s[4:5], 0, v5
	s_nop 1
	v_cndmask_b32_e64 v5, v7, v9, s[4:5]
	v_mul_f32_e32 v7, 0x37800000, v5
	v_cndmask_b32_e32 v5, v5, v7, vcc
	v_cmp_class_f32_e32 vcc, v4, v209
	s_nop 1
	v_cndmask_b32_e32 v4, v5, v4, vcc
	v_div_scale_f32 v5, s[4:5], v4, v4, 1.0
	v_rcp_f32_e32 v7, v5
	s_nop 0
	v_fma_f32 v9, -v5, v7, 1.0
	v_fmac_f32_e32 v7, v9, v7
	v_div_scale_f32 v9, vcc, 1.0, v4, 1.0
	v_mul_f32_e32 v10, v9, v7
	v_fma_f32 v11, -v5, v10, v9
	v_fmac_f32_e32 v10, v11, v7
	v_fma_f32 v5, -v5, v10, v9
	v_div_fmas_f32 v5, v5, v7, v10
	v_div_fixup_f32 v7, v5, v4, 1.0
	v_mul_f32_e32 v2, v2, v7
	v_mul_f32_e32 v5, v6, v7
	v_mul_f32_e32 v2, v72, v2
	v_mul_f32_e32 v5, v74, v5
	v_add_u32_e32 v4, 0x1b000, v68
	v_cvt_pk_bf16_f32 v2, v2, v5
	v_mov_b32_e32 v5, v3
	v_lshl_add_u64 v[4:5], v[4:5], 1, s[6:7]
	global_store_short v[4:5], v2, off
	v_add_u32_e32 v4, 0x1b020, v68
	v_mov_b32_e32 v5, v3
	v_lshl_add_u64 v[4:5], v[4:5], 1, s[6:7]
	global_store_short_d16_hi v[4:5], v2, off
	v_mul_f32_e32 v1, v1, v7
	v_add_u32_e32 v4, 0x1b040, v68
	v_mov_b32_e32 v5, v3
	v_mul_f32_e32 v2, v8, v7
	v_mul_f32_e32 v1, v73, v1
	v_lshl_add_u64 v[4:5], v[4:5], 1, s[6:7]
	v_mul_f32_e32 v2, v71, v2
	v_cvt_pk_bf16_f32 v1, v2, v1
	global_store_short v[4:5], v1, off
	v_add_u32_e32 v4, 0x1b060, v68
	v_mov_b32_e32 v5, v3
	v_lshl_add_u64 v[4:5], v[4:5], 1, s[6:7]
	global_store_short_d16_hi v[4:5], v1, off

.LBB0_1653:
	s_or_b64 exec, exec, s[4:5]
	s_waitcnt lgkmcnt(0)
	v_add_u32_e32 v4, s46, v148
	ds_read_b32 v20, v4
	ds_read_b32 v21, v4 offset:4
	ds_read_b32 v22, v4 offset:8
	ds_read_b32 v23, v4 offset:12
	ds_read_b32 v24, v4 offset:32
	ds_read_b32 v25, v4 offset:36
	ds_read_b32 v26, v4 offset:40
	ds_read_b32 v27, v4 offset:44
	ds_read_b32 v28, v4 offset:64
	ds_read_b32 v29, v4 offset:68
	ds_read_b32 v30, v4 offset:72
	ds_read_b32 v31, v4 offset:76
	ds_read_b32 v32, v4 offset:96
	ds_read_b32 v33, v4 offset:100
	ds_read_b32 v34, v4 offset:104
	ds_read_b32 v35, v4 offset:108
	s_waitcnt lgkmcnt(0)
	v_mul_f32_e32 v6, v68, v20
	ds_write_b32 v1, v6
	v_mul_f32_e32 v6, v100, v20
	ds_write_b32 v1, v6 offset:4096
	v_mul_f32_e32 v6, v116, v20
	v_mul_f32_e32 v20, v132, v20
	ds_write_b32 v1, v6 offset:8192
	ds_write_b32 v1, v20 offset:12288
	v_mul_f32_e32 v6, v69, v21
	ds_write_b32 v1, v6 offset:256
	v_mul_f32_e32 v6, v101, v21
	ds_write_b32 v1, v6 offset:4352
	v_mul_f32_e32 v6, v117, v21
	v_mul_f32_e32 v21, v133, v21
	ds_write_b32 v1, v6 offset:8448
	ds_write_b32 v1, v21 offset:12544
	v_mul_f32_e32 v6, v70, v22
	ds_write_b32 v1, v6 offset:512
	v_mul_f32_e32 v6, v102, v22
	ds_write_b32 v1, v6 offset:4608
	v_mul_f32_e32 v6, v118, v22
	v_mul_f32_e32 v22, v134, v22
	ds_write_b32 v1, v6 offset:8704
	ds_write_b32 v1, v22 offset:12800
	v_mul_f32_e32 v6, v71, v23
	ds_write_b32 v1, v6 offset:768
	v_mul_f32_e32 v6, v103, v23
	ds_write_b32 v1, v6 offset:4864
	v_mul_f32_e32 v6, v119, v23
	v_mul_f32_e32 v23, v135, v23
	ds_write_b32 v1, v6 offset:8960
	ds_write_b32 v1, v23 offset:13056
	v_mul_f32_e32 v6, v72, v24
	ds_write_b32 v1, v6 offset:1024
	v_mul_f32_e32 v6, v104, v24
	ds_write_b32 v1, v6 offset:5120
	v_mul_f32_e32 v6, v120, v24
	v_mul_f32_e32 v24, v136, v24
	ds_write_b32 v1, v6 offset:9216
	ds_write_b32 v1, v24 offset:13312
	v_mul_f32_e32 v6, v73, v25
	ds_write_b32 v1, v6 offset:1280
	v_mul_f32_e32 v6, v105, v25
	ds_write_b32 v1, v6 offset:5376
	v_mul_f32_e32 v6, v121, v25
	v_mul_f32_e32 v25, v137, v25
	ds_write_b32 v1, v6 offset:9472
	ds_write_b32 v1, v25 offset:13568
	v_mul_f32_e32 v6, v74, v26
	ds_write_b32 v1, v6 offset:1536
	v_mul_f32_e32 v6, v106, v26
	ds_write_b32 v1, v6 offset:5632
	v_mul_f32_e32 v6, v122, v26
	v_mul_f32_e32 v26, v138, v26
	ds_write_b32 v1, v6 offset:9728
	ds_write_b32 v1, v26 offset:13824
	v_mul_f32_e32 v6, v75, v27
	ds_write_b32 v1, v6 offset:1792
	v_mul_f32_e32 v6, v107, v27
	ds_write_b32 v1, v6 offset:5888
	v_mul_f32_e32 v6, v123, v27
	v_mul_f32_e32 v27, v139, v27
	ds_write_b32 v1, v6 offset:9984
	ds_write_b32 v1, v27 offset:14080
	v_mul_f32_e32 v6, v76, v28
	ds_write_b32 v1, v6 offset:2048
	v_mul_f32_e32 v6, v108, v28
	ds_write_b32 v1, v6 offset:6144
	v_mul_f32_e32 v6, v124, v28
	v_mul_f32_e32 v28, v140, v28
	ds_write_b32 v1, v6 offset:10240
	ds_write_b32 v1, v28 offset:14336
	v_mul_f32_e32 v6, v77, v29
	ds_write_b32 v1, v6 offset:2304
	v_mul_f32_e32 v6, v109, v29
	ds_write_b32 v1, v6 offset:6400
	v_mul_f32_e32 v6, v125, v29
	v_mul_f32_e32 v29, v141, v29
	ds_write_b32 v1, v6 offset:10496
	ds_write_b32 v1, v29 offset:14592
	v_mul_f32_e32 v6, v78, v30
	ds_write_b32 v1, v6 offset:2560
	v_mul_f32_e32 v6, v110, v30
	ds_write_b32 v1, v6 offset:6656
	v_mul_f32_e32 v6, v126, v30
	v_mul_f32_e32 v30, v142, v30
	ds_write_b32 v1, v6 offset:10752
	ds_write_b32 v1, v30 offset:14848
	v_mul_f32_e32 v6, v79, v31
	ds_write_b32 v1, v6 offset:2816
	v_mul_f32_e32 v6, v111, v31
	ds_write_b32 v1, v6 offset:6912
	v_mul_f32_e32 v6, v127, v31
	v_mul_f32_e32 v31, v143, v31
	ds_write_b32 v1, v6 offset:11008
	ds_write_b32 v1, v31 offset:15104
	v_mul_f32_e32 v6, v80, v32
	ds_write_b32 v1, v6 offset:3072
	v_mul_f32_e32 v6, v112, v32
	ds_write_b32 v1, v6 offset:7168
	v_mul_f32_e32 v6, v128, v32
	v_mul_f32_e32 v32, v144, v32
	ds_write_b32 v1, v6 offset:11264
	ds_write_b32 v1, v32 offset:15360
	v_mul_f32_e32 v6, v81, v33
	ds_write_b32 v1, v6 offset:3328
	v_mul_f32_e32 v6, v113, v33
	ds_write_b32 v1, v6 offset:7424
	v_mul_f32_e32 v6, v129, v33
	v_mul_f32_e32 v33, v145, v33
	ds_write_b32 v1, v6 offset:11520
	ds_write_b32 v1, v33 offset:15616
	v_mul_f32_e32 v6, v82, v34
	ds_write_b32 v1, v6 offset:3584
	v_mul_f32_e32 v6, v114, v34
	ds_write_b32 v1, v6 offset:7680
	v_mul_f32_e32 v6, v130, v34
	v_mul_f32_e32 v34, v146, v34
	ds_write_b32 v1, v6 offset:11776
	ds_write_b32 v1, v34 offset:15872
	v_mul_f32_e32 v5, v83, v35
	ds_write_b32 v1, v5 offset:3840
	v_mul_f32_e32 v5, v115, v35
	ds_write_b32 v1, v5 offset:7936
	v_mul_f32_e32 v5, v131, v35
	v_mul_f32_e32 v35, v147, v35
	ds_write_b32 v1, v5 offset:12032
	ds_write_b32 v1, v35 offset:16128
	v_mov_b32_e32 v5, v34
	v_mov_b32_e32 v4, v35

.LBB0_1657:
	s_or_b64 exec, exec, s[4:5]
	s_waitcnt lgkmcnt(0)
	v_lshlrev_b32_e32 v2, 2, v158
	global_load_dword v248, v2, s[0:1]
	global_load_dword v249, v2, s[0:1] offset:128
	global_load_dword v250, v2, s[0:1] offset:256
	global_load_dword v251, v2, s[0:1] offset:384
	v_add_u32_e32 v8, s46, v148
	s_lshl_b64 s[4:5], s[26:27], 13
	s_add_u32 s6, s86, s4
	s_addc_u32 s7, s87, s5
	s_waitcnt vmcnt(0)
	v_mul_f32_e32 v5, v164, v248
	v_mul_f32_e32 v7, v164, v249
	v_mul_f32_e32 v4, v164, v250
	v_mul_f32_e32 v6, v164, v251
	v_lshl_or_b32 v2, v159, 14, v158
	ds_read_b32 v9, v8
	ds_read2st64_b32 v[10:11], v1 offset1:16
	ds_read_b32 v21, v8 offset:4
	ds_read2st64_b32 v[22:23], v1 offset0:1 offset1:17
	s_waitcnt lgkmcnt(0)
	v_fma_f32 v12, v68, v9, -v10
	v_fma_f32 v13, v100, v9, -v11
	ds_read2st64_b32 v[10:11], v1 offset0:32 offset1:48
	v_mul_f32_e32 v14, v13, v13
	v_fmac_f32_e32 v14, v12, v12
	v_fma_f32 v24, v69, v21, -v22
	v_fma_f32 v25, v101, v21, -v23
	ds_read2st64_b32 v[22:23], v1 offset0:33 offset1:49
	v_mul_f32_e32 v26, v25, v25
	v_fmac_f32_e32 v26, v24, v24
	s_waitcnt lgkmcnt(0)
	v_fma_f32 v15, v116, v9, -v10
	v_fmac_f32_e32 v14, v15, v15
	v_fma_f32 v9, v132, v9, -v11
	v_fmac_f32_e32 v14, v9, v9
	s_nop 1
	v_add_f32_dpp v10, v14, v14 quad_perm:[1,0,3,2] row_mask:0xf bank_mask:0xf
	s_nop 1
	v_add_f32_dpp v10, v10, v10 quad_perm:[2,3,0,1] row_mask:0xf bank_mask:0xf
	s_nop 1
	v_add_f32_dpp v10, v10, v10 row_half_mirror row_mask:0xf bank_mask:0xf
	s_nop 1
	v_add_f32_dpp v10, v10, v10 row_mirror row_mask:0xf bank_mask:0xf
	ds_swizzle_b32 v11, v10 offset:swizzle(SWAP,16)
	v_fma_f32 v27, v117, v21, -v22
	v_fmac_f32_e32 v26, v27, v27
	v_fma_f32 v21, v133, v21, -v23
	v_fmac_f32_e32 v26, v21, v21
	s_nop 1
	v_add_f32_dpp v22, v26, v26 quad_perm:[1,0,3,2] row_mask:0xf bank_mask:0xf
	s_nop 1
	v_add_f32_dpp v22, v22, v22 quad_perm:[2,3,0,1] row_mask:0xf bank_mask:0xf
	s_nop 1
	v_add_f32_dpp v22, v22, v22 row_half_mirror row_mask:0xf bank_mask:0xf
	s_nop 1
	v_add_f32_dpp v22, v22, v22 row_mirror row_mask:0xf bank_mask:0xf
	ds_swizzle_b32 v23, v22 offset:swizzle(SWAP,16)
	s_waitcnt lgkmcnt(0)
	v_add_f32_e32 v10, v10, v11
	v_fmamk_f32 v10, v10, 0x3c000000, v254
	v_rsq_f32_e32 v14, v10
	s_nop 0
	v_mul_f32_e32 v10, v12, v14
	v_mul_f32_e32 v11, v13, v14
	v_mul_f32_e32 v10, v5, v10
	v_mul_f32_e32 v11, v7, v11
	v_cvt_pk_bf16_f32 v12, v10, v11
	v_lshl_add_u64 v[10:11], v[2:3], 1, s[6:7]
	global_store_short v[10:11], v12, off offset:768
	v_add_u32_e32 v10, 32, v2
	v_mov_b32_e32 v11, v3
	v_lshl_add_u64 v[10:11], v[10:11], 1, s[6:7]
	global_store_short_d16_hi v[10:11], v12, off offset:768
	v_mul_f32_e32 v10, v15, v14
	v_mul_f32_e32 v9, v9, v14
	v_mul_f32_e32 v10, v4, v10
	v_mul_f32_e32 v9, v6, v9
	v_cvt_pk_bf16_f32 v9, v10, v9
	v_add_u32_e32 v10, 64, v2
	v_mov_b32_e32 v11, v3
	v_lshl_add_u64 v[10:11], v[10:11], 1, s[6:7]
	global_store_short v[10:11], v9, off offset:768
	v_add_u32_e32 v10, 0x60, v2
	v_mov_b32_e32 v11, v3
	v_lshl_add_u64 v[10:11], v[10:11], 1, s[6:7]
	global_store_short_d16_hi v[10:11], v9, off offset:768
	v_add_f32_e32 v22, v22, v23
	v_fmamk_f32 v22, v22, 0x3c000000, v254
	v_rsq_f32_e32 v26, v22
	s_nop 0
	v_mul_f32_e32 v23, v24, v26
	v_mul_f32_e32 v24, v25, v26
	v_mul_f32_e32 v23, v5, v23
	v_mul_f32_e32 v24, v7, v24
	v_add_u32_e32 v22, 0x1000, v2
	v_cvt_pk_bf16_f32 v24, v23, v24
	v_mov_b32_e32 v23, v3
	v_lshl_add_u64 v[22:23], v[22:23], 1, s[6:7]
	global_store_short v[22:23], v24, off offset:768
	v_add_u32_e32 v22, 0x1020, v2
	v_mov_b32_e32 v23, v3
	v_lshl_add_u64 v[22:23], v[22:23], 1, s[6:7]
	global_store_short_d16_hi v[22:23], v24, off offset:768
	v_mul_f32_e32 v22, v27, v26
	v_mul_f32_e32 v21, v21, v26
	v_mul_f32_e32 v22, v4, v22
	v_mul_f32_e32 v21, v6, v21
	v_cvt_pk_bf16_f32 v21, v22, v21
	v_add_u32_e32 v22, 0x1040, v2
	v_mov_b32_e32 v23, v3
	v_lshl_add_u64 v[22:23], v[22:23], 1, s[6:7]
	global_store_short v[22:23], v21, off offset:768
	v_add_u32_e32 v22, 0x1060, v2
	v_mov_b32_e32 v23, v3
	v_lshl_add_u64 v[22:23], v[22:23], 1, s[6:7]
	global_store_short_d16_hi v[22:23], v21, off offset:768
	ds_read_b32 v9, v8 offset:8
	ds_read2st64_b32 v[10:11], v1 offset0:2 offset1:18
	ds_read_b32 v21, v8 offset:12
	ds_read2st64_b32 v[22:23], v1 offset0:3 offset1:19
	s_waitcnt lgkmcnt(0)
	v_fma_f32 v12, v70, v9, -v10
	v_fma_f32 v13, v102, v9, -v11
	ds_read2st64_b32 v[10:11], v1 offset0:34 offset1:50
	v_mul_f32_e32 v14, v13, v13
	v_fmac_f32_e32 v14, v12, v12
	v_fma_f32 v24, v71, v21, -v22
	v_fma_f32 v25, v103, v21, -v23
	ds_read2st64_b32 v[22:23], v1 offset0:35 offset1:51
	v_mul_f32_e32 v26, v25, v25
	v_fmac_f32_e32 v26, v24, v24
	s_waitcnt lgkmcnt(0)
	v_fma_f32 v15, v118, v9, -v10
	v_fmac_f32_e32 v14, v15, v15
	v_fma_f32 v9, v134, v9, -v11
	v_fmac_f32_e32 v14, v9, v9
	s_nop 1
	v_add_f32_dpp v10, v14, v14 quad_perm:[1,0,3,2] row_mask:0xf bank_mask:0xf
	s_nop 1
	v_add_f32_dpp v10, v10, v10 quad_perm:[2,3,0,1] row_mask:0xf bank_mask:0xf
	s_nop 1
	v_add_f32_dpp v10, v10, v10 row_half_mirror row_mask:0xf bank_mask:0xf
	s_nop 1
	v_add_f32_dpp v10, v10, v10 row_mirror row_mask:0xf bank_mask:0xf
	ds_swizzle_b32 v11, v10 offset:swizzle(SWAP,16)
	v_fma_f32 v27, v119, v21, -v22
	v_fmac_f32_e32 v26, v27, v27
	v_fma_f32 v21, v135, v21, -v23
	v_fmac_f32_e32 v26, v21, v21
	s_nop 1
	v_add_f32_dpp v22, v26, v26 quad_perm:[1,0,3,2] row_mask:0xf bank_mask:0xf
	s_nop 1
	v_add_f32_dpp v22, v22, v22 quad_perm:[2,3,0,1] row_mask:0xf bank_mask:0xf
	s_nop 1
	v_add_f32_dpp v22, v22, v22 row_half_mirror row_mask:0xf bank_mask:0xf
	s_nop 1
	v_add_f32_dpp v22, v22, v22 row_mirror row_mask:0xf bank_mask:0xf
	ds_swizzle_b32 v23, v22 offset:swizzle(SWAP,16)
	s_waitcnt lgkmcnt(0)
	v_add_f32_e32 v10, v10, v11
	v_fmamk_f32 v10, v10, 0x3c000000, v254
	v_rsq_f32_e32 v14, v10
	s_nop 0
	v_mul_f32_e32 v11, v12, v14
	v_mul_f32_e32 v12, v13, v14
	v_mul_f32_e32 v11, v5, v11
	v_mul_f32_e32 v12, v7, v12
	v_add_u32_e32 v10, 0x2000, v2
	v_cvt_pk_bf16_f32 v12, v11, v12
	v_mov_b32_e32 v11, v3
	v_lshl_add_u64 v[10:11], v[10:11], 1, s[6:7]
	global_store_short v[10:11], v12, off offset:768
	v_add_u32_e32 v10, 0x2020, v2
	v_mov_b32_e32 v11, v3
	v_lshl_add_u64 v[10:11], v[10:11], 1, s[6:7]
	global_store_short_d16_hi v[10:11], v12, off offset:768
	v_mul_f32_e32 v10, v15, v14
	v_mul_f32_e32 v9, v9, v14
	v_mul_f32_e32 v10, v4, v10
	v_mul_f32_e32 v9, v6, v9
	v_cvt_pk_bf16_f32 v9, v10, v9
	v_add_u32_e32 v10, 0x2040, v2
	v_mov_b32_e32 v11, v3
	v_lshl_add_u64 v[10:11], v[10:11], 1, s[6:7]
	global_store_short v[10:11], v9, off offset:768
	v_add_u32_e32 v10, 0x2060, v2
	v_mov_b32_e32 v11, v3
	v_lshl_add_u64 v[10:11], v[10:11], 1, s[6:7]
	global_store_short_d16_hi v[10:11], v9, off offset:768
	v_add_f32_e32 v22, v22, v23
	v_fmamk_f32 v22, v22, 0x3c000000, v254
	v_rsq_f32_e32 v26, v22
	s_nop 0
	v_mul_f32_e32 v23, v24, v26
	v_mul_f32_e32 v24, v25, v26
	v_mul_f32_e32 v23, v5, v23
	v_mul_f32_e32 v24, v7, v24
	v_add_u32_e32 v22, 0x3000, v2
	v_cvt_pk_bf16_f32 v24, v23, v24
	v_mov_b32_e32 v23, v3
	v_lshl_add_u64 v[22:23], v[22:23], 1, s[6:7]
	global_store_short v[22:23], v24, off offset:768
	v_add_u32_e32 v22, 0x3020, v2
	v_mov_b32_e32 v23, v3
	v_lshl_add_u64 v[22:23], v[22:23], 1, s[6:7]
	global_store_short_d16_hi v[22:23], v24, off offset:768
	v_mul_f32_e32 v22, v27, v26
	v_mul_f32_e32 v21, v21, v26
	v_mul_f32_e32 v22, v4, v22
	v_mul_f32_e32 v21, v6, v21
	v_cvt_pk_bf16_f32 v21, v22, v21
	v_add_u32_e32 v22, 0x3040, v2
	v_mov_b32_e32 v23, v3
	v_lshl_add_u64 v[22:23], v[22:23], 1, s[6:7]
	global_store_short v[22:23], v21, off offset:768
	v_add_u32_e32 v22, 0x3060, v2
	v_mov_b32_e32 v23, v3
	v_lshl_add_u64 v[22:23], v[22:23], 1, s[6:7]
	global_store_short_d16_hi v[22:23], v21, off offset:768
	ds_read_b32 v9, v8 offset:32
	ds_read2st64_b32 v[10:11], v1 offset0:4 offset1:20
	ds_read_b32 v21, v8 offset:36
	ds_read2st64_b32 v[22:23], v1 offset0:5 offset1:21
	s_waitcnt lgkmcnt(0)
	v_fma_f32 v12, v72, v9, -v10
	v_fma_f32 v13, v104, v9, -v11
	ds_read2st64_b32 v[10:11], v1 offset0:36 offset1:52
	v_mul_f32_e32 v14, v13, v13
	v_fmac_f32_e32 v14, v12, v12
	v_fma_f32 v24, v73, v21, -v22
	v_fma_f32 v25, v105, v21, -v23
	ds_read2st64_b32 v[22:23], v1 offset0:37 offset1:53
	v_mul_f32_e32 v26, v25, v25
	v_fmac_f32_e32 v26, v24, v24
	s_waitcnt lgkmcnt(0)
	v_fma_f32 v15, v120, v9, -v10
	v_fmac_f32_e32 v14, v15, v15
	v_fma_f32 v9, v136, v9, -v11
	v_fmac_f32_e32 v14, v9, v9
	s_nop 1
	v_add_f32_dpp v10, v14, v14 quad_perm:[1,0,3,2] row_mask:0xf bank_mask:0xf
	s_nop 1
	v_add_f32_dpp v10, v10, v10 quad_perm:[2,3,0,1] row_mask:0xf bank_mask:0xf
	s_nop 1
	v_add_f32_dpp v10, v10, v10 row_half_mirror row_mask:0xf bank_mask:0xf
	s_nop 1
	v_add_f32_dpp v10, v10, v10 row_mirror row_mask:0xf bank_mask:0xf
	ds_swizzle_b32 v11, v10 offset:swizzle(SWAP,16)
	v_fma_f32 v27, v121, v21, -v22
	v_fmac_f32_e32 v26, v27, v27
	v_fma_f32 v21, v137, v21, -v23
	v_fmac_f32_e32 v26, v21, v21
	s_nop 1
	v_add_f32_dpp v22, v26, v26 quad_perm:[1,0,3,2] row_mask:0xf bank_mask:0xf
	s_nop 1
	v_add_f32_dpp v22, v22, v22 quad_perm:[2,3,0,1] row_mask:0xf bank_mask:0xf
	s_nop 1
	v_add_f32_dpp v22, v22, v22 row_half_mirror row_mask:0xf bank_mask:0xf
	s_nop 1
	v_add_f32_dpp v22, v22, v22 row_mirror row_mask:0xf bank_mask:0xf
	ds_swizzle_b32 v23, v22 offset:swizzle(SWAP,16)
	s_waitcnt lgkmcnt(0)
	v_add_f32_e32 v10, v10, v11
	v_fmamk_f32 v10, v10, 0x3c000000, v254
	v_rsq_f32_e32 v14, v10
	s_nop 0
	v_mul_f32_e32 v11, v12, v14
	v_mul_f32_e32 v12, v13, v14
	v_mul_f32_e32 v11, v5, v11
	v_mul_f32_e32 v12, v7, v12
	v_add_u32_e32 v10, 0x8000, v2
	v_cvt_pk_bf16_f32 v12, v11, v12
	v_mov_b32_e32 v11, v3
	v_lshl_add_u64 v[10:11], v[10:11], 1, s[6:7]
	global_store_short v[10:11], v12, off offset:768
	v_add_u32_e32 v10, 0x8020, v2
	v_mov_b32_e32 v11, v3
	v_lshl_add_u64 v[10:11], v[10:11], 1, s[6:7]
	global_store_short_d16_hi v[10:11], v12, off offset:768
	v_mul_f32_e32 v10, v15, v14
	v_mul_f32_e32 v9, v9, v14
	v_mul_f32_e32 v10, v4, v10
	v_mul_f32_e32 v9, v6, v9
	v_cvt_pk_bf16_f32 v9, v10, v9
	v_add_u32_e32 v10, 0x8040, v2
	v_mov_b32_e32 v11, v3
	v_lshl_add_u64 v[10:11], v[10:11], 1, s[6:7]
	global_store_short v[10:11], v9, off offset:768
	v_add_u32_e32 v10, 0x8060, v2
	v_mov_b32_e32 v11, v3
	v_lshl_add_u64 v[10:11], v[10:11], 1, s[6:7]
	global_store_short_d16_hi v[10:11], v9, off offset:768
	v_add_f32_e32 v22, v22, v23
	v_fmamk_f32 v22, v22, 0x3c000000, v254
	v_rsq_f32_e32 v26, v22
	s_nop 0
	v_mul_f32_e32 v23, v24, v26
	v_mul_f32_e32 v24, v25, v26
	v_mul_f32_e32 v23, v5, v23
	v_mul_f32_e32 v24, v7, v24
	v_add_u32_e32 v22, 0x9000, v2
	v_cvt_pk_bf16_f32 v24, v23, v24
	v_mov_b32_e32 v23, v3
	v_lshl_add_u64 v[22:23], v[22:23], 1, s[6:7]
	global_store_short v[22:23], v24, off offset:768
	v_add_u32_e32 v22, 0x9020, v2
	v_mov_b32_e32 v23, v3
	v_lshl_add_u64 v[22:23], v[22:23], 1, s[6:7]
	global_store_short_d16_hi v[22:23], v24, off offset:768
	v_mul_f32_e32 v22, v27, v26
	v_mul_f32_e32 v21, v21, v26
	v_mul_f32_e32 v22, v4, v22
	v_mul_f32_e32 v21, v6, v21
	v_cvt_pk_bf16_f32 v21, v22, v21
	v_add_u32_e32 v22, 0x9040, v2
	v_mov_b32_e32 v23, v3
	v_lshl_add_u64 v[22:23], v[22:23], 1, s[6:7]
	global_store_short v[22:23], v21, off offset:768
	v_add_u32_e32 v22, 0x9060, v2
	v_mov_b32_e32 v23, v3
	v_lshl_add_u64 v[22:23], v[22:23], 1, s[6:7]
	global_store_short_d16_hi v[22:23], v21, off offset:768
	ds_read_b32 v9, v8 offset:40
	ds_read2st64_b32 v[10:11], v1 offset0:6 offset1:22
	ds_read_b32 v21, v8 offset:44
	ds_read2st64_b32 v[22:23], v1 offset0:7 offset1:23
	s_waitcnt lgkmcnt(0)
	v_fma_f32 v12, v74, v9, -v10
	v_fma_f32 v13, v106, v9, -v11
	ds_read2st64_b32 v[10:11], v1 offset0:38 offset1:54
	v_mul_f32_e32 v14, v13, v13
	v_fmac_f32_e32 v14, v12, v12
	v_fma_f32 v24, v75, v21, -v22
	v_fma_f32 v25, v107, v21, -v23
	ds_read2st64_b32 v[22:23], v1 offset0:39 offset1:55
	v_mul_f32_e32 v26, v25, v25
	v_fmac_f32_e32 v26, v24, v24
	s_waitcnt lgkmcnt(0)
	v_fma_f32 v15, v122, v9, -v10
	v_fmac_f32_e32 v14, v15, v15
	v_fma_f32 v9, v138, v9, -v11
	v_fmac_f32_e32 v14, v9, v9
	s_nop 1
	v_add_f32_dpp v10, v14, v14 quad_perm:[1,0,3,2] row_mask:0xf bank_mask:0xf
	s_nop 1
	v_add_f32_dpp v10, v10, v10 quad_perm:[2,3,0,1] row_mask:0xf bank_mask:0xf
	s_nop 1
	v_add_f32_dpp v10, v10, v10 row_half_mirror row_mask:0xf bank_mask:0xf
	s_nop 1
	v_add_f32_dpp v10, v10, v10 row_mirror row_mask:0xf bank_mask:0xf
	ds_swizzle_b32 v11, v10 offset:swizzle(SWAP,16)
	v_fma_f32 v27, v123, v21, -v22
	v_fmac_f32_e32 v26, v27, v27
	v_fma_f32 v21, v139, v21, -v23
	v_fmac_f32_e32 v26, v21, v21
	s_nop 1
	v_add_f32_dpp v22, v26, v26 quad_perm:[1,0,3,2] row_mask:0xf bank_mask:0xf
	s_nop 1
	v_add_f32_dpp v22, v22, v22 quad_perm:[2,3,0,1] row_mask:0xf bank_mask:0xf
	s_nop 1
	v_add_f32_dpp v22, v22, v22 row_half_mirror row_mask:0xf bank_mask:0xf
	s_nop 1
	v_add_f32_dpp v22, v22, v22 row_mirror row_mask:0xf bank_mask:0xf
	ds_swizzle_b32 v23, v22 offset:swizzle(SWAP,16)
	s_waitcnt lgkmcnt(0)
	v_add_f32_e32 v10, v10, v11
	v_fmamk_f32 v10, v10, 0x3c000000, v254
	v_rsq_f32_e32 v14, v10
	s_nop 0
	v_mul_f32_e32 v11, v12, v14
	v_mul_f32_e32 v12, v13, v14
	v_mul_f32_e32 v11, v5, v11
	v_mul_f32_e32 v12, v7, v12
	v_add_u32_e32 v10, 0xa000, v2
	v_cvt_pk_bf16_f32 v12, v11, v12
	v_mov_b32_e32 v11, v3
	v_lshl_add_u64 v[10:11], v[10:11], 1, s[6:7]
	global_store_short v[10:11], v12, off offset:768
	v_add_u32_e32 v10, 0xa020, v2
	v_mov_b32_e32 v11, v3
	v_lshl_add_u64 v[10:11], v[10:11], 1, s[6:7]
	global_store_short_d16_hi v[10:11], v12, off offset:768
	v_mul_f32_e32 v10, v15, v14
	v_mul_f32_e32 v9, v9, v14
	v_mul_f32_e32 v10, v4, v10
	v_mul_f32_e32 v9, v6, v9
	v_cvt_pk_bf16_f32 v9, v10, v9
	v_add_u32_e32 v10, 0xa040, v2
	v_mov_b32_e32 v11, v3
	v_lshl_add_u64 v[10:11], v[10:11], 1, s[6:7]
	global_store_short v[10:11], v9, off offset:768
	v_add_u32_e32 v10, 0xa060, v2
	v_mov_b32_e32 v11, v3
	v_lshl_add_u64 v[10:11], v[10:11], 1, s[6:7]
	global_store_short_d16_hi v[10:11], v9, off offset:768
	v_add_f32_e32 v22, v22, v23
	v_fmamk_f32 v22, v22, 0x3c000000, v254
	v_rsq_f32_e32 v26, v22
	s_nop 0
	v_mul_f32_e32 v23, v24, v26
	v_mul_f32_e32 v24, v25, v26
	v_mul_f32_e32 v23, v5, v23
	v_mul_f32_e32 v24, v7, v24
	v_add_u32_e32 v22, 0xb000, v2
	v_cvt_pk_bf16_f32 v24, v23, v24
	v_mov_b32_e32 v23, v3
	v_lshl_add_u64 v[22:23], v[22:23], 1, s[6:7]
	global_store_short v[22:23], v24, off offset:768
	v_add_u32_e32 v22, 0xb020, v2
	v_mov_b32_e32 v23, v3
	v_lshl_add_u64 v[22:23], v[22:23], 1, s[6:7]
	global_store_short_d16_hi v[22:23], v24, off offset:768
	v_mul_f32_e32 v22, v27, v26
	v_mul_f32_e32 v21, v21, v26
	v_mul_f32_e32 v22, v4, v22
	v_mul_f32_e32 v21, v6, v21
	v_cvt_pk_bf16_f32 v21, v22, v21
	v_add_u32_e32 v22, 0xb040, v2
	v_mov_b32_e32 v23, v3
	v_lshl_add_u64 v[22:23], v[22:23], 1, s[6:7]
	global_store_short v[22:23], v21, off offset:768
	v_add_u32_e32 v22, 0xb060, v2
	v_mov_b32_e32 v23, v3
	v_lshl_add_u64 v[22:23], v[22:23], 1, s[6:7]
	global_store_short_d16_hi v[22:23], v21, off offset:768
	ds_read_b32 v9, v8 offset:64
	ds_read2st64_b32 v[10:11], v1 offset0:8 offset1:24
	ds_read_b32 v21, v8 offset:68
	ds_read2st64_b32 v[22:23], v1 offset0:9 offset1:25
	s_waitcnt lgkmcnt(0)
	v_fma_f32 v12, v76, v9, -v10
	v_fma_f32 v13, v108, v9, -v11
	ds_read2st64_b32 v[10:11], v1 offset0:40 offset1:56
	v_mul_f32_e32 v14, v13, v13
	v_fmac_f32_e32 v14, v12, v12
	v_fma_f32 v24, v77, v21, -v22
	v_fma_f32 v25, v109, v21, -v23
	ds_read2st64_b32 v[22:23], v1 offset0:41 offset1:57
	v_mul_f32_e32 v26, v25, v25
	v_fmac_f32_e32 v26, v24, v24
	s_waitcnt lgkmcnt(0)
	v_fma_f32 v15, v124, v9, -v10
	v_fmac_f32_e32 v14, v15, v15
	v_fma_f32 v9, v140, v9, -v11
	v_fmac_f32_e32 v14, v9, v9
	s_nop 1
	v_add_f32_dpp v10, v14, v14 quad_perm:[1,0,3,2] row_mask:0xf bank_mask:0xf
	s_nop 1
	v_add_f32_dpp v10, v10, v10 quad_perm:[2,3,0,1] row_mask:0xf bank_mask:0xf
	s_nop 1
	v_add_f32_dpp v10, v10, v10 row_half_mirror row_mask:0xf bank_mask:0xf
	s_nop 1
	v_add_f32_dpp v10, v10, v10 row_mirror row_mask:0xf bank_mask:0xf
	ds_swizzle_b32 v11, v10 offset:swizzle(SWAP,16)
	v_fma_f32 v27, v125, v21, -v22
	v_fmac_f32_e32 v26, v27, v27
	v_fma_f32 v21, v141, v21, -v23
	v_fmac_f32_e32 v26, v21, v21
	s_nop 1
	v_add_f32_dpp v22, v26, v26 quad_perm:[1,0,3,2] row_mask:0xf bank_mask:0xf
	s_nop 1
	v_add_f32_dpp v22, v22, v22 quad_perm:[2,3,0,1] row_mask:0xf bank_mask:0xf
	s_nop 1
	v_add_f32_dpp v22, v22, v22 row_half_mirror row_mask:0xf bank_mask:0xf
	s_nop 1
	v_add_f32_dpp v22, v22, v22 row_mirror row_mask:0xf bank_mask:0xf
	ds_swizzle_b32 v23, v22 offset:swizzle(SWAP,16)
	s_waitcnt lgkmcnt(0)
	v_add_f32_e32 v10, v10, v11
	v_fmamk_f32 v10, v10, 0x3c000000, v254
	v_rsq_f32_e32 v14, v10
	s_nop 0
	v_mul_f32_e32 v11, v12, v14
	v_mul_f32_e32 v12, v13, v14
	v_mul_f32_e32 v11, v5, v11
	v_mul_f32_e32 v12, v7, v12
	v_add_u32_e32 v10, 0x10000, v2
	v_cvt_pk_bf16_f32 v12, v11, v12
	v_mov_b32_e32 v11, v3
	v_lshl_add_u64 v[10:11], v[10:11], 1, s[6:7]
	global_store_short v[10:11], v12, off offset:768
	v_add_u32_e32 v10, 0x10020, v2
	v_mov_b32_e32 v11, v3
	v_lshl_add_u64 v[10:11], v[10:11], 1, s[6:7]
	global_store_short_d16_hi v[10:11], v12, off offset:768
	v_mul_f32_e32 v10, v15, v14
	v_mul_f32_e32 v9, v9, v14
	v_mul_f32_e32 v10, v4, v10
	v_mul_f32_e32 v9, v6, v9
	v_cvt_pk_bf16_f32 v9, v10, v9
	v_add_u32_e32 v10, 0x10040, v2
	v_mov_b32_e32 v11, v3
	v_lshl_add_u64 v[10:11], v[10:11], 1, s[6:7]
	global_store_short v[10:11], v9, off offset:768
	v_add_u32_e32 v10, 0x10060, v2
	v_mov_b32_e32 v11, v3
	v_lshl_add_u64 v[10:11], v[10:11], 1, s[6:7]
	global_store_short_d16_hi v[10:11], v9, off offset:768
	v_add_f32_e32 v22, v22, v23
	v_fmamk_f32 v22, v22, 0x3c000000, v254
	v_rsq_f32_e32 v26, v22
	s_nop 0
	v_mul_f32_e32 v23, v24, v26
	v_mul_f32_e32 v24, v25, v26
	v_mul_f32_e32 v23, v5, v23
	v_mul_f32_e32 v24, v7, v24
	v_add_u32_e32 v22, 0x11000, v2
	v_cvt_pk_bf16_f32 v24, v23, v24
	v_mov_b32_e32 v23, v3
	v_lshl_add_u64 v[22:23], v[22:23], 1, s[6:7]
	global_store_short v[22:23], v24, off offset:768
	v_add_u32_e32 v22, 0x11020, v2
	v_mov_b32_e32 v23, v3
	v_lshl_add_u64 v[22:23], v[22:23], 1, s[6:7]
	global_store_short_d16_hi v[22:23], v24, off offset:768
	v_mul_f32_e32 v22, v27, v26
	v_mul_f32_e32 v21, v21, v26
	v_mul_f32_e32 v22, v4, v22
	v_mul_f32_e32 v21, v6, v21
	v_cvt_pk_bf16_f32 v21, v22, v21
	v_add_u32_e32 v22, 0x11040, v2
	v_mov_b32_e32 v23, v3
	v_lshl_add_u64 v[22:23], v[22:23], 1, s[6:7]
	global_store_short v[22:23], v21, off offset:768
	v_add_u32_e32 v22, 0x11060, v2
	v_mov_b32_e32 v23, v3
	v_lshl_add_u64 v[22:23], v[22:23], 1, s[6:7]
	global_store_short_d16_hi v[22:23], v21, off offset:768
	ds_read_b32 v9, v8 offset:72
	ds_read2st64_b32 v[10:11], v1 offset0:10 offset1:26
	ds_read_b32 v21, v8 offset:76
	ds_read2st64_b32 v[22:23], v1 offset0:11 offset1:27
	s_waitcnt lgkmcnt(0)
	v_fma_f32 v12, v78, v9, -v10
	v_fma_f32 v13, v110, v9, -v11
	ds_read2st64_b32 v[10:11], v1 offset0:42 offset1:58
	v_mul_f32_e32 v14, v13, v13
	v_fmac_f32_e32 v14, v12, v12
	v_fma_f32 v24, v79, v21, -v22
	v_fma_f32 v25, v111, v21, -v23
	ds_read2st64_b32 v[22:23], v1 offset0:43 offset1:59
	v_mul_f32_e32 v26, v25, v25
	v_fmac_f32_e32 v26, v24, v24
	s_waitcnt lgkmcnt(0)
	v_fma_f32 v15, v126, v9, -v10
	v_fmac_f32_e32 v14, v15, v15
	v_fma_f32 v9, v142, v9, -v11
	v_fmac_f32_e32 v14, v9, v9
	s_nop 1
	v_add_f32_dpp v10, v14, v14 quad_perm:[1,0,3,2] row_mask:0xf bank_mask:0xf
	s_nop 1
	v_add_f32_dpp v10, v10, v10 quad_perm:[2,3,0,1] row_mask:0xf bank_mask:0xf
	s_nop 1
	v_add_f32_dpp v10, v10, v10 row_half_mirror row_mask:0xf bank_mask:0xf
	s_nop 1
	v_add_f32_dpp v10, v10, v10 row_mirror row_mask:0xf bank_mask:0xf
	ds_swizzle_b32 v11, v10 offset:swizzle(SWAP,16)
	v_fma_f32 v27, v127, v21, -v22
	v_fmac_f32_e32 v26, v27, v27
	v_fma_f32 v21, v143, v21, -v23
	v_fmac_f32_e32 v26, v21, v21
	s_nop 1
	v_add_f32_dpp v22, v26, v26 quad_perm:[1,0,3,2] row_mask:0xf bank_mask:0xf
	s_nop 1
	v_add_f32_dpp v22, v22, v22 quad_perm:[2,3,0,1] row_mask:0xf bank_mask:0xf
	s_nop 1
	v_add_f32_dpp v22, v22, v22 row_half_mirror row_mask:0xf bank_mask:0xf
	s_nop 1
	v_add_f32_dpp v22, v22, v22 row_mirror row_mask:0xf bank_mask:0xf
	ds_swizzle_b32 v23, v22 offset:swizzle(SWAP,16)
	s_waitcnt lgkmcnt(0)
	v_add_f32_e32 v10, v10, v11
	v_fmamk_f32 v10, v10, 0x3c000000, v254
	v_rsq_f32_e32 v14, v10
	s_nop 0
	v_mul_f32_e32 v11, v12, v14
	v_mul_f32_e32 v12, v13, v14
	v_mul_f32_e32 v11, v5, v11
	v_mul_f32_e32 v12, v7, v12
	v_add_u32_e32 v10, 0x12000, v2
	v_cvt_pk_bf16_f32 v12, v11, v12
	v_mov_b32_e32 v11, v3
	v_lshl_add_u64 v[10:11], v[10:11], 1, s[6:7]
	global_store_short v[10:11], v12, off offset:768
	v_add_u32_e32 v10, 0x12020, v2
	v_mov_b32_e32 v11, v3
	v_lshl_add_u64 v[10:11], v[10:11], 1, s[6:7]
	global_store_short_d16_hi v[10:11], v12, off offset:768
	v_mul_f32_e32 v10, v15, v14
	v_mul_f32_e32 v9, v9, v14
	v_mul_f32_e32 v10, v4, v10
	v_mul_f32_e32 v9, v6, v9
	v_cvt_pk_bf16_f32 v9, v10, v9
	v_add_u32_e32 v10, 0x12040, v2
	v_mov_b32_e32 v11, v3
	v_lshl_add_u64 v[10:11], v[10:11], 1, s[6:7]
	global_store_short v[10:11], v9, off offset:768
	v_add_u32_e32 v10, 0x12060, v2
	v_mov_b32_e32 v11, v3
	v_lshl_add_u64 v[10:11], v[10:11], 1, s[6:7]
	global_store_short_d16_hi v[10:11], v9, off offset:768
	v_add_f32_e32 v22, v22, v23
	v_fmamk_f32 v22, v22, 0x3c000000, v254
	v_rsq_f32_e32 v26, v22
	s_nop 0
	v_mul_f32_e32 v23, v24, v26
	v_mul_f32_e32 v24, v25, v26
	v_mul_f32_e32 v23, v5, v23
	v_mul_f32_e32 v24, v7, v24
	v_add_u32_e32 v22, 0x13000, v2
	v_cvt_pk_bf16_f32 v24, v23, v24
	v_mov_b32_e32 v23, v3
	v_lshl_add_u64 v[22:23], v[22:23], 1, s[6:7]
	global_store_short v[22:23], v24, off offset:768
	v_add_u32_e32 v22, 0x13020, v2
	v_mov_b32_e32 v23, v3
	v_lshl_add_u64 v[22:23], v[22:23], 1, s[6:7]
	global_store_short_d16_hi v[22:23], v24, off offset:768
	v_mul_f32_e32 v22, v27, v26
	v_mul_f32_e32 v21, v21, v26
	v_mul_f32_e32 v22, v4, v22
	v_mul_f32_e32 v21, v6, v21
	v_cvt_pk_bf16_f32 v21, v22, v21
	v_add_u32_e32 v22, 0x13040, v2
	v_mov_b32_e32 v23, v3
	v_lshl_add_u64 v[22:23], v[22:23], 1, s[6:7]
	global_store_short v[22:23], v21, off offset:768
	v_add_u32_e32 v22, 0x13060, v2
	v_mov_b32_e32 v23, v3
	v_lshl_add_u64 v[22:23], v[22:23], 1, s[6:7]
	global_store_short_d16_hi v[22:23], v21, off offset:768
	ds_read_b32 v9, v8 offset:96
	ds_read2st64_b32 v[10:11], v1 offset0:12 offset1:28
	ds_read_b32 v21, v8 offset:100
	ds_read2st64_b32 v[22:23], v1 offset0:13 offset1:29
	s_waitcnt lgkmcnt(0)
	v_fma_f32 v12, v80, v9, -v10
	v_fma_f32 v13, v112, v9, -v11
	ds_read2st64_b32 v[10:11], v1 offset0:44 offset1:60
	v_mul_f32_e32 v14, v13, v13
	v_fmac_f32_e32 v14, v12, v12
	v_fma_f32 v24, v81, v21, -v22
	v_fma_f32 v25, v113, v21, -v23
	ds_read2st64_b32 v[22:23], v1 offset0:45 offset1:61
	v_mul_f32_e32 v26, v25, v25
	v_fmac_f32_e32 v26, v24, v24
	s_waitcnt lgkmcnt(0)
	v_fma_f32 v15, v128, v9, -v10
	v_fmac_f32_e32 v14, v15, v15
	v_fma_f32 v9, v144, v9, -v11
	v_fmac_f32_e32 v14, v9, v9
	s_nop 1
	v_add_f32_dpp v10, v14, v14 quad_perm:[1,0,3,2] row_mask:0xf bank_mask:0xf
	s_nop 1
	v_add_f32_dpp v10, v10, v10 quad_perm:[2,3,0,1] row_mask:0xf bank_mask:0xf
	s_nop 1
	v_add_f32_dpp v10, v10, v10 row_half_mirror row_mask:0xf bank_mask:0xf
	s_nop 1
	v_add_f32_dpp v10, v10, v10 row_mirror row_mask:0xf bank_mask:0xf
	ds_swizzle_b32 v11, v10 offset:swizzle(SWAP,16)
	v_fma_f32 v27, v129, v21, -v22
	v_fmac_f32_e32 v26, v27, v27
	v_fma_f32 v21, v145, v21, -v23
	v_fmac_f32_e32 v26, v21, v21
	s_nop 1
	v_add_f32_dpp v22, v26, v26 quad_perm:[1,0,3,2] row_mask:0xf bank_mask:0xf
	s_nop 1
	v_add_f32_dpp v22, v22, v22 quad_perm:[2,3,0,1] row_mask:0xf bank_mask:0xf
	s_nop 1
	v_add_f32_dpp v22, v22, v22 row_half_mirror row_mask:0xf bank_mask:0xf
	s_nop 1
	v_add_f32_dpp v22, v22, v22 row_mirror row_mask:0xf bank_mask:0xf
	ds_swizzle_b32 v23, v22 offset:swizzle(SWAP,16)
	s_waitcnt lgkmcnt(0)
	v_add_f32_e32 v10, v10, v11
	v_fmamk_f32 v10, v10, 0x3c000000, v254
	v_rsq_f32_e32 v14, v10
	s_nop 0
	v_mul_f32_e32 v11, v12, v14
	v_mul_f32_e32 v12, v13, v14
	v_mul_f32_e32 v11, v5, v11
	v_mul_f32_e32 v12, v7, v12
	v_add_u32_e32 v10, 0x18000, v2
	v_cvt_pk_bf16_f32 v12, v11, v12
	v_mov_b32_e32 v11, v3
	v_lshl_add_u64 v[10:11], v[10:11], 1, s[6:7]
	global_store_short v[10:11], v12, off offset:768
	v_add_u32_e32 v10, 0x18020, v2
	v_mov_b32_e32 v11, v3
	v_lshl_add_u64 v[10:11], v[10:11], 1, s[6:7]
	global_store_short_d16_hi v[10:11], v12, off offset:768
	v_mul_f32_e32 v10, v15, v14
	v_mul_f32_e32 v9, v9, v14
	v_mul_f32_e32 v10, v4, v10
	v_mul_f32_e32 v9, v6, v9
	v_cvt_pk_bf16_f32 v9, v10, v9
	v_add_u32_e32 v10, 0x18040, v2
	v_mov_b32_e32 v11, v3
	v_lshl_add_u64 v[10:11], v[10:11], 1, s[6:7]
	global_store_short v[10:11], v9, off offset:768
	v_add_u32_e32 v10, 0x18060, v2
	v_mov_b32_e32 v11, v3
	v_lshl_add_u64 v[10:11], v[10:11], 1, s[6:7]
	global_store_short_d16_hi v[10:11], v9, off offset:768
	v_add_f32_e32 v22, v22, v23
	v_fmamk_f32 v22, v22, 0x3c000000, v254
	v_rsq_f32_e32 v26, v22
	s_nop 0
	v_mul_f32_e32 v23, v24, v26
	v_mul_f32_e32 v24, v25, v26
	v_mul_f32_e32 v23, v5, v23
	v_mul_f32_e32 v24, v7, v24
	v_add_u32_e32 v22, 0x19000, v2
	v_cvt_pk_bf16_f32 v24, v23, v24
	v_mov_b32_e32 v23, v3
	v_lshl_add_u64 v[22:23], v[22:23], 1, s[6:7]
	global_store_short v[22:23], v24, off offset:768
	v_add_u32_e32 v22, 0x19020, v2
	v_mov_b32_e32 v23, v3
	v_lshl_add_u64 v[22:23], v[22:23], 1, s[6:7]
	global_store_short_d16_hi v[22:23], v24, off offset:768
	v_mul_f32_e32 v22, v27, v26
	v_mul_f32_e32 v21, v21, v26
	v_mul_f32_e32 v22, v4, v22
	v_mul_f32_e32 v21, v6, v21
	v_cvt_pk_bf16_f32 v21, v22, v21
	v_add_u32_e32 v22, 0x19040, v2
	v_mov_b32_e32 v23, v3
	v_lshl_add_u64 v[22:23], v[22:23], 1, s[6:7]
	global_store_short v[22:23], v21, off offset:768
	v_add_u32_e32 v22, 0x19060, v2
	v_mov_b32_e32 v23, v3
	v_lshl_add_u64 v[22:23], v[22:23], 1, s[6:7]
	global_store_short_d16_hi v[22:23], v21, off offset:768
	ds_read_b32 v9, v8 offset:104
	ds_read2st64_b32 v[10:11], v1 offset0:14 offset1:30
	s_waitcnt lgkmcnt(0)
	v_fma_f32 v12, v82, v9, -v10
	v_fma_f32 v13, v114, v9, -v11
	ds_read2st64_b32 v[10:11], v1 offset0:46 offset1:62
	v_mul_f32_e32 v14, v13, v13
	v_fmac_f32_e32 v14, v12, v12
	s_waitcnt lgkmcnt(0)
	v_fma_f32 v15, v130, v9, -v10
	v_fmac_f32_e32 v14, v15, v15
	v_fma_f32 v9, v146, v9, -v11
	v_fmac_f32_e32 v14, v9, v9
	s_nop 1
	v_add_f32_dpp v10, v14, v14 quad_perm:[1,0,3,2] row_mask:0xf bank_mask:0xf
	s_nop 1
	v_add_f32_dpp v10, v10, v10 quad_perm:[2,3,0,1] row_mask:0xf bank_mask:0xf
	s_nop 1
	v_add_f32_dpp v10, v10, v10 row_half_mirror row_mask:0xf bank_mask:0xf
	s_nop 1
	v_add_f32_dpp v10, v10, v10 row_mirror row_mask:0xf bank_mask:0xf
	ds_swizzle_b32 v11, v10 offset:swizzle(SWAP,16)
	s_waitcnt lgkmcnt(0)
	v_add_f32_e32 v10, v10, v11
	v_fmamk_f32 v10, v10, 0x3c000000, v254
	v_cmp_gt_f32_e32 vcc, s90, v10
	v_mul_f32_e32 v11, 0x4f800000, v10
	s_nop 0
	v_cndmask_b32_e32 v10, v10, v11, vcc
	v_sqrt_f32_e32 v11, v10
	s_nop 0
	v_add_u32_e32 v14, -1, v11
	v_fma_f32 v16, -v14, v11, v10
	v_cmp_ge_f32_e64 s[4:5], 0, v16
	v_add_u32_e32 v16, 1, v11
	s_nop 0
	v_cndmask_b32_e64 v14, v11, v14, s[4:5]
	v_fma_f32 v11, -v16, v11, v10
	v_cmp_lt_f32_e64 s[4:5], 0, v11
	s_nop 1
	v_cndmask_b32_e64 v11, v14, v16, s[4:5]
	v_mul_f32_e32 v14, 0x37800000, v11
	v_cndmask_b32_e32 v11, v11, v14, vcc
	v_cmp_class_f32_e32 vcc, v10, v209
	s_nop 1
	v_cndmask_b32_e32 v10, v11, v10, vcc
	v_div_scale_f32 v11, s[4:5], v10, v10, 1.0
	v_rcp_f32_e32 v14, v11
	s_nop 0
	v_fma_f32 v16, -v11, v14, 1.0
	v_fmac_f32_e32 v14, v16, v14
	v_div_scale_f32 v16, vcc, 1.0, v10, 1.0
	v_mul_f32_e32 v17, v16, v14
	v_fma_f32 v18, -v11, v17, v16
	v_fmac_f32_e32 v17, v18, v14
	v_fma_f32 v11, -v11, v17, v16
	v_div_fmas_f32 v11, v11, v14, v17
	v_div_fixup_f32 v14, v11, v10, 1.0
	v_mul_f32_e32 v11, v12, v14
	v_mul_f32_e32 v12, v13, v14
	v_mul_f32_e32 v11, v5, v11
	v_mul_f32_e32 v12, v7, v12
	v_add_u32_e32 v10, 0x1a000, v2
	v_cvt_pk_bf16_f32 v12, v11, v12
	v_mov_b32_e32 v11, v3
	v_lshl_add_u64 v[10:11], v[10:11], 1, s[6:7]
	global_store_short v[10:11], v12, off offset:768
	v_add_u32_e32 v10, 0x1a020, v2
	v_mov_b32_e32 v11, v3
	v_lshl_add_u64 v[10:11], v[10:11], 1, s[6:7]
	global_store_short_d16_hi v[10:11], v12, off offset:768
	v_mul_f32_e32 v10, v15, v14
	v_mul_f32_e32 v9, v9, v14
	v_mul_f32_e32 v10, v4, v10
	v_mul_f32_e32 v9, v6, v9
	v_cvt_pk_bf16_f32 v9, v10, v9
	v_add_u32_e32 v10, 0x1a040, v2
	v_mov_b32_e32 v11, v3
	v_lshl_add_u64 v[10:11], v[10:11], 1, s[6:7]
	global_store_short v[10:11], v9, off offset:768
	v_add_u32_e32 v10, 0x1a060, v2
	v_mov_b32_e32 v11, v3
	v_lshl_add_u64 v[10:11], v[10:11], 1, s[6:7]
	global_store_short_d16_hi v[10:11], v9, off offset:768
	ds_read_b32 v10, v8 offset:108
	ds_read2st64_b32 v[8:9], v1 offset0:15 offset1:31
	s_waitcnt lgkmcnt(0)
	v_fma_f32 v11, v83, v10, -v8
	v_fma_f32 v12, v115, v10, -v9
	ds_read2st64_b32 v[8:9], v1 offset0:47 offset1:63
	v_mul_f32_e32 v13, v12, v12
	v_fmac_f32_e32 v13, v11, v11
	s_waitcnt lgkmcnt(0)
	v_fma_f32 v1, v131, v10, -v8
	v_fmac_f32_e32 v13, v1, v1
	v_fma_f32 v10, v147, v10, -v9
	v_fmac_f32_e32 v13, v10, v10
	s_nop 1
	v_add_f32_dpp v8, v13, v13 quad_perm:[1,0,3,2] row_mask:0xf bank_mask:0xf
	s_nop 1
	v_add_f32_dpp v8, v8, v8 quad_perm:[2,3,0,1] row_mask:0xf bank_mask:0xf
	s_nop 1
	v_add_f32_dpp v8, v8, v8 row_half_mirror row_mask:0xf bank_mask:0xf
	s_nop 1
	v_add_f32_dpp v8, v8, v8 row_mirror row_mask:0xf bank_mask:0xf
	ds_swizzle_b32 v9, v8 offset:swizzle(SWAP,16)
	s_waitcnt lgkmcnt(0)
	v_add_f32_e32 v8, v8, v9
	v_fmamk_f32 v8, v8, 0x3c000000, v254
	v_cmp_gt_f32_e32 vcc, s90, v8
	v_mul_f32_e32 v9, 0x4f800000, v8
	s_nop 0
	v_cndmask_b32_e32 v8, v8, v9, vcc
	v_sqrt_f32_e32 v9, v8
	s_nop 0
	v_add_u32_e32 v13, -1, v9
	v_fma_f32 v14, -v13, v9, v8
	v_cmp_ge_f32_e64 s[4:5], 0, v14
	v_add_u32_e32 v14, 1, v9
	s_nop 0
	v_cndmask_b32_e64 v13, v9, v13, s[4:5]
	v_fma_f32 v9, -v14, v9, v8
	v_cmp_lt_f32_e64 s[4:5], 0, v9
	s_nop 1
	v_cndmask_b32_e64 v9, v13, v14, s[4:5]
	v_mul_f32_e32 v13, 0x37800000, v9
	v_cndmask_b32_e32 v9, v9, v13, vcc
	v_cmp_class_f32_e32 vcc, v8, v209
	s_nop 1
	v_cndmask_b32_e32 v8, v9, v8, vcc
	v_div_scale_f32 v9, s[4:5], v8, v8, 1.0
	v_rcp_f32_e32 v13, v9
	s_nop 0
	v_fma_f32 v14, -v9, v13, 1.0
	v_fmac_f32_e32 v13, v14, v13
	v_div_scale_f32 v14, vcc, 1.0, v8, 1.0
	v_mul_f32_e32 v15, v14, v13
	v_fma_f32 v16, -v9, v15, v14
	v_fmac_f32_e32 v15, v16, v13
	v_fma_f32 v9, -v9, v15, v14
	v_div_fmas_f32 v9, v9, v13, v15
	v_div_fixup_f32 v13, v9, v8, 1.0
	v_mul_f32_e32 v9, v11, v13
	v_mul_f32_e32 v5, v5, v9
	v_mul_f32_e32 v9, v12, v13
	v_add_u32_e32 v8, 0x1b000, v2
	v_mul_f32_e32 v7, v7, v9
	v_mov_b32_e32 v9, v3
	v_lshl_add_u64 v[8:9], v[8:9], 1, s[6:7]
	v_mul_f32_e32 v1, v1, v13
	v_cvt_pk_bf16_f32 v5, v5, v7
	global_store_short v[8:9], v5, off offset:768
	v_add_u32_e32 v8, 0x1b020, v2
	v_mov_b32_e32 v9, v3
	v_mul_f32_e32 v1, v4, v1
	v_mul_f32_e32 v4, v10, v13
	v_lshl_add_u64 v[8:9], v[8:9], 1, s[6:7]
	v_mul_f32_e32 v4, v6, v4
	global_store_short_d16_hi v[8:9], v5, off offset:768
	v_cvt_pk_bf16_f32 v1, v1, v4
	v_add_u32_e32 v4, 0x1b040, v2
	v_mov_b32_e32 v5, v3
	v_lshl_add_u64 v[4:5], v[4:5], 1, s[6:7]
	global_store_short v[4:5], v1, off offset:768
	v_add_u32_e32 v4, 0x1b060, v2
	v_mov_b32_e32 v5, v3
	v_lshl_add_u64 v[4:5], v[4:5], 1, s[6:7]
	global_store_short_d16_hi v[4:5], v1, off offset:768

.LBB0_2192:
	s_lshl_b32 s4, s48, 8
	v_mov_b32_e32 v2, v1
	v_mov_b32_e32 v145, v150
	s_add_i32 s4, s4, s40
	s_lshl_b32 s26, s45, 8
	v_add_u32_e32 v144, s4, v2
	v_lshlrev_b32_e32 v148, 3, v145
	v_ashrrev_i32_e32 v145, 31, v144
	v_lshl_add_u64 v[146:147], v[144:145], 2, s[2:3]
	v_mov_b32_e32 v2, v217
	v_mov_b32_e32 v158, v232
	v_mov_b32_e32 v159, v233
	v_mov_b32_e32 v160, v234
	v_mov_b32_e32 v161, v235
	v_mov_b32_e32 v162, v236
	v_mov_b32_e32 v163, v237
	v_mov_b32_e32 v164, v238
	s_ashr_i32 s27, s26, 31
	s_lshl_b64 s[26:27], s[26:27], 1
	v_ashrrev_i32_e32 v149, 31, v148
	s_cmp_eq_u32 s44, 3
	s_waitcnt vmcnt(8)
	v_fmamk_f32 v2, v2, 0x3a800000, v208
	v_rsq_f32_e32 v2, v2
	s_nop 0
	v_mul_f32_e32 v2, 0x3db8aa3b, v2
	v_pk_mul_f32 v[128:129], v[128:129], v[2:3] op_sel_hi:[1,0]
	v_pk_mul_f32 v[154:155], v[126:127], v[2:3] op_sel_hi:[1,0]
	v_pk_mul_f32 v[126:127], v[124:125], v[2:3] op_sel_hi:[1,0]
	v_cvt_pk_bf16_f32 v124, v128, v129
	v_lshlrev_b64 v[128:129], 13, v[144:145]
	v_lshl_add_u64 v[128:129], s[0:1], 0, v[128:129]
	v_pk_mul_f32 v[130:131], v[130:131], v[2:3] op_sel_hi:[1,0]
	v_lshl_add_u64 v[128:129], v[128:129], 0, s[26:27]
	v_cvt_pk_bf16_f32 v125, v130, v131
	v_lshl_add_u64 v[130:131], v[128:129], 0, s[46:47]
	v_lshlrev_b64 v[128:129], 1, v[148:149]
	v_lshl_add_u64 v[130:131], v[130:131], 0, v[128:129]
	v_cvt_pk_bf16_f32 v126, v126, v127
	v_cvt_pk_bf16_f32 v127, v154, v155
	global_store_dwordx4 v[130:131], v[124:127], off nt
	v_pk_mul_f32 v[122:123], v[122:123], v[2:3] op_sel_hi:[1,0]
	v_pk_mul_f32 v[120:121], v[120:121], v[2:3] op_sel_hi:[1,0]
	v_pk_mul_f32 v[124:125], v[118:119], v[2:3] op_sel_hi:[1,0]
	v_pk_mul_f32 v[118:119], v[116:117], v[2:3] op_sel_hi:[1,0]
	v_cvt_pk_bf16_f32 v116, v120, v121
	v_cvt_pk_bf16_f32 v117, v122, v123
	s_nop 0
	v_cvt_pk_bf16_f32 v118, v118, v119
	v_cvt_pk_bf16_f32 v119, v124, v125
	global_store_dwordx4 v[130:131], v[116:119], off offset:256 nt
	s_nop 1
	v_mov_b32_e32 v2, v158
	v_fmamk_f32 v2, v2, 0x3a800000, v208
	v_add_u32_e32 v116, 16, v144
	v_ashrrev_i32_e32 v117, 31, v116
	s_nop 0
	s_nop 1
	s_nop 1
	s_nop 0
	v_rsq_f32_e32 v2, v2
	s_nop 0
	v_mul_f32_e32 v2, 0x3db8aa3b, v2
	v_pk_mul_f32 v[112:113], v[112:113], v[2:3] op_sel_hi:[1,0]
	v_pk_mul_f32 v[118:119], v[110:111], v[2:3] op_sel_hi:[1,0]
	v_pk_mul_f32 v[110:111], v[108:109], v[2:3] op_sel_hi:[1,0]
	v_cvt_pk_bf16_f32 v108, v112, v113
	v_lshlrev_b64 v[112:113], 13, v[116:117]
	v_lshl_add_u64 v[112:113], s[0:1], 0, v[112:113]
	v_lshl_add_u64 v[112:113], v[112:113], 0, s[26:27]
	v_lshl_add_u64 v[112:113], v[112:113], 0, s[46:47]
	v_pk_mul_f32 v[114:115], v[114:115], v[2:3] op_sel_hi:[1,0]
	v_lshl_add_u64 v[112:113], v[112:113], 0, v[128:129]
	v_cvt_pk_bf16_f32 v109, v114, v115
	v_cvt_pk_bf16_f32 v110, v110, v111
	v_cvt_pk_bf16_f32 v111, v118, v119
	global_store_dwordx4 v[112:113], v[108:111], off nt
	v_pk_mul_f32 v[106:107], v[106:107], v[2:3] op_sel_hi:[1,0]
	v_pk_mul_f32 v[104:105], v[104:105], v[2:3] op_sel_hi:[1,0]
	v_pk_mul_f32 v[108:109], v[102:103], v[2:3] op_sel_hi:[1,0]
	v_pk_mul_f32 v[102:103], v[100:101], v[2:3] op_sel_hi:[1,0]
	v_cvt_pk_bf16_f32 v100, v104, v105
	v_cvt_pk_bf16_f32 v101, v106, v107
	s_nop 0
	v_cvt_pk_bf16_f32 v102, v102, v103
	v_cvt_pk_bf16_f32 v103, v108, v109
	global_store_dwordx4 v[112:113], v[100:103], off offset:256 nt
	s_nop 1
	v_mov_b32_e32 v2, v159
	v_fmamk_f32 v2, v2, 0x3a800000, v208
	v_add_u32_e32 v100, 32, v144
	v_ashrrev_i32_e32 v101, 31, v100
	s_nop 0
	s_nop 1
	s_nop 1
	s_nop 0
	v_rsq_f32_e32 v2, v2
	s_nop 0
	v_mul_f32_e32 v2, 0x3db8aa3b, v2
	v_pk_mul_f32 v[96:97], v[96:97], v[2:3] op_sel_hi:[1,0]
	v_pk_mul_f32 v[102:103], v[94:95], v[2:3] op_sel_hi:[1,0]
	v_pk_mul_f32 v[94:95], v[92:93], v[2:3] op_sel_hi:[1,0]
	v_cvt_pk_bf16_f32 v92, v96, v97
	v_lshlrev_b64 v[96:97], 13, v[100:101]
	v_lshl_add_u64 v[96:97], s[0:1], 0, v[96:97]
	v_lshl_add_u64 v[96:97], v[96:97], 0, s[26:27]
	v_lshl_add_u64 v[96:97], v[96:97], 0, s[46:47]
	v_pk_mul_f32 v[98:99], v[98:99], v[2:3] op_sel_hi:[1,0]
	v_lshl_add_u64 v[96:97], v[96:97], 0, v[128:129]
	v_cvt_pk_bf16_f32 v93, v98, v99
	v_cvt_pk_bf16_f32 v94, v94, v95
	v_cvt_pk_bf16_f32 v95, v102, v103
	global_store_dwordx4 v[96:97], v[92:95], off nt
	v_pk_mul_f32 v[90:91], v[90:91], v[2:3] op_sel_hi:[1,0]
	v_pk_mul_f32 v[88:89], v[88:89], v[2:3] op_sel_hi:[1,0]
	v_pk_mul_f32 v[92:93], v[86:87], v[2:3] op_sel_hi:[1,0]
	v_pk_mul_f32 v[86:87], v[84:85], v[2:3] op_sel_hi:[1,0]
	v_cvt_pk_bf16_f32 v84, v88, v89
	v_cvt_pk_bf16_f32 v85, v90, v91
	s_nop 0
	v_cvt_pk_bf16_f32 v86, v86, v87
	v_cvt_pk_bf16_f32 v87, v92, v93
	global_store_dwordx4 v[96:97], v[84:87], off offset:256 nt
	s_nop 1
	v_mov_b32_e32 v2, v160
	v_fmamk_f32 v2, v2, 0x3a800000, v208
	v_add_u32_e32 v84, 48, v144
	v_ashrrev_i32_e32 v85, 31, v84
	s_nop 0
	s_nop 1
	s_nop 1
	s_nop 0
	v_rsq_f32_e32 v2, v2
	s_nop 0
	v_mul_f32_e32 v2, 0x3db8aa3b, v2
	v_pk_mul_f32 v[80:81], v[80:81], v[2:3] op_sel_hi:[1,0]
	v_pk_mul_f32 v[86:87], v[78:79], v[2:3] op_sel_hi:[1,0]
	v_pk_mul_f32 v[78:79], v[76:77], v[2:3] op_sel_hi:[1,0]
	v_cvt_pk_bf16_f32 v76, v80, v81
	v_lshlrev_b64 v[80:81], 13, v[84:85]
	v_lshl_add_u64 v[80:81], s[0:1], 0, v[80:81]
	v_lshl_add_u64 v[80:81], v[80:81], 0, s[26:27]
	v_lshl_add_u64 v[80:81], v[80:81], 0, s[46:47]
	v_pk_mul_f32 v[82:83], v[82:83], v[2:3] op_sel_hi:[1,0]
	v_lshl_add_u64 v[80:81], v[80:81], 0, v[128:129]
	v_cvt_pk_bf16_f32 v77, v82, v83
	v_cvt_pk_bf16_f32 v78, v78, v79
	v_cvt_pk_bf16_f32 v79, v86, v87
	global_store_dwordx4 v[80:81], v[76:79], off nt
	v_pk_mul_f32 v[74:75], v[74:75], v[2:3] op_sel_hi:[1,0]
	v_pk_mul_f32 v[72:73], v[72:73], v[2:3] op_sel_hi:[1,0]
	v_pk_mul_f32 v[76:77], v[70:71], v[2:3] op_sel_hi:[1,0]
	v_pk_mul_f32 v[70:71], v[68:69], v[2:3] op_sel_hi:[1,0]
	v_cvt_pk_bf16_f32 v68, v72, v73
	v_cvt_pk_bf16_f32 v69, v74, v75
	s_nop 0
	v_cvt_pk_bf16_f32 v70, v70, v71
	v_cvt_pk_bf16_f32 v71, v76, v77
	global_store_dwordx4 v[80:81], v[68:71], off offset:256 nt
	s_nop 1
	v_mov_b32_e32 v2, v161
	v_fmamk_f32 v2, v2, 0x3a800000, v208
	v_add_u32_e32 v68, 0x80, v144
	v_ashrrev_i32_e32 v69, 31, v68
	s_nop 0
	s_nop 1
	s_nop 1
	s_nop 0
	v_rsq_f32_e32 v2, v2
	s_nop 0
	v_mul_f32_e32 v2, 0x3db8aa3b, v2
	v_pk_mul_f32 v[64:65], v[64:65], v[2:3] op_sel_hi:[1,0]
	v_pk_mul_f32 v[70:71], v[62:63], v[2:3] op_sel_hi:[1,0]
	v_pk_mul_f32 v[62:63], v[60:61], v[2:3] op_sel_hi:[1,0]
	v_cvt_pk_bf16_f32 v60, v64, v65
	v_lshlrev_b64 v[64:65], 13, v[68:69]
	v_lshl_add_u64 v[64:65], s[0:1], 0, v[64:65]
	v_lshl_add_u64 v[64:65], v[64:65], 0, s[26:27]
	v_lshl_add_u64 v[64:65], v[64:65], 0, s[46:47]
	v_pk_mul_f32 v[66:67], v[66:67], v[2:3] op_sel_hi:[1,0]
	v_lshl_add_u64 v[64:65], v[64:65], 0, v[128:129]
	v_cvt_pk_bf16_f32 v61, v66, v67
	v_cvt_pk_bf16_f32 v62, v62, v63
	v_cvt_pk_bf16_f32 v63, v70, v71
	global_store_dwordx4 v[64:65], v[60:63], off nt
	v_pk_mul_f32 v[58:59], v[58:59], v[2:3] op_sel_hi:[1,0]
	v_pk_mul_f32 v[56:57], v[56:57], v[2:3] op_sel_hi:[1,0]
	v_pk_mul_f32 v[60:61], v[54:55], v[2:3] op_sel_hi:[1,0]
	v_pk_mul_f32 v[54:55], v[52:53], v[2:3] op_sel_hi:[1,0]
	v_cvt_pk_bf16_f32 v52, v56, v57
	v_cvt_pk_bf16_f32 v53, v58, v59
	s_nop 0
	v_cvt_pk_bf16_f32 v54, v54, v55
	v_cvt_pk_bf16_f32 v55, v60, v61
	global_store_dwordx4 v[64:65], v[52:55], off offset:256 nt
	s_nop 1
	v_mov_b32_e32 v2, v162
	v_fmamk_f32 v2, v2, 0x3a800000, v208
	v_add_u32_e32 v52, 0x90, v144
	v_ashrrev_i32_e32 v53, 31, v52
	s_nop 0
	s_nop 1
	s_nop 1
	s_nop 0
	v_rsq_f32_e32 v2, v2
	s_nop 0
	v_mul_f32_e32 v2, 0x3db8aa3b, v2
	v_pk_mul_f32 v[48:49], v[48:49], v[2:3] op_sel_hi:[1,0]
	v_pk_mul_f32 v[54:55], v[46:47], v[2:3] op_sel_hi:[1,0]
	v_pk_mul_f32 v[46:47], v[44:45], v[2:3] op_sel_hi:[1,0]
	v_cvt_pk_bf16_f32 v44, v48, v49
	v_lshlrev_b64 v[48:49], 13, v[52:53]
	v_lshl_add_u64 v[48:49], s[0:1], 0, v[48:49]
	v_lshl_add_u64 v[48:49], v[48:49], 0, s[26:27]
	v_lshl_add_u64 v[48:49], v[48:49], 0, s[46:47]
	v_pk_mul_f32 v[50:51], v[50:51], v[2:3] op_sel_hi:[1,0]
	v_lshl_add_u64 v[48:49], v[48:49], 0, v[128:129]
	v_cvt_pk_bf16_f32 v45, v50, v51
	v_cvt_pk_bf16_f32 v46, v46, v47
	v_cvt_pk_bf16_f32 v47, v54, v55
	global_store_dwordx4 v[48:49], v[44:47], off nt
	v_pk_mul_f32 v[42:43], v[42:43], v[2:3] op_sel_hi:[1,0]
	v_pk_mul_f32 v[40:41], v[40:41], v[2:3] op_sel_hi:[1,0]
	v_pk_mul_f32 v[44:45], v[38:39], v[2:3] op_sel_hi:[1,0]
	v_pk_mul_f32 v[38:39], v[36:37], v[2:3] op_sel_hi:[1,0]
	v_cvt_pk_bf16_f32 v36, v40, v41
	v_cvt_pk_bf16_f32 v37, v42, v43
	s_nop 0
	v_cvt_pk_bf16_f32 v38, v38, v39
	v_cvt_pk_bf16_f32 v39, v44, v45
	global_store_dwordx4 v[48:49], v[36:39], off offset:256 nt
	s_nop 1
	v_mov_b32_e32 v2, v163
	v_fmamk_f32 v2, v2, 0x3a800000, v208
	v_add_u32_e32 v36, 0xa0, v144
	v_ashrrev_i32_e32 v37, 31, v36
	s_nop 0
	s_nop 1
	s_nop 1
	s_nop 0
	v_rsq_f32_e32 v2, v2
	s_nop 0
	v_mul_f32_e32 v2, 0x3db8aa3b, v2
	v_pk_mul_f32 v[32:33], v[32:33], v[2:3] op_sel_hi:[1,0]
	v_pk_mul_f32 v[38:39], v[30:31], v[2:3] op_sel_hi:[1,0]
	v_pk_mul_f32 v[30:31], v[28:29], v[2:3] op_sel_hi:[1,0]
	v_cvt_pk_bf16_f32 v28, v32, v33
	v_lshlrev_b64 v[32:33], 13, v[36:37]
	v_lshl_add_u64 v[32:33], s[0:1], 0, v[32:33]
	v_lshl_add_u64 v[32:33], v[32:33], 0, s[26:27]
	v_lshl_add_u64 v[32:33], v[32:33], 0, s[46:47]
	v_pk_mul_f32 v[34:35], v[34:35], v[2:3] op_sel_hi:[1,0]
	v_lshl_add_u64 v[32:33], v[32:33], 0, v[128:129]
	v_cvt_pk_bf16_f32 v29, v34, v35
	v_cvt_pk_bf16_f32 v30, v30, v31
	v_cvt_pk_bf16_f32 v31, v38, v39
	global_store_dwordx4 v[32:33], v[28:31], off nt
	v_pk_mul_f32 v[26:27], v[26:27], v[2:3] op_sel_hi:[1,0]
	v_pk_mul_f32 v[24:25], v[24:25], v[2:3] op_sel_hi:[1,0]
	v_pk_mul_f32 v[28:29], v[22:23], v[2:3] op_sel_hi:[1,0]
	v_pk_mul_f32 v[22:23], v[20:21], v[2:3] op_sel_hi:[1,0]
	v_cvt_pk_bf16_f32 v20, v24, v25
	v_cvt_pk_bf16_f32 v21, v26, v27
	s_nop 0
	v_cvt_pk_bf16_f32 v22, v22, v23
	v_cvt_pk_bf16_f32 v23, v28, v29
	global_store_dwordx4 v[32:33], v[20:23], off offset:256 nt
	s_nop 1
	v_mov_b32_e32 v2, v164
	v_fmamk_f32 v2, v2, 0x3a800000, v208
	v_add_u32_e32 v20, 0xb0, v144
	v_ashrrev_i32_e32 v21, 31, v20
	s_nop 0
	s_nop 1
	s_nop 1
	s_mov_b64 s[4:5], -1
	v_rsq_f32_e32 v2, v2
	s_nop 0
	v_mul_f32_e32 v2, 0x3db8aa3b, v2
	v_pk_mul_f32 v[16:17], v[16:17], v[2:3] op_sel_hi:[1,0]
	v_pk_mul_f32 v[22:23], v[14:15], v[2:3] op_sel_hi:[1,0]
	v_pk_mul_f32 v[14:15], v[12:13], v[2:3] op_sel_hi:[1,0]
	v_cvt_pk_bf16_f32 v12, v16, v17
	v_lshlrev_b64 v[16:17], 13, v[20:21]
	v_lshl_add_u64 v[16:17], s[0:1], 0, v[16:17]
	v_lshl_add_u64 v[16:17], v[16:17], 0, s[26:27]
	v_lshl_add_u64 v[16:17], v[16:17], 0, s[46:47]
	v_pk_mul_f32 v[18:19], v[18:19], v[2:3] op_sel_hi:[1,0]
	v_lshl_add_u64 v[16:17], v[16:17], 0, v[128:129]
	v_cvt_pk_bf16_f32 v13, v18, v19
	v_cvt_pk_bf16_f32 v14, v14, v15
	v_cvt_pk_bf16_f32 v15, v22, v23
	global_store_dwordx4 v[16:17], v[12:15], off nt
	v_pk_mul_f32 v[10:11], v[10:11], v[2:3] op_sel_hi:[1,0]
	v_pk_mul_f32 v[8:9], v[8:9], v[2:3] op_sel_hi:[1,0]
	v_pk_mul_f32 v[12:13], v[6:7], v[2:3] op_sel_hi:[1,0]
	v_pk_mul_f32 v[6:7], v[4:5], v[2:3] op_sel_hi:[1,0]
	v_cvt_pk_bf16_f32 v4, v8, v9
	v_cvt_pk_bf16_f32 v5, v10, v11
	s_nop 0
	v_cvt_pk_bf16_f32 v6, v6, v7
	v_cvt_pk_bf16_f32 v7, v12, v13
	global_store_dwordx4 v[16:17], v[4:7], off offset:256 nt
	s_cbranch_scc1 .LBB0_2187
	s_andn2_b64 vcc, exec, s[16:17]
	s_cbranch_vccnz .LBB0_2186
	s_barrier
	s_branch .LBB0_2186

.LBB0_2543:
	s_lshl_b32 s4, s48, 8
	v_mov_b32_e32 v2, v1
	v_mov_b32_e32 v145, v150
	s_add_i32 s4, s4, s40
	s_lshl_b32 s26, s45, 8
	v_add_u32_e32 v144, s4, v2
	v_lshlrev_b32_e32 v148, 3, v145
	v_ashrrev_i32_e32 v145, 31, v144
	v_lshl_add_u64 v[146:147], v[144:145], 2, s[2:3]
	v_mov_b32_e32 v2, v232
	v_mov_b32_e32 v158, v233
	v_mov_b32_e32 v159, v234
	v_mov_b32_e32 v160, v235
	v_mov_b32_e32 v161, v236
	v_mov_b32_e32 v162, v237
	v_mov_b32_e32 v163, v238
	v_mov_b32_e32 v164, v239
	s_ashr_i32 s27, s26, 31
	s_lshl_b64 s[26:27], s[26:27], 1
	v_ashrrev_i32_e32 v149, 31, v148
	s_cmp_eq_u32 s44, 15
	s_waitcnt vmcnt(8)
	v_fmamk_f32 v2, v2, 0x3a800000, v208
	v_rsq_f32_e32 v2, v2
	s_nop 0
	v_pk_mul_f32 v[126:127], v[126:127], v[2:3] op_sel_hi:[1,0]
	v_pk_mul_f32 v[124:125], v[124:125], v[2:3] op_sel_hi:[1,0]
	v_pk_mul_f32 v[130:131], v[130:131], v[2:3] op_sel_hi:[1,0]
	v_pk_mul_f32 v[128:129], v[128:129], v[2:3] op_sel_hi:[1,0]
	v_max_f32_e32 v124, 0, v124
	v_max_f32_e32 v125, 0, v125
	v_max_f32_e32 v126, 0, v126
	v_max_f32_e32 v128, 0, v128
	v_mul_f32_e32 v153, v124, v124
	v_max_f32_e32 v124, 0, v129
	v_mul_f32_e32 v129, v125, v125
	v_max_f32_e32 v125, 0, v130
	v_mul_f32_e32 v130, v126, v126
	v_max_f32_e32 v126, 0, v131
	v_mul_f32_e32 v128, v128, v128
	v_mul_f32_e32 v124, v124, v124
	v_mul_f32_e32 v125, v125, v125
	v_mul_f32_e32 v126, v126, v126
	v_cvt_pk_bf16_f32 v124, v128, v124
	v_cvt_pk_bf16_f32 v125, v125, v126
	v_cvt_pk_bf16_f32 v126, v153, v129
	v_lshlrev_b64 v[128:129], 13, v[144:145]
	v_max_f32_e32 v127, 0, v127
	v_lshl_add_u64 v[128:129], s[0:1], 0, v[128:129]
	v_pk_mul_f32 v[118:119], v[118:119], v[2:3] op_sel_hi:[1,0]
	v_pk_mul_f32 v[116:117], v[116:117], v[2:3] op_sel_hi:[1,0]
	v_mul_f32_e32 v127, v127, v127
	v_lshl_add_u64 v[128:129], v[128:129], 0, s[26:27]
	v_pk_mul_f32 v[122:123], v[122:123], v[2:3] op_sel_hi:[1,0]
	v_pk_mul_f32 v[120:121], v[120:121], v[2:3] op_sel_hi:[1,0]
	v_max_f32_e32 v116, 0, v116
	v_max_f32_e32 v117, 0, v117
	v_max_f32_e32 v118, 0, v118
	v_cvt_pk_bf16_f32 v127, v130, v127
	v_lshl_add_u64 v[130:131], v[128:129], 0, s[46:47]
	v_lshlrev_b64 v[128:129], 1, v[148:149]
	v_max_f32_e32 v2, 0, v120
	v_mul_f32_e32 v120, v116, v116
	v_max_f32_e32 v116, 0, v121
	v_mul_f32_e32 v121, v117, v117
	v_max_f32_e32 v117, 0, v122
	v_mul_f32_e32 v122, v118, v118
	v_max_f32_e32 v118, 0, v123
	v_max_f32_e32 v119, 0, v119
	v_lshl_add_u64 v[130:131], v[130:131], 0, v[128:129]
	v_mul_f32_e32 v116, v116, v116
	v_mul_f32_e32 v117, v117, v117
	v_mul_f32_e32 v118, v118, v118
	v_mul_f32_e32 v119, v119, v119
	global_store_dwordx4 v[130:131], v[124:127], off nt
	v_mul_f32_e32 v2, v2, v2
	v_cvt_pk_bf16_f32 v116, v2, v116
	v_cvt_pk_bf16_f32 v117, v117, v118
	v_cvt_pk_bf16_f32 v118, v120, v121
	v_cvt_pk_bf16_f32 v119, v122, v119
	global_store_dwordx4 v[130:131], v[116:119], off offset:256 nt
	s_nop 1
	v_mov_b32_e32 v2, v158
	v_fmamk_f32 v2, v2, 0x3a800000, v208
	v_add_u32_e32 v116, 16, v144
	v_ashrrev_i32_e32 v117, 31, v116
	s_nop 0
	s_nop 1
	s_nop 1
	s_nop 0
	v_rsq_f32_e32 v2, v2
	s_nop 0
	v_pk_mul_f32 v[110:111], v[110:111], v[2:3] op_sel_hi:[1,0]
	v_pk_mul_f32 v[108:109], v[108:109], v[2:3] op_sel_hi:[1,0]
	v_pk_mul_f32 v[114:115], v[114:115], v[2:3] op_sel_hi:[1,0]
	v_pk_mul_f32 v[112:113], v[112:113], v[2:3] op_sel_hi:[1,0]
	v_max_f32_e32 v108, 0, v108
	v_max_f32_e32 v109, 0, v109
	v_max_f32_e32 v110, 0, v110
	v_max_f32_e32 v112, 0, v112
	v_mul_f32_e32 v118, v108, v108
	v_max_f32_e32 v108, 0, v113
	v_mul_f32_e32 v113, v109, v109
	v_max_f32_e32 v109, 0, v114
	v_mul_f32_e32 v114, v110, v110
	v_max_f32_e32 v110, 0, v115
	v_mul_f32_e32 v112, v112, v112
	v_mul_f32_e32 v108, v108, v108
	v_mul_f32_e32 v109, v109, v109
	v_mul_f32_e32 v110, v110, v110
	v_cvt_pk_bf16_f32 v108, v112, v108
	v_cvt_pk_bf16_f32 v109, v109, v110
	v_cvt_pk_bf16_f32 v110, v118, v113
	v_lshlrev_b64 v[112:113], 13, v[116:117]
	v_lshl_add_u64 v[112:113], s[0:1], 0, v[112:113]
	v_pk_mul_f32 v[102:103], v[102:103], v[2:3] op_sel_hi:[1,0]
	v_pk_mul_f32 v[100:101], v[100:101], v[2:3] op_sel_hi:[1,0]
	v_lshl_add_u64 v[112:113], v[112:113], 0, s[26:27]
	v_pk_mul_f32 v[106:107], v[106:107], v[2:3] op_sel_hi:[1,0]
	v_pk_mul_f32 v[104:105], v[104:105], v[2:3] op_sel_hi:[1,0]
	v_max_f32_e32 v100, 0, v100
	v_max_f32_e32 v101, 0, v101
	v_max_f32_e32 v102, 0, v102
	v_max_f32_e32 v111, 0, v111
	v_lshl_add_u64 v[112:113], v[112:113], 0, s[46:47]
	v_max_f32_e32 v2, 0, v104
	v_mul_f32_e32 v104, v100, v100
	v_max_f32_e32 v100, 0, v105
	v_mul_f32_e32 v105, v101, v101
	v_max_f32_e32 v101, 0, v106
	v_mul_f32_e32 v106, v102, v102
	v_max_f32_e32 v102, 0, v107
	v_max_f32_e32 v103, 0, v103
	v_mul_f32_e32 v111, v111, v111
	v_lshl_add_u64 v[112:113], v[112:113], 0, v[128:129]
	v_mul_f32_e32 v100, v100, v100
	v_mul_f32_e32 v101, v101, v101
	v_mul_f32_e32 v102, v102, v102
	v_mul_f32_e32 v103, v103, v103
	v_cvt_pk_bf16_f32 v111, v114, v111
	global_store_dwordx4 v[112:113], v[108:111], off nt
	v_mul_f32_e32 v2, v2, v2
	v_cvt_pk_bf16_f32 v100, v2, v100
	v_cvt_pk_bf16_f32 v101, v101, v102
	v_cvt_pk_bf16_f32 v102, v104, v105
	v_cvt_pk_bf16_f32 v103, v106, v103
	global_store_dwordx4 v[112:113], v[100:103], off offset:256 nt
	s_nop 1
	v_mov_b32_e32 v2, v159
	v_fmamk_f32 v2, v2, 0x3a800000, v208
	v_add_u32_e32 v100, 32, v144
	v_ashrrev_i32_e32 v101, 31, v100
	s_nop 0
	s_nop 1
	s_nop 1
	s_nop 0
	v_rsq_f32_e32 v2, v2
	s_nop 0
	v_pk_mul_f32 v[94:95], v[94:95], v[2:3] op_sel_hi:[1,0]
	v_pk_mul_f32 v[92:93], v[92:93], v[2:3] op_sel_hi:[1,0]
	v_pk_mul_f32 v[98:99], v[98:99], v[2:3] op_sel_hi:[1,0]
	v_pk_mul_f32 v[96:97], v[96:97], v[2:3] op_sel_hi:[1,0]
	v_max_f32_e32 v92, 0, v92
	v_max_f32_e32 v93, 0, v93
	v_max_f32_e32 v94, 0, v94
	v_max_f32_e32 v96, 0, v96
	v_mul_f32_e32 v102, v92, v92
	v_max_f32_e32 v92, 0, v97
	v_mul_f32_e32 v97, v93, v93
	v_max_f32_e32 v93, 0, v98
	v_mul_f32_e32 v98, v94, v94
	v_max_f32_e32 v94, 0, v99
	v_mul_f32_e32 v96, v96, v96
	v_mul_f32_e32 v92, v92, v92
	v_mul_f32_e32 v93, v93, v93
	v_mul_f32_e32 v94, v94, v94
	v_cvt_pk_bf16_f32 v92, v96, v92
	v_cvt_pk_bf16_f32 v93, v93, v94
	v_cvt_pk_bf16_f32 v94, v102, v97
	v_lshlrev_b64 v[96:97], 13, v[100:101]
	v_lshl_add_u64 v[96:97], s[0:1], 0, v[96:97]
	v_pk_mul_f32 v[86:87], v[86:87], v[2:3] op_sel_hi:[1,0]
	v_pk_mul_f32 v[84:85], v[84:85], v[2:3] op_sel_hi:[1,0]
	v_lshl_add_u64 v[96:97], v[96:97], 0, s[26:27]
	v_pk_mul_f32 v[90:91], v[90:91], v[2:3] op_sel_hi:[1,0]
	v_pk_mul_f32 v[88:89], v[88:89], v[2:3] op_sel_hi:[1,0]
	v_max_f32_e32 v84, 0, v84
	v_max_f32_e32 v85, 0, v85
	v_max_f32_e32 v86, 0, v86
	v_max_f32_e32 v95, 0, v95
	v_lshl_add_u64 v[96:97], v[96:97], 0, s[46:47]
	v_max_f32_e32 v2, 0, v88
	v_mul_f32_e32 v88, v84, v84
	v_max_f32_e32 v84, 0, v89
	v_mul_f32_e32 v89, v85, v85
	v_max_f32_e32 v85, 0, v90
	v_mul_f32_e32 v90, v86, v86
	v_max_f32_e32 v86, 0, v91
	v_max_f32_e32 v87, 0, v87
	v_mul_f32_e32 v95, v95, v95
	v_lshl_add_u64 v[96:97], v[96:97], 0, v[128:129]
	v_mul_f32_e32 v84, v84, v84
	v_mul_f32_e32 v85, v85, v85
	v_mul_f32_e32 v86, v86, v86
	v_mul_f32_e32 v87, v87, v87
	v_cvt_pk_bf16_f32 v95, v98, v95
	global_store_dwordx4 v[96:97], v[92:95], off nt
	v_mul_f32_e32 v2, v2, v2
	v_cvt_pk_bf16_f32 v84, v2, v84
	v_cvt_pk_bf16_f32 v85, v85, v86
	v_cvt_pk_bf16_f32 v86, v88, v89
	v_cvt_pk_bf16_f32 v87, v90, v87
	global_store_dwordx4 v[96:97], v[84:87], off offset:256 nt
	s_nop 1
	v_mov_b32_e32 v2, v160
	v_fmamk_f32 v2, v2, 0x3a800000, v208
	v_add_u32_e32 v84, 48, v144
	v_ashrrev_i32_e32 v85, 31, v84
	s_nop 0
	s_nop 1
	s_nop 1
	s_nop 0
	v_rsq_f32_e32 v2, v2
	s_nop 0
	v_pk_mul_f32 v[78:79], v[78:79], v[2:3] op_sel_hi:[1,0]
	v_pk_mul_f32 v[76:77], v[76:77], v[2:3] op_sel_hi:[1,0]
	v_pk_mul_f32 v[82:83], v[82:83], v[2:3] op_sel_hi:[1,0]
	v_pk_mul_f32 v[80:81], v[80:81], v[2:3] op_sel_hi:[1,0]
	v_max_f32_e32 v76, 0, v76
	v_max_f32_e32 v77, 0, v77
	v_max_f32_e32 v78, 0, v78
	v_max_f32_e32 v80, 0, v80
	v_mul_f32_e32 v86, v76, v76
	v_max_f32_e32 v76, 0, v81
	v_mul_f32_e32 v81, v77, v77
	v_max_f32_e32 v77, 0, v82
	v_mul_f32_e32 v82, v78, v78
	v_max_f32_e32 v78, 0, v83
	v_mul_f32_e32 v80, v80, v80
	v_mul_f32_e32 v76, v76, v76
	v_mul_f32_e32 v77, v77, v77
	v_mul_f32_e32 v78, v78, v78
	v_cvt_pk_bf16_f32 v76, v80, v76
	v_cvt_pk_bf16_f32 v77, v77, v78
	v_cvt_pk_bf16_f32 v78, v86, v81
	v_lshlrev_b64 v[80:81], 13, v[84:85]
	v_lshl_add_u64 v[80:81], s[0:1], 0, v[80:81]
	v_pk_mul_f32 v[70:71], v[70:71], v[2:3] op_sel_hi:[1,0]
	v_pk_mul_f32 v[68:69], v[68:69], v[2:3] op_sel_hi:[1,0]
	v_lshl_add_u64 v[80:81], v[80:81], 0, s[26:27]
	v_pk_mul_f32 v[74:75], v[74:75], v[2:3] op_sel_hi:[1,0]
	v_pk_mul_f32 v[72:73], v[72:73], v[2:3] op_sel_hi:[1,0]
	v_max_f32_e32 v68, 0, v68
	v_max_f32_e32 v69, 0, v69
	v_max_f32_e32 v70, 0, v70
	v_max_f32_e32 v79, 0, v79
	v_lshl_add_u64 v[80:81], v[80:81], 0, s[46:47]
	v_max_f32_e32 v2, 0, v72
	v_mul_f32_e32 v72, v68, v68
	v_max_f32_e32 v68, 0, v73
	v_mul_f32_e32 v73, v69, v69
	v_max_f32_e32 v69, 0, v74
	v_mul_f32_e32 v74, v70, v70
	v_max_f32_e32 v70, 0, v75
	v_max_f32_e32 v71, 0, v71
	v_mul_f32_e32 v79, v79, v79
	v_lshl_add_u64 v[80:81], v[80:81], 0, v[128:129]
	v_mul_f32_e32 v68, v68, v68
	v_mul_f32_e32 v69, v69, v69
	v_mul_f32_e32 v70, v70, v70
	v_mul_f32_e32 v71, v71, v71
	v_cvt_pk_bf16_f32 v79, v82, v79
	global_store_dwordx4 v[80:81], v[76:79], off nt
	v_mul_f32_e32 v2, v2, v2
	v_cvt_pk_bf16_f32 v68, v2, v68
	v_cvt_pk_bf16_f32 v69, v69, v70
	v_cvt_pk_bf16_f32 v70, v72, v73
	v_cvt_pk_bf16_f32 v71, v74, v71
	global_store_dwordx4 v[80:81], v[68:71], off offset:256 nt
	s_nop 1
	v_mov_b32_e32 v2, v161
	v_fmamk_f32 v2, v2, 0x3a800000, v208
	v_add_u32_e32 v68, 0x80, v144
	v_ashrrev_i32_e32 v69, 31, v68
	s_nop 0
	s_nop 1
	s_nop 1
	s_nop 0
	v_rsq_f32_e32 v2, v2
	s_nop 0
	v_pk_mul_f32 v[62:63], v[62:63], v[2:3] op_sel_hi:[1,0]
	v_pk_mul_f32 v[60:61], v[60:61], v[2:3] op_sel_hi:[1,0]
	v_pk_mul_f32 v[66:67], v[66:67], v[2:3] op_sel_hi:[1,0]
	v_pk_mul_f32 v[64:65], v[64:65], v[2:3] op_sel_hi:[1,0]
	v_max_f32_e32 v60, 0, v60
	v_max_f32_e32 v61, 0, v61
	v_max_f32_e32 v62, 0, v62
	v_max_f32_e32 v64, 0, v64
	v_mul_f32_e32 v70, v60, v60
	v_max_f32_e32 v60, 0, v65
	v_mul_f32_e32 v65, v61, v61
	v_max_f32_e32 v61, 0, v66
	v_mul_f32_e32 v66, v62, v62
	v_max_f32_e32 v62, 0, v67
	v_mul_f32_e32 v64, v64, v64
	v_mul_f32_e32 v60, v60, v60
	v_mul_f32_e32 v61, v61, v61
	v_mul_f32_e32 v62, v62, v62
	v_cvt_pk_bf16_f32 v60, v64, v60
	v_cvt_pk_bf16_f32 v61, v61, v62
	v_cvt_pk_bf16_f32 v62, v70, v65
	v_lshlrev_b64 v[64:65], 13, v[68:69]
	v_lshl_add_u64 v[64:65], s[0:1], 0, v[64:65]
	v_pk_mul_f32 v[54:55], v[54:55], v[2:3] op_sel_hi:[1,0]
	v_pk_mul_f32 v[52:53], v[52:53], v[2:3] op_sel_hi:[1,0]
	v_lshl_add_u64 v[64:65], v[64:65], 0, s[26:27]
	v_pk_mul_f32 v[58:59], v[58:59], v[2:3] op_sel_hi:[1,0]
	v_pk_mul_f32 v[56:57], v[56:57], v[2:3] op_sel_hi:[1,0]
	v_max_f32_e32 v52, 0, v52
	v_max_f32_e32 v53, 0, v53
	v_max_f32_e32 v54, 0, v54
	v_max_f32_e32 v63, 0, v63
	v_lshl_add_u64 v[64:65], v[64:65], 0, s[46:47]
	v_max_f32_e32 v2, 0, v56
	v_mul_f32_e32 v56, v52, v52
	v_max_f32_e32 v52, 0, v57
	v_mul_f32_e32 v57, v53, v53
	v_max_f32_e32 v53, 0, v58
	v_mul_f32_e32 v58, v54, v54
	v_max_f32_e32 v54, 0, v59
	v_max_f32_e32 v55, 0, v55
	v_mul_f32_e32 v63, v63, v63
	v_lshl_add_u64 v[64:65], v[64:65], 0, v[128:129]
	v_mul_f32_e32 v52, v52, v52
	v_mul_f32_e32 v53, v53, v53
	v_mul_f32_e32 v54, v54, v54
	v_mul_f32_e32 v55, v55, v55
	v_cvt_pk_bf16_f32 v63, v66, v63
	global_store_dwordx4 v[64:65], v[60:63], off nt
	v_mul_f32_e32 v2, v2, v2
	v_cvt_pk_bf16_f32 v52, v2, v52
	v_cvt_pk_bf16_f32 v53, v53, v54
	v_cvt_pk_bf16_f32 v54, v56, v57
	v_cvt_pk_bf16_f32 v55, v58, v55
	global_store_dwordx4 v[64:65], v[52:55], off offset:256 nt
	s_nop 1
	v_mov_b32_e32 v2, v162
	v_fmamk_f32 v2, v2, 0x3a800000, v208
	v_add_u32_e32 v52, 0x90, v144
	v_ashrrev_i32_e32 v53, 31, v52
	s_nop 0
	s_nop 1
	s_nop 1
	s_nop 0
	v_rsq_f32_e32 v2, v2
	s_nop 0
	v_pk_mul_f32 v[46:47], v[46:47], v[2:3] op_sel_hi:[1,0]
	v_pk_mul_f32 v[44:45], v[44:45], v[2:3] op_sel_hi:[1,0]
	v_pk_mul_f32 v[50:51], v[50:51], v[2:3] op_sel_hi:[1,0]
	v_pk_mul_f32 v[48:49], v[48:49], v[2:3] op_sel_hi:[1,0]
	v_max_f32_e32 v44, 0, v44
	v_max_f32_e32 v45, 0, v45
	v_max_f32_e32 v46, 0, v46
	v_max_f32_e32 v48, 0, v48
	v_mul_f32_e32 v54, v44, v44
	v_max_f32_e32 v44, 0, v49
	v_mul_f32_e32 v49, v45, v45
	v_max_f32_e32 v45, 0, v50
	v_mul_f32_e32 v50, v46, v46
	v_max_f32_e32 v46, 0, v51
	v_mul_f32_e32 v48, v48, v48
	v_mul_f32_e32 v44, v44, v44
	v_mul_f32_e32 v45, v45, v45
	v_mul_f32_e32 v46, v46, v46
	v_cvt_pk_bf16_f32 v44, v48, v44
	v_cvt_pk_bf16_f32 v45, v45, v46
	v_cvt_pk_bf16_f32 v46, v54, v49
	v_lshlrev_b64 v[48:49], 13, v[52:53]
	v_lshl_add_u64 v[48:49], s[0:1], 0, v[48:49]
	v_pk_mul_f32 v[38:39], v[38:39], v[2:3] op_sel_hi:[1,0]
	v_pk_mul_f32 v[36:37], v[36:37], v[2:3] op_sel_hi:[1,0]
	v_lshl_add_u64 v[48:49], v[48:49], 0, s[26:27]
	v_pk_mul_f32 v[42:43], v[42:43], v[2:3] op_sel_hi:[1,0]
	v_pk_mul_f32 v[40:41], v[40:41], v[2:3] op_sel_hi:[1,0]
	v_max_f32_e32 v36, 0, v36
	v_max_f32_e32 v37, 0, v37
	v_max_f32_e32 v38, 0, v38
	v_max_f32_e32 v47, 0, v47
	v_lshl_add_u64 v[48:49], v[48:49], 0, s[46:47]
	v_max_f32_e32 v2, 0, v40
	v_mul_f32_e32 v40, v36, v36
	v_max_f32_e32 v36, 0, v41
	v_mul_f32_e32 v41, v37, v37
	v_max_f32_e32 v37, 0, v42
	v_mul_f32_e32 v42, v38, v38
	v_max_f32_e32 v38, 0, v43
	v_max_f32_e32 v39, 0, v39
	v_mul_f32_e32 v47, v47, v47
	v_lshl_add_u64 v[48:49], v[48:49], 0, v[128:129]
	v_mul_f32_e32 v36, v36, v36
	v_mul_f32_e32 v37, v37, v37
	v_mul_f32_e32 v38, v38, v38
	v_mul_f32_e32 v39, v39, v39
	v_cvt_pk_bf16_f32 v47, v50, v47
	global_store_dwordx4 v[48:49], v[44:47], off nt
	v_mul_f32_e32 v2, v2, v2
	v_cvt_pk_bf16_f32 v36, v2, v36
	v_cvt_pk_bf16_f32 v37, v37, v38
	v_cvt_pk_bf16_f32 v38, v40, v41
	v_cvt_pk_bf16_f32 v39, v42, v39
	global_store_dwordx4 v[48:49], v[36:39], off offset:256 nt
	s_nop 1
	v_mov_b32_e32 v2, v163
	v_fmamk_f32 v2, v2, 0x3a800000, v208
	v_add_u32_e32 v36, 0xa0, v144
	v_ashrrev_i32_e32 v37, 31, v36
	s_nop 0
	s_nop 1
	s_nop 1
	s_nop 0
	v_rsq_f32_e32 v2, v2
	s_nop 0
	v_pk_mul_f32 v[30:31], v[30:31], v[2:3] op_sel_hi:[1,0]
	v_pk_mul_f32 v[28:29], v[28:29], v[2:3] op_sel_hi:[1,0]
	v_pk_mul_f32 v[34:35], v[34:35], v[2:3] op_sel_hi:[1,0]
	v_pk_mul_f32 v[32:33], v[32:33], v[2:3] op_sel_hi:[1,0]
	v_max_f32_e32 v28, 0, v28
	v_max_f32_e32 v29, 0, v29
	v_max_f32_e32 v30, 0, v30
	v_max_f32_e32 v32, 0, v32
	v_mul_f32_e32 v38, v28, v28
	v_max_f32_e32 v28, 0, v33
	v_mul_f32_e32 v33, v29, v29
	v_max_f32_e32 v29, 0, v34
	v_mul_f32_e32 v34, v30, v30
	v_max_f32_e32 v30, 0, v35
	v_mul_f32_e32 v32, v32, v32
	v_mul_f32_e32 v28, v28, v28
	v_mul_f32_e32 v29, v29, v29
	v_mul_f32_e32 v30, v30, v30
	v_cvt_pk_bf16_f32 v28, v32, v28
	v_cvt_pk_bf16_f32 v29, v29, v30
	v_cvt_pk_bf16_f32 v30, v38, v33
	v_lshlrev_b64 v[32:33], 13, v[36:37]
	v_lshl_add_u64 v[32:33], s[0:1], 0, v[32:33]
	v_pk_mul_f32 v[22:23], v[22:23], v[2:3] op_sel_hi:[1,0]
	v_pk_mul_f32 v[20:21], v[20:21], v[2:3] op_sel_hi:[1,0]
	v_lshl_add_u64 v[32:33], v[32:33], 0, s[26:27]
	v_pk_mul_f32 v[26:27], v[26:27], v[2:3] op_sel_hi:[1,0]
	v_pk_mul_f32 v[24:25], v[24:25], v[2:3] op_sel_hi:[1,0]
	v_max_f32_e32 v20, 0, v20
	v_max_f32_e32 v21, 0, v21
	v_max_f32_e32 v22, 0, v22
	v_max_f32_e32 v31, 0, v31
	v_lshl_add_u64 v[32:33], v[32:33], 0, s[46:47]
	v_max_f32_e32 v2, 0, v24
	v_mul_f32_e32 v24, v20, v20
	v_max_f32_e32 v20, 0, v25
	v_mul_f32_e32 v25, v21, v21
	v_max_f32_e32 v21, 0, v26
	v_mul_f32_e32 v26, v22, v22
	v_max_f32_e32 v22, 0, v27
	v_max_f32_e32 v23, 0, v23
	v_mul_f32_e32 v31, v31, v31
	v_lshl_add_u64 v[32:33], v[32:33], 0, v[128:129]
	v_mul_f32_e32 v20, v20, v20
	v_mul_f32_e32 v21, v21, v21
	v_mul_f32_e32 v22, v22, v22
	v_mul_f32_e32 v23, v23, v23
	v_cvt_pk_bf16_f32 v31, v34, v31
	global_store_dwordx4 v[32:33], v[28:31], off nt
	v_mul_f32_e32 v2, v2, v2
	v_cvt_pk_bf16_f32 v20, v2, v20
	v_cvt_pk_bf16_f32 v21, v21, v22
	v_cvt_pk_bf16_f32 v22, v24, v25
	v_cvt_pk_bf16_f32 v23, v26, v23
	global_store_dwordx4 v[32:33], v[20:23], off offset:256 nt
	s_nop 1
	v_mov_b32_e32 v2, v164
	v_fmamk_f32 v2, v2, 0x3a800000, v208
	v_add_u32_e32 v20, 0xb0, v144
	v_ashrrev_i32_e32 v21, 31, v20
	s_nop 0
	s_nop 1
	s_nop 1
	s_mov_b64 s[4:5], -1
	v_rsq_f32_e32 v2, v2
	s_nop 0
	v_pk_mul_f32 v[14:15], v[14:15], v[2:3] op_sel_hi:[1,0]
	v_pk_mul_f32 v[12:13], v[12:13], v[2:3] op_sel_hi:[1,0]
	v_pk_mul_f32 v[18:19], v[18:19], v[2:3] op_sel_hi:[1,0]
	v_pk_mul_f32 v[16:17], v[16:17], v[2:3] op_sel_hi:[1,0]
	v_max_f32_e32 v12, 0, v12
	v_max_f32_e32 v13, 0, v13
	v_max_f32_e32 v14, 0, v14
	v_max_f32_e32 v16, 0, v16
	v_mul_f32_e32 v22, v12, v12
	v_max_f32_e32 v12, 0, v17
	v_mul_f32_e32 v17, v13, v13
	v_max_f32_e32 v13, 0, v18
	v_mul_f32_e32 v18, v14, v14
	v_max_f32_e32 v14, 0, v19
	v_mul_f32_e32 v16, v16, v16
	v_mul_f32_e32 v12, v12, v12
	v_mul_f32_e32 v13, v13, v13
	v_mul_f32_e32 v14, v14, v14
	v_cvt_pk_bf16_f32 v12, v16, v12
	v_cvt_pk_bf16_f32 v13, v13, v14
	v_cvt_pk_bf16_f32 v14, v22, v17
	v_lshlrev_b64 v[16:17], 13, v[20:21]
	v_lshl_add_u64 v[16:17], s[0:1], 0, v[16:17]
	v_pk_mul_f32 v[6:7], v[6:7], v[2:3] op_sel_hi:[1,0]
	v_pk_mul_f32 v[4:5], v[4:5], v[2:3] op_sel_hi:[1,0]
	v_lshl_add_u64 v[16:17], v[16:17], 0, s[26:27]
	v_pk_mul_f32 v[10:11], v[10:11], v[2:3] op_sel_hi:[1,0]
	v_pk_mul_f32 v[8:9], v[8:9], v[2:3] op_sel_hi:[1,0]
	v_max_f32_e32 v4, 0, v4
	v_max_f32_e32 v5, 0, v5
	v_max_f32_e32 v6, 0, v6
	v_max_f32_e32 v15, 0, v15
	v_lshl_add_u64 v[16:17], v[16:17], 0, s[46:47]
	v_max_f32_e32 v2, 0, v8
	v_mul_f32_e32 v8, v4, v4
	v_max_f32_e32 v4, 0, v9
	v_mul_f32_e32 v9, v5, v5
	v_max_f32_e32 v5, 0, v10
	v_mul_f32_e32 v10, v6, v6
	v_max_f32_e32 v6, 0, v11
	v_max_f32_e32 v7, 0, v7
	v_mul_f32_e32 v15, v15, v15
	v_lshl_add_u64 v[16:17], v[16:17], 0, v[128:129]
	v_mul_f32_e32 v4, v4, v4
	v_mul_f32_e32 v5, v5, v5
	v_mul_f32_e32 v6, v6, v6
	v_mul_f32_e32 v7, v7, v7
	v_cvt_pk_bf16_f32 v15, v18, v15
	global_store_dwordx4 v[16:17], v[12:15], off nt
	v_mul_f32_e32 v2, v2, v2
	v_cvt_pk_bf16_f32 v4, v2, v4
	v_cvt_pk_bf16_f32 v5, v5, v6
	v_cvt_pk_bf16_f32 v6, v8, v9
	v_cvt_pk_bf16_f32 v7, v10, v7
	global_store_dwordx4 v[16:17], v[4:7], off offset:256 nt
	s_cbranch_scc1 .LBB0_2536
	s_andn2_b64 vcc, exec, s[14:15]
	s_cbranch_vccnz .LBB0_2535
	s_barrier
	s_branch .LBB0_2535
